# v19
# speedup vs baseline: 1.0433x; 1.0206x over previous
.LBB0_159:
	global_load_dwordx4 v[16:19], v[8:9], off offset:-2048
	global_load_dwordx4 v[20:23], v[8:9], off offset:-1024
	global_load_dwordx4 v[24:27], v[8:9], off
	global_load_dwordx4 v[28:31], v[8:9], off offset:1024
	global_load_dwordx4 v[32:35], v[4:5], off
	global_load_dwordx4 v[36:39], v[4:5], off offset:1024
	global_load_dwordx4 v[40:43], v[4:5], off offset:2048
	global_load_dwordx4 v[44:47], v[4:5], off offset:3072
	v_add_u32_e32 v2, s8, v2
	v_lshl_add_u64 v[8:9], v[8:9], 0, s[4:5]
	s_waitcnt vmcnt(4)
	v_pk_mul_f32 v[48:49], v[16:17], v[16:17]
	v_pk_fma_f32 v[48:49], v[18:19], v[18:19], v[48:49]
	v_pk_fma_f32 v[48:49], v[20:21], v[20:21], v[48:49]
	v_pk_fma_f32 v[48:49], v[22:23], v[22:23], v[48:49]
	v_pk_fma_f32 v[48:49], v[24:25], v[24:25], v[48:49]
	v_pk_fma_f32 v[48:49], v[26:27], v[26:27], v[48:49]
	v_pk_fma_f32 v[48:49], v[28:29], v[28:29], v[48:49]
	v_pk_fma_f32 v[48:49], v[30:31], v[30:31], v[48:49]
	v_add_f32_e32 v50, v48, v49
	s_nop 1
	v_add_f32_dpp v50, v50, v50 quad_perm:[1,0,3,2] row_mask:0xf bank_mask:0xf
	s_nop 1
	v_add_f32_dpp v50, v50, v50 quad_perm:[2,3,0,1] row_mask:0xf bank_mask:0xf
	s_nop 1
	v_add_f32_dpp v50, v50, v50 row_half_mirror row_mask:0xf bank_mask:0xf
	s_nop 1
	v_add_f32_dpp v50, v50, v50 row_mirror row_mask:0xf bank_mask:0xf
	v_mov_b32_e32 v51, v50
	s_nop 1
	v_permlane16_swap_b32_e32 v50, v51
	s_nop 0
	v_add_f32_e32 v50, v50, v51
	v_mov_b32_e32 v51, v50
	s_nop 1
	v_permlane32_swap_b32_e32 v50, v51
	s_nop 0
	v_add_f32_e32 v50, v50, v51
	v_fmamk_f32 v50, v50, 0x3a800000, v3
	v_rsq_f32_e32 v50, v50
	v_cmp_lt_i32_e32 vcc, s20, v2
	s_or_b64 s[18:19], vcc, s[18:19]
	v_pk_mul_f32 v[16:17], v[16:17], v[50:51] op_sel_hi:[1,0]
	v_pk_mul_f32 v[18:19], v[18:19], v[50:51] op_sel_hi:[1,0]
	v_pk_mul_f32 v[20:21], v[20:21], v[50:51] op_sel_hi:[1,0]
	v_pk_mul_f32 v[22:23], v[22:23], v[50:51] op_sel_hi:[1,0]
	v_pk_mul_f32 v[24:25], v[24:25], v[50:51] op_sel_hi:[1,0]
	v_pk_mul_f32 v[26:27], v[26:27], v[50:51] op_sel_hi:[1,0]
	v_pk_mul_f32 v[28:29], v[28:29], v[50:51] op_sel_hi:[1,0]
	v_pk_mul_f32 v[30:31], v[30:31], v[50:51] op_sel_hi:[1,0]
	s_waitcnt vmcnt(0)
	v_pk_mul_f32 v[16:17], v[32:33], v[16:17]
	v_pk_mul_f32 v[18:19], v[34:35], v[18:19]
	v_pk_mul_f32 v[20:21], v[36:37], v[20:21]
	v_pk_mul_f32 v[22:23], v[38:39], v[22:23]
	v_pk_mul_f32 v[24:25], v[40:41], v[24:25]
	v_pk_mul_f32 v[26:27], v[42:43], v[26:27]
	v_pk_mul_f32 v[28:29], v[44:45], v[28:29]
	v_pk_mul_f32 v[30:31], v[46:47], v[30:31]
	v_cvt_pk_bf16_f32 v16, v16, v17
	v_cvt_pk_bf16_f32 v17, v18, v19
	global_store_dwordx2 v[6:7], v[16:17], off offset:-1536
	v_cvt_pk_bf16_f32 v20, v20, v21
	v_cvt_pk_bf16_f32 v21, v22, v23
	global_store_dwordx2 v[6:7], v[20:21], off offset:-1024
	v_cvt_pk_bf16_f32 v24, v24, v25
	v_cvt_pk_bf16_f32 v25, v26, v27
	global_store_dwordx2 v[6:7], v[24:25], off offset:-512
	v_cvt_pk_bf16_f32 v28, v28, v29
	v_cvt_pk_bf16_f32 v29, v30, v31
	global_store_dwordx2 v[6:7], v[28:29], off
	v_lshl_add_u64 v[6:7], v[6:7], 0, s[6:7]
	s_andn2_b64 exec, exec, s[18:19]
	s_cbranch_execnz .LBB0_159

.LBB0_162:
	global_load_dwordx4 v[16:19], v[8:9], off offset:-2048
	global_load_dwordx4 v[20:23], v[8:9], off offset:-1024
	global_load_dwordx4 v[24:27], v[8:9], off
	global_load_dwordx4 v[28:31], v[8:9], off offset:1024
	global_load_dwordx4 v[32:35], v[4:5], off
	global_load_dwordx4 v[36:39], v[4:5], off offset:1024
	global_load_dwordx4 v[40:43], v[4:5], off offset:2048
	global_load_dwordx4 v[44:47], v[4:5], off offset:3072
	v_add_u32_e32 v2, s8, v2
	v_lshl_add_u64 v[8:9], v[8:9], 0, s[12:13]
	s_waitcnt vmcnt(4)
	v_pk_mul_f32 v[48:49], v[16:17], v[16:17]
	v_pk_fma_f32 v[48:49], v[18:19], v[18:19], v[48:49]
	v_pk_fma_f32 v[48:49], v[20:21], v[20:21], v[48:49]
	v_pk_fma_f32 v[48:49], v[22:23], v[22:23], v[48:49]
	v_pk_fma_f32 v[48:49], v[24:25], v[24:25], v[48:49]
	v_pk_fma_f32 v[48:49], v[26:27], v[26:27], v[48:49]
	v_pk_fma_f32 v[48:49], v[28:29], v[28:29], v[48:49]
	v_pk_fma_f32 v[48:49], v[30:31], v[30:31], v[48:49]
	v_add_f32_e32 v50, v48, v49
	s_nop 1
	v_add_f32_dpp v50, v50, v50 quad_perm:[1,0,3,2] row_mask:0xf bank_mask:0xf
	s_nop 1
	v_add_f32_dpp v50, v50, v50 quad_perm:[2,3,0,1] row_mask:0xf bank_mask:0xf
	s_nop 1
	v_add_f32_dpp v50, v50, v50 row_half_mirror row_mask:0xf bank_mask:0xf
	s_nop 1
	v_add_f32_dpp v50, v50, v50 row_mirror row_mask:0xf bank_mask:0xf
	v_mov_b32_e32 v51, v50
	s_nop 1
	v_permlane16_swap_b32_e32 v50, v51
	s_nop 0
	v_add_f32_e32 v50, v50, v51
	v_mov_b32_e32 v51, v50
	s_nop 1
	v_permlane32_swap_b32_e32 v50, v51
	s_nop 0
	v_add_f32_e32 v50, v50, v51
	v_fmamk_f32 v50, v50, 0x3a800000, v3
	v_rsq_f32_e32 v50, v50
	v_cmp_lt_i32_e32 vcc, s16, v2
	s_or_b64 s[14:15], vcc, s[14:15]
	v_pk_mul_f32 v[16:17], v[16:17], v[50:51] op_sel_hi:[1,0]
	v_pk_mul_f32 v[18:19], v[18:19], v[50:51] op_sel_hi:[1,0]
	v_pk_mul_f32 v[20:21], v[20:21], v[50:51] op_sel_hi:[1,0]
	v_pk_mul_f32 v[22:23], v[22:23], v[50:51] op_sel_hi:[1,0]
	v_pk_mul_f32 v[24:25], v[24:25], v[50:51] op_sel_hi:[1,0]
	v_pk_mul_f32 v[26:27], v[26:27], v[50:51] op_sel_hi:[1,0]
	v_pk_mul_f32 v[28:29], v[28:29], v[50:51] op_sel_hi:[1,0]
	v_pk_mul_f32 v[30:31], v[30:31], v[50:51] op_sel_hi:[1,0]
	s_waitcnt vmcnt(0)
	v_pk_mul_f32 v[16:17], v[32:33], v[16:17]
	v_pk_mul_f32 v[18:19], v[34:35], v[18:19]
	v_pk_mul_f32 v[20:21], v[36:37], v[20:21]
	v_pk_mul_f32 v[22:23], v[38:39], v[22:23]
	v_pk_mul_f32 v[24:25], v[40:41], v[24:25]
	v_pk_mul_f32 v[26:27], v[42:43], v[26:27]
	v_pk_mul_f32 v[28:29], v[44:45], v[28:29]
	v_pk_mul_f32 v[30:31], v[46:47], v[30:31]
	v_cvt_pk_bf16_f32 v16, v16, v17
	v_cvt_pk_bf16_f32 v17, v18, v19
	global_store_dwordx2 v[6:7], v[16:17], off offset:-1536
	v_cvt_pk_bf16_f32 v20, v20, v21
	v_cvt_pk_bf16_f32 v21, v22, v23
	global_store_dwordx2 v[6:7], v[20:21], off offset:-1024
	v_cvt_pk_bf16_f32 v24, v24, v25
	v_cvt_pk_bf16_f32 v25, v26, v27
	global_store_dwordx2 v[6:7], v[24:25], off offset:-512
	v_cvt_pk_bf16_f32 v28, v28, v29
	v_cvt_pk_bf16_f32 v29, v30, v31
	global_store_dwordx2 v[6:7], v[28:29], off
	v_lshl_add_u64 v[6:7], v[6:7], 0, s[6:7]
	s_andn2_b64 exec, exec, s[14:15]
	s_cbranch_execnz .LBB0_162

.LBB0_265:
	s_mov_b32 s4, s2
	v_mbcnt_lo_u32_b32 v1, -1, 0
	v_mbcnt_hi_u32_b32 v1, -1, v1
	v_mbcnt_lo_u32_b32 v0, -1, 0
	v_mbcnt_hi_u32_b32 v0, -1, v0
	s_lshl_b32 s8, s4, 3
	v_or_b32_e32 v0, s40, v0
	v_ashrrev_i32_e32 v0, 6, v0
	v_add_u32_e32 v50, s8, v0
	s_mov_b32 s4, 0x10000
	v_cmp_gt_i32_e32 vcc, s4, v50
	s_mul_hi_i32 s19, s16, 0xc00
	s_mul_i32 s18, s16, 0xc00
	s_and_saveexec_b64 s[22:23], vcc
	s_cbranch_execz .LBB0_292
	s_waitcnt lgkmcnt(0)
	s_load_dwordx4 s[4:7], s[0:1], 0x38
	s_load_dwordx2 s[10:11], s[0:1], 0x70
	v_and_b32_e32 v48, 63, v1
	v_lshlrev_b32_e32 v49, 5, v48
	v_lshlrev_b32_e32 v48, 4, v48
	v_readfirstlane_b32 s8, v50
	s_mov_b32 s28, 0xffff0000
	s_mov_b32 s29, 0
	s_waitcnt lgkmcnt(0)
.Lpa_blk_loop:
	s_cmpk_lt_u32 s8, 0x800
	s_cbranch_scc0 .Lpa_done
	s_mul_i32 s24, s8, 0x30000
	s_mul_hi_u32 s25, s8, 0x30000
	s_add_u32 s12, s20, s24
	s_addc_u32 s13, s21, s25
	s_add_u32 s12, s12, 0x11ffe800
	s_addc_u32 s13, s13, 0
	s_mul_i32 s24, s8, 0x18000
	s_mul_hi_u32 s25, s8, 0x18000
	s_add_u32 s14, s20, s24
	s_addc_u32 s15, s21, s25
	s_add_u32 s14, s14, 0x32000000
	s_addc_u32 s15, s15, 0
	s_and_b32 s30, s8, 63
	v_mov_b32_e32 v84, v48
	global_load_dwordx4 v[2:5], v84, s[12:13]
	v_add_u32_e32 v84, 0x1800, v84
	global_load_dwordx4 v[6:9], v84, s[12:13]
	v_add_u32_e32 v84, 0x1800, v84
	global_load_dwordx4 v[10:13], v84, s[12:13]
	v_add_u32_e32 v84, 0x1800, v84
	global_load_dwordx4 v[14:17], v84, s[12:13]
	v_add_u32_e32 v84, 0x1800, v84
	global_load_dwordx4 v[18:21], v84, s[12:13]
	v_add_u32_e32 v84, 0x1800, v84
	global_load_dwordx4 v[22:25], v84, s[12:13]
	v_add_u32_e32 v84, 0x1800, v84
	v_add_u32_e32 v26, 0x0, v49
	global_load_dwordx4 v[32:35], v26, s[4:5]
	global_load_dwordx4 v[36:39], v26, s[4:5] offset:16
	global_load_dwordx4 v[40:43], v26, s[6:7]
	global_load_dwordx4 v[44:47], v26, s[6:7] offset:16
	v_mov_b32_e32 v85, v48
	v_mov_b32_e32 v68, v48
	s_waitcnt vmcnt(0)
	s_cmp_lg_u32 s30, 0
	s_cbranch_scc1 .Lpa0_nofirst
	v_mov_b32_e32 v2, 0
	v_mov_b32_e32 v3, 0
	v_mov_b32_e32 v4, 0
	v_mov_b32_e32 v5, 0
.Lpa0_nofirst:
	s_mov_b32 s17, 0
.Lpa0_loop:
	s_waitcnt vmcnt(6)
	v_lshlrev_b32_e32 v26, 16, v6
	v_and_b32_e32 v27, 0xffff0000, v6
	v_lshlrev_b32_e32 v28, 16, v2
	v_and_b32_e32 v29, 0xffff0000, v2
	v_lshlrev_b32_e32 v30, 16, v10
	v_and_b32_e32 v31, 0xffff0000, v10
	v_pk_add_f32 v[28:29], v[28:29], v[26:27] neg_lo:[0,1] neg_hi:[0,1]
	v_pk_add_f32 v[30:31], v[30:31], v[26:27] neg_lo:[0,1] neg_hi:[0,1]
	v_pk_fma_f32 v[26:27], v[28:29], v[32:33], v[26:27]
	v_pk_fma_f32 v[60:61], v[30:31], v[40:41], v[26:27]
	v_lshlrev_b32_e32 v26, 16, v7
	v_and_b32_e32 v27, 0xffff0000, v7
	v_lshlrev_b32_e32 v28, 16, v3
	v_and_b32_e32 v29, 0xffff0000, v3
	v_lshlrev_b32_e32 v30, 16, v11
	v_and_b32_e32 v31, 0xffff0000, v11
	v_pk_add_f32 v[28:29], v[28:29], v[26:27] neg_lo:[0,1] neg_hi:[0,1]
	v_pk_add_f32 v[30:31], v[30:31], v[26:27] neg_lo:[0,1] neg_hi:[0,1]
	v_pk_fma_f32 v[26:27], v[28:29], v[34:35], v[26:27]
	v_pk_fma_f32 v[62:63], v[30:31], v[42:43], v[26:27]
	v_lshlrev_b32_e32 v26, 16, v8
	v_and_b32_e32 v27, 0xffff0000, v8
	v_lshlrev_b32_e32 v28, 16, v4
	v_and_b32_e32 v29, 0xffff0000, v4
	v_lshlrev_b32_e32 v30, 16, v12
	v_and_b32_e32 v31, 0xffff0000, v12
	v_pk_add_f32 v[28:29], v[28:29], v[26:27] neg_lo:[0,1] neg_hi:[0,1]
	v_pk_add_f32 v[30:31], v[30:31], v[26:27] neg_lo:[0,1] neg_hi:[0,1]
	v_pk_fma_f32 v[26:27], v[28:29], v[36:37], v[26:27]
	v_pk_fma_f32 v[64:65], v[30:31], v[44:45], v[26:27]
	v_lshlrev_b32_e32 v26, 16, v9
	v_and_b32_e32 v27, 0xffff0000, v9
	v_lshlrev_b32_e32 v28, 16, v5
	v_and_b32_e32 v29, 0xffff0000, v5
	v_lshlrev_b32_e32 v30, 16, v13
	v_and_b32_e32 v31, 0xffff0000, v13
	v_pk_add_f32 v[28:29], v[28:29], v[26:27] neg_lo:[0,1] neg_hi:[0,1]
	v_pk_add_f32 v[30:31], v[30:31], v[26:27] neg_lo:[0,1] neg_hi:[0,1]
	v_pk_fma_f32 v[26:27], v[28:29], v[38:39], v[26:27]
	v_pk_fma_f32 v[66:67], v[30:31], v[46:47], v[26:27]
	v_cvt_pk_bf16_f32 v80, v60, v61
	v_cvt_pk_bf16_f32 v81, v62, v63
	v_cvt_pk_bf16_f32 v82, v64, v65
	v_cvt_pk_bf16_f32 v83, v66, v67
	global_store_dwordx4 v85, v[80:83], s[14:15]
	v_add_u32_e32 v85, 0xc00, v85
	global_load_dwordx4 v[2:5], v84, s[12:13]
	v_add_u32_e32 v84, 0x1800, v84
	s_add_u32 s17, s17, 6
	s_cmp_eq_u32 s17, 36
	s_cbranch_scc1 .Lpa0_last
	s_waitcnt vmcnt(6)
	v_lshlrev_b32_e32 v26, 16, v10
	v_and_b32_e32 v27, 0xffff0000, v10
	v_lshlrev_b32_e32 v28, 16, v6
	v_and_b32_e32 v29, 0xffff0000, v6
	v_lshlrev_b32_e32 v30, 16, v14
	v_and_b32_e32 v31, 0xffff0000, v14
	v_pk_add_f32 v[28:29], v[28:29], v[26:27] neg_lo:[0,1] neg_hi:[0,1]
	v_pk_add_f32 v[30:31], v[30:31], v[26:27] neg_lo:[0,1] neg_hi:[0,1]
	v_pk_fma_f32 v[26:27], v[28:29], v[32:33], v[26:27]
	v_pk_fma_f32 v[60:61], v[30:31], v[40:41], v[26:27]
	v_lshlrev_b32_e32 v26, 16, v11
	v_and_b32_e32 v27, 0xffff0000, v11
	v_lshlrev_b32_e32 v28, 16, v7
	v_and_b32_e32 v29, 0xffff0000, v7
	v_lshlrev_b32_e32 v30, 16, v15
	v_and_b32_e32 v31, 0xffff0000, v15
	v_pk_add_f32 v[28:29], v[28:29], v[26:27] neg_lo:[0,1] neg_hi:[0,1]
	v_pk_add_f32 v[30:31], v[30:31], v[26:27] neg_lo:[0,1] neg_hi:[0,1]
	v_pk_fma_f32 v[26:27], v[28:29], v[34:35], v[26:27]
	v_pk_fma_f32 v[62:63], v[30:31], v[42:43], v[26:27]
	v_lshlrev_b32_e32 v26, 16, v12
	v_and_b32_e32 v27, 0xffff0000, v12
	v_lshlrev_b32_e32 v28, 16, v8
	v_and_b32_e32 v29, 0xffff0000, v8
	v_lshlrev_b32_e32 v30, 16, v16
	v_and_b32_e32 v31, 0xffff0000, v16
	v_pk_add_f32 v[28:29], v[28:29], v[26:27] neg_lo:[0,1] neg_hi:[0,1]
	v_pk_add_f32 v[30:31], v[30:31], v[26:27] neg_lo:[0,1] neg_hi:[0,1]
	v_pk_fma_f32 v[26:27], v[28:29], v[36:37], v[26:27]
	v_pk_fma_f32 v[64:65], v[30:31], v[44:45], v[26:27]
	v_lshlrev_b32_e32 v26, 16, v13
	v_and_b32_e32 v27, 0xffff0000, v13
	v_lshlrev_b32_e32 v28, 16, v9
	v_and_b32_e32 v29, 0xffff0000, v9
	v_lshlrev_b32_e32 v30, 16, v17
	v_and_b32_e32 v31, 0xffff0000, v17
	v_pk_add_f32 v[28:29], v[28:29], v[26:27] neg_lo:[0,1] neg_hi:[0,1]
	v_pk_add_f32 v[30:31], v[30:31], v[26:27] neg_lo:[0,1] neg_hi:[0,1]
	v_pk_fma_f32 v[26:27], v[28:29], v[38:39], v[26:27]
	v_pk_fma_f32 v[66:67], v[30:31], v[46:47], v[26:27]
	v_cvt_pk_bf16_f32 v80, v60, v61
	v_cvt_pk_bf16_f32 v81, v62, v63
	v_cvt_pk_bf16_f32 v82, v64, v65
	v_cvt_pk_bf16_f32 v83, v66, v67
	global_store_dwordx4 v85, v[80:83], s[14:15]
	v_add_u32_e32 v85, 0xc00, v85
	global_load_dwordx4 v[6:9], v84, s[12:13]
	v_add_u32_e32 v84, 0x1800, v84
	s_waitcnt vmcnt(6)
	v_lshlrev_b32_e32 v26, 16, v14
	v_and_b32_e32 v27, 0xffff0000, v14
	v_lshlrev_b32_e32 v28, 16, v10
	v_and_b32_e32 v29, 0xffff0000, v10
	v_lshlrev_b32_e32 v30, 16, v18
	v_and_b32_e32 v31, 0xffff0000, v18
	v_pk_add_f32 v[28:29], v[28:29], v[26:27] neg_lo:[0,1] neg_hi:[0,1]
	v_pk_add_f32 v[30:31], v[30:31], v[26:27] neg_lo:[0,1] neg_hi:[0,1]
	v_pk_fma_f32 v[26:27], v[28:29], v[32:33], v[26:27]
	v_pk_fma_f32 v[60:61], v[30:31], v[40:41], v[26:27]
	v_lshlrev_b32_e32 v26, 16, v15
	v_and_b32_e32 v27, 0xffff0000, v15
	v_lshlrev_b32_e32 v28, 16, v11
	v_and_b32_e32 v29, 0xffff0000, v11
	v_lshlrev_b32_e32 v30, 16, v19
	v_and_b32_e32 v31, 0xffff0000, v19
	v_pk_add_f32 v[28:29], v[28:29], v[26:27] neg_lo:[0,1] neg_hi:[0,1]
	v_pk_add_f32 v[30:31], v[30:31], v[26:27] neg_lo:[0,1] neg_hi:[0,1]
	v_pk_fma_f32 v[26:27], v[28:29], v[34:35], v[26:27]
	v_pk_fma_f32 v[62:63], v[30:31], v[42:43], v[26:27]
	v_lshlrev_b32_e32 v26, 16, v16
	v_and_b32_e32 v27, 0xffff0000, v16
	v_lshlrev_b32_e32 v28, 16, v12
	v_and_b32_e32 v29, 0xffff0000, v12
	v_lshlrev_b32_e32 v30, 16, v20
	v_and_b32_e32 v31, 0xffff0000, v20
	v_pk_add_f32 v[28:29], v[28:29], v[26:27] neg_lo:[0,1] neg_hi:[0,1]
	v_pk_add_f32 v[30:31], v[30:31], v[26:27] neg_lo:[0,1] neg_hi:[0,1]
	v_pk_fma_f32 v[26:27], v[28:29], v[36:37], v[26:27]
	v_pk_fma_f32 v[64:65], v[30:31], v[44:45], v[26:27]
	v_lshlrev_b32_e32 v26, 16, v17
	v_and_b32_e32 v27, 0xffff0000, v17
	v_lshlrev_b32_e32 v28, 16, v13
	v_and_b32_e32 v29, 0xffff0000, v13
	v_lshlrev_b32_e32 v30, 16, v21
	v_and_b32_e32 v31, 0xffff0000, v21
	v_pk_add_f32 v[28:29], v[28:29], v[26:27] neg_lo:[0,1] neg_hi:[0,1]
	v_pk_add_f32 v[30:31], v[30:31], v[26:27] neg_lo:[0,1] neg_hi:[0,1]
	v_pk_fma_f32 v[26:27], v[28:29], v[38:39], v[26:27]
	v_pk_fma_f32 v[66:67], v[30:31], v[46:47], v[26:27]
	v_cvt_pk_bf16_f32 v80, v60, v61
	v_cvt_pk_bf16_f32 v81, v62, v63
	v_cvt_pk_bf16_f32 v82, v64, v65
	v_cvt_pk_bf16_f32 v83, v66, v67
	global_store_dwordx4 v85, v[80:83], s[14:15]
	v_add_u32_e32 v85, 0xc00, v85
	global_load_dwordx4 v[10:13], v84, s[12:13]
	v_add_u32_e32 v84, 0x1800, v84
	s_waitcnt vmcnt(6)
	v_lshlrev_b32_e32 v26, 16, v18
	v_and_b32_e32 v27, 0xffff0000, v18
	v_lshlrev_b32_e32 v28, 16, v14
	v_and_b32_e32 v29, 0xffff0000, v14
	v_lshlrev_b32_e32 v30, 16, v22
	v_and_b32_e32 v31, 0xffff0000, v22
	v_pk_add_f32 v[28:29], v[28:29], v[26:27] neg_lo:[0,1] neg_hi:[0,1]
	v_pk_add_f32 v[30:31], v[30:31], v[26:27] neg_lo:[0,1] neg_hi:[0,1]
	v_pk_fma_f32 v[26:27], v[28:29], v[32:33], v[26:27]
	v_pk_fma_f32 v[60:61], v[30:31], v[40:41], v[26:27]
	v_lshlrev_b32_e32 v26, 16, v19
	v_and_b32_e32 v27, 0xffff0000, v19
	v_lshlrev_b32_e32 v28, 16, v15
	v_and_b32_e32 v29, 0xffff0000, v15
	v_lshlrev_b32_e32 v30, 16, v23
	v_and_b32_e32 v31, 0xffff0000, v23
	v_pk_add_f32 v[28:29], v[28:29], v[26:27] neg_lo:[0,1] neg_hi:[0,1]
	v_pk_add_f32 v[30:31], v[30:31], v[26:27] neg_lo:[0,1] neg_hi:[0,1]
	v_pk_fma_f32 v[26:27], v[28:29], v[34:35], v[26:27]
	v_pk_fma_f32 v[62:63], v[30:31], v[42:43], v[26:27]
	v_lshlrev_b32_e32 v26, 16, v20
	v_and_b32_e32 v27, 0xffff0000, v20
	v_lshlrev_b32_e32 v28, 16, v16
	v_and_b32_e32 v29, 0xffff0000, v16
	v_lshlrev_b32_e32 v30, 16, v24
	v_and_b32_e32 v31, 0xffff0000, v24
	v_pk_add_f32 v[28:29], v[28:29], v[26:27] neg_lo:[0,1] neg_hi:[0,1]
	v_pk_add_f32 v[30:31], v[30:31], v[26:27] neg_lo:[0,1] neg_hi:[0,1]
	v_pk_fma_f32 v[26:27], v[28:29], v[36:37], v[26:27]
	v_pk_fma_f32 v[64:65], v[30:31], v[44:45], v[26:27]
	v_lshlrev_b32_e32 v26, 16, v21
	v_and_b32_e32 v27, 0xffff0000, v21
	v_lshlrev_b32_e32 v28, 16, v17
	v_and_b32_e32 v29, 0xffff0000, v17
	v_lshlrev_b32_e32 v30, 16, v25
	v_and_b32_e32 v31, 0xffff0000, v25
	v_pk_add_f32 v[28:29], v[28:29], v[26:27] neg_lo:[0,1] neg_hi:[0,1]
	v_pk_add_f32 v[30:31], v[30:31], v[26:27] neg_lo:[0,1] neg_hi:[0,1]
	v_pk_fma_f32 v[26:27], v[28:29], v[38:39], v[26:27]
	v_pk_fma_f32 v[66:67], v[30:31], v[46:47], v[26:27]
	v_cvt_pk_bf16_f32 v80, v60, v61
	v_cvt_pk_bf16_f32 v81, v62, v63
	v_cvt_pk_bf16_f32 v82, v64, v65
	v_cvt_pk_bf16_f32 v83, v66, v67
	global_store_dwordx4 v85, v[80:83], s[14:15]
	v_add_u32_e32 v85, 0xc00, v85
	global_load_dwordx4 v[14:17], v84, s[12:13]
	v_add_u32_e32 v84, 0x1800, v84
	s_waitcnt vmcnt(6)
	v_lshlrev_b32_e32 v26, 16, v22
	v_and_b32_e32 v27, 0xffff0000, v22
	v_lshlrev_b32_e32 v28, 16, v18
	v_and_b32_e32 v29, 0xffff0000, v18
	v_lshlrev_b32_e32 v30, 16, v2
	v_and_b32_e32 v31, 0xffff0000, v2
	v_pk_add_f32 v[28:29], v[28:29], v[26:27] neg_lo:[0,1] neg_hi:[0,1]
	v_pk_add_f32 v[30:31], v[30:31], v[26:27] neg_lo:[0,1] neg_hi:[0,1]
	v_pk_fma_f32 v[26:27], v[28:29], v[32:33], v[26:27]
	v_pk_fma_f32 v[60:61], v[30:31], v[40:41], v[26:27]
	v_lshlrev_b32_e32 v26, 16, v23
	v_and_b32_e32 v27, 0xffff0000, v23
	v_lshlrev_b32_e32 v28, 16, v19
	v_and_b32_e32 v29, 0xffff0000, v19
	v_lshlrev_b32_e32 v30, 16, v3
	v_and_b32_e32 v31, 0xffff0000, v3
	v_pk_add_f32 v[28:29], v[28:29], v[26:27] neg_lo:[0,1] neg_hi:[0,1]
	v_pk_add_f32 v[30:31], v[30:31], v[26:27] neg_lo:[0,1] neg_hi:[0,1]
	v_pk_fma_f32 v[26:27], v[28:29], v[34:35], v[26:27]
	v_pk_fma_f32 v[62:63], v[30:31], v[42:43], v[26:27]
	v_lshlrev_b32_e32 v26, 16, v24
	v_and_b32_e32 v27, 0xffff0000, v24
	v_lshlrev_b32_e32 v28, 16, v20
	v_and_b32_e32 v29, 0xffff0000, v20
	v_lshlrev_b32_e32 v30, 16, v4
	v_and_b32_e32 v31, 0xffff0000, v4
	v_pk_add_f32 v[28:29], v[28:29], v[26:27] neg_lo:[0,1] neg_hi:[0,1]
	v_pk_add_f32 v[30:31], v[30:31], v[26:27] neg_lo:[0,1] neg_hi:[0,1]
	v_pk_fma_f32 v[26:27], v[28:29], v[36:37], v[26:27]
	v_pk_fma_f32 v[64:65], v[30:31], v[44:45], v[26:27]
	v_lshlrev_b32_e32 v26, 16, v25
	v_and_b32_e32 v27, 0xffff0000, v25
	v_lshlrev_b32_e32 v28, 16, v21
	v_and_b32_e32 v29, 0xffff0000, v21
	v_lshlrev_b32_e32 v30, 16, v5
	v_and_b32_e32 v31, 0xffff0000, v5
	v_pk_add_f32 v[28:29], v[28:29], v[26:27] neg_lo:[0,1] neg_hi:[0,1]
	v_pk_add_f32 v[30:31], v[30:31], v[26:27] neg_lo:[0,1] neg_hi:[0,1]
	v_pk_fma_f32 v[26:27], v[28:29], v[38:39], v[26:27]
	v_pk_fma_f32 v[66:67], v[30:31], v[46:47], v[26:27]
	v_cvt_pk_bf16_f32 v80, v60, v61
	v_cvt_pk_bf16_f32 v81, v62, v63
	v_cvt_pk_bf16_f32 v82, v64, v65
	v_cvt_pk_bf16_f32 v83, v66, v67
	global_store_dwordx4 v85, v[80:83], s[14:15]
	v_add_u32_e32 v85, 0xc00, v85
	global_load_dwordx4 v[18:21], v84, s[12:13]
	v_add_u32_e32 v84, 0x1800, v84
	s_waitcnt vmcnt(6)
	v_lshlrev_b32_e32 v26, 16, v2
	v_and_b32_e32 v27, 0xffff0000, v2
	v_lshlrev_b32_e32 v28, 16, v22
	v_and_b32_e32 v29, 0xffff0000, v22
	v_lshlrev_b32_e32 v30, 16, v6
	v_and_b32_e32 v31, 0xffff0000, v6
	v_pk_add_f32 v[28:29], v[28:29], v[26:27] neg_lo:[0,1] neg_hi:[0,1]
	v_pk_add_f32 v[30:31], v[30:31], v[26:27] neg_lo:[0,1] neg_hi:[0,1]
	v_pk_fma_f32 v[26:27], v[28:29], v[32:33], v[26:27]
	v_pk_fma_f32 v[60:61], v[30:31], v[40:41], v[26:27]
	v_lshlrev_b32_e32 v26, 16, v3
	v_and_b32_e32 v27, 0xffff0000, v3
	v_lshlrev_b32_e32 v28, 16, v23
	v_and_b32_e32 v29, 0xffff0000, v23
	v_lshlrev_b32_e32 v30, 16, v7
	v_and_b32_e32 v31, 0xffff0000, v7
	v_pk_add_f32 v[28:29], v[28:29], v[26:27] neg_lo:[0,1] neg_hi:[0,1]
	v_pk_add_f32 v[30:31], v[30:31], v[26:27] neg_lo:[0,1] neg_hi:[0,1]
	v_pk_fma_f32 v[26:27], v[28:29], v[34:35], v[26:27]
	v_pk_fma_f32 v[62:63], v[30:31], v[42:43], v[26:27]
	v_lshlrev_b32_e32 v26, 16, v4
	v_and_b32_e32 v27, 0xffff0000, v4
	v_lshlrev_b32_e32 v28, 16, v24
	v_and_b32_e32 v29, 0xffff0000, v24
	v_lshlrev_b32_e32 v30, 16, v8
	v_and_b32_e32 v31, 0xffff0000, v8
	v_pk_add_f32 v[28:29], v[28:29], v[26:27] neg_lo:[0,1] neg_hi:[0,1]
	v_pk_add_f32 v[30:31], v[30:31], v[26:27] neg_lo:[0,1] neg_hi:[0,1]
	v_pk_fma_f32 v[26:27], v[28:29], v[36:37], v[26:27]
	v_pk_fma_f32 v[64:65], v[30:31], v[44:45], v[26:27]
	v_lshlrev_b32_e32 v26, 16, v5
	v_and_b32_e32 v27, 0xffff0000, v5
	v_lshlrev_b32_e32 v28, 16, v25
	v_and_b32_e32 v29, 0xffff0000, v25
	v_lshlrev_b32_e32 v30, 16, v9
	v_and_b32_e32 v31, 0xffff0000, v9
	v_pk_add_f32 v[28:29], v[28:29], v[26:27] neg_lo:[0,1] neg_hi:[0,1]
	v_pk_add_f32 v[30:31], v[30:31], v[26:27] neg_lo:[0,1] neg_hi:[0,1]
	v_pk_fma_f32 v[26:27], v[28:29], v[38:39], v[26:27]
	v_pk_fma_f32 v[66:67], v[30:31], v[46:47], v[26:27]
	v_cvt_pk_bf16_f32 v80, v60, v61
	v_cvt_pk_bf16_f32 v81, v62, v63
	v_cvt_pk_bf16_f32 v82, v64, v65
	v_cvt_pk_bf16_f32 v83, v66, v67
	global_store_dwordx4 v85, v[80:83], s[14:15]
	v_add_u32_e32 v85, 0xc00, v85
	global_load_dwordx4 v[22:25], v84, s[12:13]
	v_add_u32_e32 v84, 0x1800, v84
	s_branch .Lpa0_loop
.Lpa0_last:
	s_waitcnt vmcnt(0)
	s_cmp_lg_u32 s30, 63
	s_cbranch_scc1 .Lpa0_nolast
	v_mov_b32_e32 v14, 0
	v_mov_b32_e32 v15, 0
	v_mov_b32_e32 v16, 0
	v_mov_b32_e32 v17, 0
.Lpa0_nolast:
	v_lshlrev_b32_e32 v26, 16, v10
	v_and_b32_e32 v27, 0xffff0000, v10
	v_lshlrev_b32_e32 v28, 16, v6
	v_and_b32_e32 v29, 0xffff0000, v6
	v_lshlrev_b32_e32 v30, 16, v14
	v_and_b32_e32 v31, 0xffff0000, v14
	v_pk_add_f32 v[28:29], v[28:29], v[26:27] neg_lo:[0,1] neg_hi:[0,1]
	v_pk_add_f32 v[30:31], v[30:31], v[26:27] neg_lo:[0,1] neg_hi:[0,1]
	v_pk_fma_f32 v[26:27], v[28:29], v[32:33], v[26:27]
	v_pk_fma_f32 v[60:61], v[30:31], v[40:41], v[26:27]
	v_lshlrev_b32_e32 v26, 16, v11
	v_and_b32_e32 v27, 0xffff0000, v11
	v_lshlrev_b32_e32 v28, 16, v7
	v_and_b32_e32 v29, 0xffff0000, v7
	v_lshlrev_b32_e32 v30, 16, v15
	v_and_b32_e32 v31, 0xffff0000, v15
	v_pk_add_f32 v[28:29], v[28:29], v[26:27] neg_lo:[0,1] neg_hi:[0,1]
	v_pk_add_f32 v[30:31], v[30:31], v[26:27] neg_lo:[0,1] neg_hi:[0,1]
	v_pk_fma_f32 v[26:27], v[28:29], v[34:35], v[26:27]
	v_pk_fma_f32 v[62:63], v[30:31], v[42:43], v[26:27]
	v_lshlrev_b32_e32 v26, 16, v12
	v_and_b32_e32 v27, 0xffff0000, v12
	v_lshlrev_b32_e32 v28, 16, v8
	v_and_b32_e32 v29, 0xffff0000, v8
	v_lshlrev_b32_e32 v30, 16, v16
	v_and_b32_e32 v31, 0xffff0000, v16
	v_pk_add_f32 v[28:29], v[28:29], v[26:27] neg_lo:[0,1] neg_hi:[0,1]
	v_pk_add_f32 v[30:31], v[30:31], v[26:27] neg_lo:[0,1] neg_hi:[0,1]
	v_pk_fma_f32 v[26:27], v[28:29], v[36:37], v[26:27]
	v_pk_fma_f32 v[64:65], v[30:31], v[44:45], v[26:27]
	v_lshlrev_b32_e32 v26, 16, v13
	v_and_b32_e32 v27, 0xffff0000, v13
	v_lshlrev_b32_e32 v28, 16, v9
	v_and_b32_e32 v29, 0xffff0000, v9
	v_lshlrev_b32_e32 v30, 16, v17
	v_and_b32_e32 v31, 0xffff0000, v17
	v_pk_add_f32 v[28:29], v[28:29], v[26:27] neg_lo:[0,1] neg_hi:[0,1]
	v_pk_add_f32 v[30:31], v[30:31], v[26:27] neg_lo:[0,1] neg_hi:[0,1]
	v_pk_fma_f32 v[26:27], v[28:29], v[38:39], v[26:27]
	v_pk_fma_f32 v[66:67], v[30:31], v[46:47], v[26:27]
	v_cvt_pk_bf16_f32 v80, v60, v61
	v_cvt_pk_bf16_f32 v81, v62, v63
	v_cvt_pk_bf16_f32 v82, v64, v65
	v_cvt_pk_bf16_f32 v83, v66, v67
	global_store_dwordx4 v85, v[80:83], s[14:15]
	v_add_u32_e32 v85, 0xc00, v85
	s_lshl_b32 s24, s8, 15
	s_add_u32 s34, s20, s24
	s_addc_u32 s35, s21, 0
	s_add_u32 s34, s34, 0xa000000
	s_addc_u32 s35, s35, 0
	v_mov_b32_e32 v84, v48
	global_load_dwordx4 v[2:5], v84, s[12:13] offset:1024
	v_add_u32_e32 v84, 0x1800, v84
	global_load_dwordx4 v[6:9], v84, s[12:13] offset:1024
	v_add_u32_e32 v84, 0x1800, v84
	global_load_dwordx4 v[10:13], v84, s[12:13] offset:1024
	v_add_u32_e32 v84, 0x1800, v84
	global_load_dwordx4 v[14:17], v84, s[12:13] offset:1024
	v_add_u32_e32 v84, 0x1800, v84
	global_load_dwordx4 v[18:21], v84, s[12:13] offset:1024
	v_add_u32_e32 v84, 0x1800, v84
	global_load_dwordx4 v[22:25], v84, s[12:13] offset:1024
	v_add_u32_e32 v84, 0x1800, v84
	v_add_u32_e32 v26, 0x800, v49
	global_load_dwordx4 v[32:35], v26, s[4:5]
	global_load_dwordx4 v[36:39], v26, s[4:5] offset:16
	global_load_dwordx4 v[40:43], v26, s[6:7]
	global_load_dwordx4 v[44:47], v26, s[6:7] offset:16
	global_load_dwordx4 v[52:55], v49, s[10:11]
	global_load_dwordx4 v[56:59], v49, s[10:11] offset:16
	v_mov_b32_e32 v85, v48
	v_mov_b32_e32 v68, v48
	s_waitcnt vmcnt(0)
	s_cmp_lg_u32 s30, 0
	s_cbranch_scc1 .Lpa1_nofirst
	v_mov_b32_e32 v2, 0
	v_mov_b32_e32 v3, 0
	v_mov_b32_e32 v4, 0
	v_mov_b32_e32 v5, 0

.Lpa1_loop:
	s_waitcnt vmcnt(9)
	v_lshlrev_b32_e32 v26, 16, v6
	v_and_b32_e32 v27, 0xffff0000, v6
	v_lshlrev_b32_e32 v28, 16, v2
	v_and_b32_e32 v29, 0xffff0000, v2
	v_lshlrev_b32_e32 v30, 16, v10
	v_and_b32_e32 v31, 0xffff0000, v10
	v_pk_add_f32 v[28:29], v[28:29], v[26:27] neg_lo:[0,1] neg_hi:[0,1]
	v_pk_add_f32 v[30:31], v[30:31], v[26:27] neg_lo:[0,1] neg_hi:[0,1]
	v_pk_fma_f32 v[26:27], v[28:29], v[32:33], v[26:27]
	v_pk_fma_f32 v[60:61], v[30:31], v[40:41], v[26:27]
	v_lshlrev_b32_e32 v26, 16, v7
	v_and_b32_e32 v27, 0xffff0000, v7
	v_lshlrev_b32_e32 v28, 16, v3
	v_and_b32_e32 v29, 0xffff0000, v3
	v_lshlrev_b32_e32 v30, 16, v11
	v_and_b32_e32 v31, 0xffff0000, v11
	v_pk_add_f32 v[28:29], v[28:29], v[26:27] neg_lo:[0,1] neg_hi:[0,1]
	v_pk_add_f32 v[30:31], v[30:31], v[26:27] neg_lo:[0,1] neg_hi:[0,1]
	v_pk_fma_f32 v[26:27], v[28:29], v[34:35], v[26:27]
	v_pk_fma_f32 v[62:63], v[30:31], v[42:43], v[26:27]
	v_lshlrev_b32_e32 v26, 16, v8
	v_and_b32_e32 v27, 0xffff0000, v8
	v_lshlrev_b32_e32 v28, 16, v4
	v_and_b32_e32 v29, 0xffff0000, v4
	v_lshlrev_b32_e32 v30, 16, v12
	v_and_b32_e32 v31, 0xffff0000, v12
	v_pk_add_f32 v[28:29], v[28:29], v[26:27] neg_lo:[0,1] neg_hi:[0,1]
	v_pk_add_f32 v[30:31], v[30:31], v[26:27] neg_lo:[0,1] neg_hi:[0,1]
	v_pk_fma_f32 v[26:27], v[28:29], v[36:37], v[26:27]
	v_pk_fma_f32 v[64:65], v[30:31], v[44:45], v[26:27]
	v_lshlrev_b32_e32 v26, 16, v9
	v_and_b32_e32 v27, 0xffff0000, v9
	v_lshlrev_b32_e32 v28, 16, v5
	v_and_b32_e32 v29, 0xffff0000, v5
	v_lshlrev_b32_e32 v30, 16, v13
	v_and_b32_e32 v31, 0xffff0000, v13
	v_pk_add_f32 v[28:29], v[28:29], v[26:27] neg_lo:[0,1] neg_hi:[0,1]
	v_pk_add_f32 v[30:31], v[30:31], v[26:27] neg_lo:[0,1] neg_hi:[0,1]
	v_pk_fma_f32 v[26:27], v[28:29], v[38:39], v[26:27]
	v_pk_fma_f32 v[66:67], v[30:31], v[46:47], v[26:27]
	v_cvt_pk_bf16_f32 v80, v60, v61
	v_cvt_pk_bf16_f32 v81, v62, v63
	v_cvt_pk_bf16_f32 v82, v64, v65
	v_cvt_pk_bf16_f32 v83, v66, v67
	global_store_dwordx4 v85, v[80:83], s[14:15] offset:1024
	v_add_u32_e32 v85, 0xc00, v85
	v_pk_mul_f32 v[60:61], v[60:61], v[52:53]
	v_pk_mul_f32 v[62:63], v[62:63], v[54:55]
	v_pk_mul_f32 v[64:65], v[64:65], v[56:57]
	v_pk_mul_f32 v[66:67], v[66:67], v[58:59]
	v_pk_mul_f32 v[26:27], v[60:61], v[60:61]
	v_pk_fma_f32 v[26:27], v[62:63], v[62:63], v[26:27]
	v_pk_fma_f32 v[26:27], v[64:65], v[64:65], v[26:27]
	v_pk_fma_f32 v[26:27], v[66:67], v[66:67], v[26:27]
	v_add_f32_e32 v28, v26, v27
	s_nop 1
	v_add_f32_dpp v28, v28, v28 quad_perm:[1,0,3,2] row_mask:0xf bank_mask:0xf
	s_nop 1
	v_add_f32_dpp v28, v28, v28 quad_perm:[2,3,0,1] row_mask:0xf bank_mask:0xf
	s_nop 1
	v_add_f32_dpp v28, v28, v28 row_half_mirror row_mask:0xf bank_mask:0xf
	s_nop 0
	v_add_f32_e32 v28, 0x2b8cbccc, v28
	v_rsq_f32_e32 v28, v28
	s_nop 0
	v_pk_mul_f32 v[60:61], v[60:61], v[28:29] op_sel_hi:[1,0]
	v_pk_mul_f32 v[62:63], v[62:63], v[28:29] op_sel_hi:[1,0]
	v_pk_mul_f32 v[64:65], v[64:65], v[28:29] op_sel_hi:[1,0]
	v_pk_mul_f32 v[66:67], v[66:67], v[28:29] op_sel_hi:[1,0]
	v_cvt_pk_bf16_f32 v80, v60, v61
	v_cvt_pk_bf16_f32 v81, v62, v63
	v_cvt_pk_bf16_f32 v82, v64, v65
	v_cvt_pk_bf16_f32 v83, v66, v67
	global_store_dwordx4 v68, v[80:83], s[34:35]
	v_add_u32_e32 v68, 0x400, v68
	global_load_dwordx4 v[2:5], v84, s[12:13] offset:1024
	v_add_u32_e32 v84, 0x1800, v84
	s_add_u32 s17, s17, 6
	s_cmp_eq_u32 s17, 36
	s_cbranch_scc1 .Lpa1_last
	s_waitcnt vmcnt(9)
	v_lshlrev_b32_e32 v26, 16, v10
	v_and_b32_e32 v27, 0xffff0000, v10
	v_lshlrev_b32_e32 v28, 16, v6
	v_and_b32_e32 v29, 0xffff0000, v6
	v_lshlrev_b32_e32 v30, 16, v14
	v_and_b32_e32 v31, 0xffff0000, v14
	v_pk_add_f32 v[28:29], v[28:29], v[26:27] neg_lo:[0,1] neg_hi:[0,1]
	v_pk_add_f32 v[30:31], v[30:31], v[26:27] neg_lo:[0,1] neg_hi:[0,1]
	v_pk_fma_f32 v[26:27], v[28:29], v[32:33], v[26:27]
	v_pk_fma_f32 v[60:61], v[30:31], v[40:41], v[26:27]
	v_lshlrev_b32_e32 v26, 16, v11
	v_and_b32_e32 v27, 0xffff0000, v11
	v_lshlrev_b32_e32 v28, 16, v7
	v_and_b32_e32 v29, 0xffff0000, v7
	v_lshlrev_b32_e32 v30, 16, v15
	v_and_b32_e32 v31, 0xffff0000, v15
	v_pk_add_f32 v[28:29], v[28:29], v[26:27] neg_lo:[0,1] neg_hi:[0,1]
	v_pk_add_f32 v[30:31], v[30:31], v[26:27] neg_lo:[0,1] neg_hi:[0,1]
	v_pk_fma_f32 v[26:27], v[28:29], v[34:35], v[26:27]
	v_pk_fma_f32 v[62:63], v[30:31], v[42:43], v[26:27]
	v_lshlrev_b32_e32 v26, 16, v12
	v_and_b32_e32 v27, 0xffff0000, v12
	v_lshlrev_b32_e32 v28, 16, v8
	v_and_b32_e32 v29, 0xffff0000, v8
	v_lshlrev_b32_e32 v30, 16, v16
	v_and_b32_e32 v31, 0xffff0000, v16
	v_pk_add_f32 v[28:29], v[28:29], v[26:27] neg_lo:[0,1] neg_hi:[0,1]
	v_pk_add_f32 v[30:31], v[30:31], v[26:27] neg_lo:[0,1] neg_hi:[0,1]
	v_pk_fma_f32 v[26:27], v[28:29], v[36:37], v[26:27]
	v_pk_fma_f32 v[64:65], v[30:31], v[44:45], v[26:27]
	v_lshlrev_b32_e32 v26, 16, v13
	v_and_b32_e32 v27, 0xffff0000, v13
	v_lshlrev_b32_e32 v28, 16, v9
	v_and_b32_e32 v29, 0xffff0000, v9
	v_lshlrev_b32_e32 v30, 16, v17
	v_and_b32_e32 v31, 0xffff0000, v17
	v_pk_add_f32 v[28:29], v[28:29], v[26:27] neg_lo:[0,1] neg_hi:[0,1]
	v_pk_add_f32 v[30:31], v[30:31], v[26:27] neg_lo:[0,1] neg_hi:[0,1]
	v_pk_fma_f32 v[26:27], v[28:29], v[38:39], v[26:27]
	v_pk_fma_f32 v[66:67], v[30:31], v[46:47], v[26:27]
	v_cvt_pk_bf16_f32 v80, v60, v61
	v_cvt_pk_bf16_f32 v81, v62, v63
	v_cvt_pk_bf16_f32 v82, v64, v65
	v_cvt_pk_bf16_f32 v83, v66, v67
	global_store_dwordx4 v85, v[80:83], s[14:15] offset:1024
	v_add_u32_e32 v85, 0xc00, v85
	v_pk_mul_f32 v[60:61], v[60:61], v[52:53]
	v_pk_mul_f32 v[62:63], v[62:63], v[54:55]
	v_pk_mul_f32 v[64:65], v[64:65], v[56:57]
	v_pk_mul_f32 v[66:67], v[66:67], v[58:59]
	v_pk_mul_f32 v[26:27], v[60:61], v[60:61]
	v_pk_fma_f32 v[26:27], v[62:63], v[62:63], v[26:27]
	v_pk_fma_f32 v[26:27], v[64:65], v[64:65], v[26:27]
	v_pk_fma_f32 v[26:27], v[66:67], v[66:67], v[26:27]
	v_add_f32_e32 v28, v26, v27
	s_nop 1
	v_add_f32_dpp v28, v28, v28 quad_perm:[1,0,3,2] row_mask:0xf bank_mask:0xf
	s_nop 1
	v_add_f32_dpp v28, v28, v28 quad_perm:[2,3,0,1] row_mask:0xf bank_mask:0xf
	s_nop 1
	v_add_f32_dpp v28, v28, v28 row_half_mirror row_mask:0xf bank_mask:0xf
	s_nop 0
	v_add_f32_e32 v28, 0x2b8cbccc, v28
	v_rsq_f32_e32 v28, v28
	s_nop 0
	v_pk_mul_f32 v[60:61], v[60:61], v[28:29] op_sel_hi:[1,0]
	v_pk_mul_f32 v[62:63], v[62:63], v[28:29] op_sel_hi:[1,0]
	v_pk_mul_f32 v[64:65], v[64:65], v[28:29] op_sel_hi:[1,0]
	v_pk_mul_f32 v[66:67], v[66:67], v[28:29] op_sel_hi:[1,0]
	v_cvt_pk_bf16_f32 v80, v60, v61
	v_cvt_pk_bf16_f32 v81, v62, v63
	v_cvt_pk_bf16_f32 v82, v64, v65
	v_cvt_pk_bf16_f32 v83, v66, v67
	global_store_dwordx4 v68, v[80:83], s[34:35]
	v_add_u32_e32 v68, 0x400, v68
	global_load_dwordx4 v[6:9], v84, s[12:13] offset:1024
	v_add_u32_e32 v84, 0x1800, v84
	s_waitcnt vmcnt(9)
	v_lshlrev_b32_e32 v26, 16, v14
	v_and_b32_e32 v27, 0xffff0000, v14
	v_lshlrev_b32_e32 v28, 16, v10
	v_and_b32_e32 v29, 0xffff0000, v10
	v_lshlrev_b32_e32 v30, 16, v18
	v_and_b32_e32 v31, 0xffff0000, v18
	v_pk_add_f32 v[28:29], v[28:29], v[26:27] neg_lo:[0,1] neg_hi:[0,1]
	v_pk_add_f32 v[30:31], v[30:31], v[26:27] neg_lo:[0,1] neg_hi:[0,1]
	v_pk_fma_f32 v[26:27], v[28:29], v[32:33], v[26:27]
	v_pk_fma_f32 v[60:61], v[30:31], v[40:41], v[26:27]
	v_lshlrev_b32_e32 v26, 16, v15
	v_and_b32_e32 v27, 0xffff0000, v15
	v_lshlrev_b32_e32 v28, 16, v11
	v_and_b32_e32 v29, 0xffff0000, v11
	v_lshlrev_b32_e32 v30, 16, v19
	v_and_b32_e32 v31, 0xffff0000, v19
	v_pk_add_f32 v[28:29], v[28:29], v[26:27] neg_lo:[0,1] neg_hi:[0,1]
	v_pk_add_f32 v[30:31], v[30:31], v[26:27] neg_lo:[0,1] neg_hi:[0,1]
	v_pk_fma_f32 v[26:27], v[28:29], v[34:35], v[26:27]
	v_pk_fma_f32 v[62:63], v[30:31], v[42:43], v[26:27]
	v_lshlrev_b32_e32 v26, 16, v16
	v_and_b32_e32 v27, 0xffff0000, v16
	v_lshlrev_b32_e32 v28, 16, v12
	v_and_b32_e32 v29, 0xffff0000, v12
	v_lshlrev_b32_e32 v30, 16, v20
	v_and_b32_e32 v31, 0xffff0000, v20
	v_pk_add_f32 v[28:29], v[28:29], v[26:27] neg_lo:[0,1] neg_hi:[0,1]
	v_pk_add_f32 v[30:31], v[30:31], v[26:27] neg_lo:[0,1] neg_hi:[0,1]
	v_pk_fma_f32 v[26:27], v[28:29], v[36:37], v[26:27]
	v_pk_fma_f32 v[64:65], v[30:31], v[44:45], v[26:27]
	v_lshlrev_b32_e32 v26, 16, v17
	v_and_b32_e32 v27, 0xffff0000, v17
	v_lshlrev_b32_e32 v28, 16, v13
	v_and_b32_e32 v29, 0xffff0000, v13
	v_lshlrev_b32_e32 v30, 16, v21
	v_and_b32_e32 v31, 0xffff0000, v21
	v_pk_add_f32 v[28:29], v[28:29], v[26:27] neg_lo:[0,1] neg_hi:[0,1]
	v_pk_add_f32 v[30:31], v[30:31], v[26:27] neg_lo:[0,1] neg_hi:[0,1]
	v_pk_fma_f32 v[26:27], v[28:29], v[38:39], v[26:27]
	v_pk_fma_f32 v[66:67], v[30:31], v[46:47], v[26:27]
	v_cvt_pk_bf16_f32 v80, v60, v61
	v_cvt_pk_bf16_f32 v81, v62, v63
	v_cvt_pk_bf16_f32 v82, v64, v65
	v_cvt_pk_bf16_f32 v83, v66, v67
	global_store_dwordx4 v85, v[80:83], s[14:15] offset:1024
	v_add_u32_e32 v85, 0xc00, v85
	v_pk_mul_f32 v[60:61], v[60:61], v[52:53]
	v_pk_mul_f32 v[62:63], v[62:63], v[54:55]
	v_pk_mul_f32 v[64:65], v[64:65], v[56:57]
	v_pk_mul_f32 v[66:67], v[66:67], v[58:59]
	v_pk_mul_f32 v[26:27], v[60:61], v[60:61]
	v_pk_fma_f32 v[26:27], v[62:63], v[62:63], v[26:27]
	v_pk_fma_f32 v[26:27], v[64:65], v[64:65], v[26:27]
	v_pk_fma_f32 v[26:27], v[66:67], v[66:67], v[26:27]
	v_add_f32_e32 v28, v26, v27
	s_nop 1
	v_add_f32_dpp v28, v28, v28 quad_perm:[1,0,3,2] row_mask:0xf bank_mask:0xf
	s_nop 1
	v_add_f32_dpp v28, v28, v28 quad_perm:[2,3,0,1] row_mask:0xf bank_mask:0xf
	s_nop 1
	v_add_f32_dpp v28, v28, v28 row_half_mirror row_mask:0xf bank_mask:0xf
	s_nop 0
	v_add_f32_e32 v28, 0x2b8cbccc, v28
	v_rsq_f32_e32 v28, v28
	s_nop 0
	v_pk_mul_f32 v[60:61], v[60:61], v[28:29] op_sel_hi:[1,0]
	v_pk_mul_f32 v[62:63], v[62:63], v[28:29] op_sel_hi:[1,0]
	v_pk_mul_f32 v[64:65], v[64:65], v[28:29] op_sel_hi:[1,0]
	v_pk_mul_f32 v[66:67], v[66:67], v[28:29] op_sel_hi:[1,0]
	v_cvt_pk_bf16_f32 v80, v60, v61
	v_cvt_pk_bf16_f32 v81, v62, v63
	v_cvt_pk_bf16_f32 v82, v64, v65
	v_cvt_pk_bf16_f32 v83, v66, v67
	global_store_dwordx4 v68, v[80:83], s[34:35]
	v_add_u32_e32 v68, 0x400, v68
	global_load_dwordx4 v[10:13], v84, s[12:13] offset:1024
	v_add_u32_e32 v84, 0x1800, v84
	s_waitcnt vmcnt(9)
	v_lshlrev_b32_e32 v26, 16, v18
	v_and_b32_e32 v27, 0xffff0000, v18
	v_lshlrev_b32_e32 v28, 16, v14
	v_and_b32_e32 v29, 0xffff0000, v14
	v_lshlrev_b32_e32 v30, 16, v22
	v_and_b32_e32 v31, 0xffff0000, v22
	v_pk_add_f32 v[28:29], v[28:29], v[26:27] neg_lo:[0,1] neg_hi:[0,1]
	v_pk_add_f32 v[30:31], v[30:31], v[26:27] neg_lo:[0,1] neg_hi:[0,1]
	v_pk_fma_f32 v[26:27], v[28:29], v[32:33], v[26:27]
	v_pk_fma_f32 v[60:61], v[30:31], v[40:41], v[26:27]
	v_lshlrev_b32_e32 v26, 16, v19
	v_and_b32_e32 v27, 0xffff0000, v19
	v_lshlrev_b32_e32 v28, 16, v15
	v_and_b32_e32 v29, 0xffff0000, v15
	v_lshlrev_b32_e32 v30, 16, v23
	v_and_b32_e32 v31, 0xffff0000, v23
	v_pk_add_f32 v[28:29], v[28:29], v[26:27] neg_lo:[0,1] neg_hi:[0,1]
	v_pk_add_f32 v[30:31], v[30:31], v[26:27] neg_lo:[0,1] neg_hi:[0,1]
	v_pk_fma_f32 v[26:27], v[28:29], v[34:35], v[26:27]
	v_pk_fma_f32 v[62:63], v[30:31], v[42:43], v[26:27]
	v_lshlrev_b32_e32 v26, 16, v20
	v_and_b32_e32 v27, 0xffff0000, v20
	v_lshlrev_b32_e32 v28, 16, v16
	v_and_b32_e32 v29, 0xffff0000, v16
	v_lshlrev_b32_e32 v30, 16, v24
	v_and_b32_e32 v31, 0xffff0000, v24
	v_pk_add_f32 v[28:29], v[28:29], v[26:27] neg_lo:[0,1] neg_hi:[0,1]
	v_pk_add_f32 v[30:31], v[30:31], v[26:27] neg_lo:[0,1] neg_hi:[0,1]
	v_pk_fma_f32 v[26:27], v[28:29], v[36:37], v[26:27]
	v_pk_fma_f32 v[64:65], v[30:31], v[44:45], v[26:27]
	v_lshlrev_b32_e32 v26, 16, v21
	v_and_b32_e32 v27, 0xffff0000, v21
	v_lshlrev_b32_e32 v28, 16, v17
	v_and_b32_e32 v29, 0xffff0000, v17
	v_lshlrev_b32_e32 v30, 16, v25
	v_and_b32_e32 v31, 0xffff0000, v25
	v_pk_add_f32 v[28:29], v[28:29], v[26:27] neg_lo:[0,1] neg_hi:[0,1]
	v_pk_add_f32 v[30:31], v[30:31], v[26:27] neg_lo:[0,1] neg_hi:[0,1]
	v_pk_fma_f32 v[26:27], v[28:29], v[38:39], v[26:27]
	v_pk_fma_f32 v[66:67], v[30:31], v[46:47], v[26:27]
	v_cvt_pk_bf16_f32 v80, v60, v61
	v_cvt_pk_bf16_f32 v81, v62, v63
	v_cvt_pk_bf16_f32 v82, v64, v65
	v_cvt_pk_bf16_f32 v83, v66, v67
	global_store_dwordx4 v85, v[80:83], s[14:15] offset:1024
	v_add_u32_e32 v85, 0xc00, v85
	v_pk_mul_f32 v[60:61], v[60:61], v[52:53]
	v_pk_mul_f32 v[62:63], v[62:63], v[54:55]
	v_pk_mul_f32 v[64:65], v[64:65], v[56:57]
	v_pk_mul_f32 v[66:67], v[66:67], v[58:59]
	v_pk_mul_f32 v[26:27], v[60:61], v[60:61]
	v_pk_fma_f32 v[26:27], v[62:63], v[62:63], v[26:27]
	v_pk_fma_f32 v[26:27], v[64:65], v[64:65], v[26:27]
	v_pk_fma_f32 v[26:27], v[66:67], v[66:67], v[26:27]
	v_add_f32_e32 v28, v26, v27
	s_nop 1
	v_add_f32_dpp v28, v28, v28 quad_perm:[1,0,3,2] row_mask:0xf bank_mask:0xf
	s_nop 1
	v_add_f32_dpp v28, v28, v28 quad_perm:[2,3,0,1] row_mask:0xf bank_mask:0xf
	s_nop 1
	v_add_f32_dpp v28, v28, v28 row_half_mirror row_mask:0xf bank_mask:0xf
	s_nop 0
	v_add_f32_e32 v28, 0x2b8cbccc, v28
	v_rsq_f32_e32 v28, v28
	s_nop 0
	v_pk_mul_f32 v[60:61], v[60:61], v[28:29] op_sel_hi:[1,0]
	v_pk_mul_f32 v[62:63], v[62:63], v[28:29] op_sel_hi:[1,0]
	v_pk_mul_f32 v[64:65], v[64:65], v[28:29] op_sel_hi:[1,0]
	v_pk_mul_f32 v[66:67], v[66:67], v[28:29] op_sel_hi:[1,0]
	v_cvt_pk_bf16_f32 v80, v60, v61
	v_cvt_pk_bf16_f32 v81, v62, v63
	v_cvt_pk_bf16_f32 v82, v64, v65
	v_cvt_pk_bf16_f32 v83, v66, v67
	global_store_dwordx4 v68, v[80:83], s[34:35]
	v_add_u32_e32 v68, 0x400, v68
	global_load_dwordx4 v[14:17], v84, s[12:13] offset:1024
	v_add_u32_e32 v84, 0x1800, v84
	s_waitcnt vmcnt(9)
	v_lshlrev_b32_e32 v26, 16, v22
	v_and_b32_e32 v27, 0xffff0000, v22
	v_lshlrev_b32_e32 v28, 16, v18
	v_and_b32_e32 v29, 0xffff0000, v18
	v_lshlrev_b32_e32 v30, 16, v2
	v_and_b32_e32 v31, 0xffff0000, v2
	v_pk_add_f32 v[28:29], v[28:29], v[26:27] neg_lo:[0,1] neg_hi:[0,1]
	v_pk_add_f32 v[30:31], v[30:31], v[26:27] neg_lo:[0,1] neg_hi:[0,1]
	v_pk_fma_f32 v[26:27], v[28:29], v[32:33], v[26:27]
	v_pk_fma_f32 v[60:61], v[30:31], v[40:41], v[26:27]
	v_lshlrev_b32_e32 v26, 16, v23
	v_and_b32_e32 v27, 0xffff0000, v23
	v_lshlrev_b32_e32 v28, 16, v19
	v_and_b32_e32 v29, 0xffff0000, v19
	v_lshlrev_b32_e32 v30, 16, v3
	v_and_b32_e32 v31, 0xffff0000, v3
	v_pk_add_f32 v[28:29], v[28:29], v[26:27] neg_lo:[0,1] neg_hi:[0,1]
	v_pk_add_f32 v[30:31], v[30:31], v[26:27] neg_lo:[0,1] neg_hi:[0,1]
	v_pk_fma_f32 v[26:27], v[28:29], v[34:35], v[26:27]
	v_pk_fma_f32 v[62:63], v[30:31], v[42:43], v[26:27]
	v_lshlrev_b32_e32 v26, 16, v24
	v_and_b32_e32 v27, 0xffff0000, v24
	v_lshlrev_b32_e32 v28, 16, v20
	v_and_b32_e32 v29, 0xffff0000, v20
	v_lshlrev_b32_e32 v30, 16, v4
	v_and_b32_e32 v31, 0xffff0000, v4
	v_pk_add_f32 v[28:29], v[28:29], v[26:27] neg_lo:[0,1] neg_hi:[0,1]
	v_pk_add_f32 v[30:31], v[30:31], v[26:27] neg_lo:[0,1] neg_hi:[0,1]
	v_pk_fma_f32 v[26:27], v[28:29], v[36:37], v[26:27]
	v_pk_fma_f32 v[64:65], v[30:31], v[44:45], v[26:27]
	v_lshlrev_b32_e32 v26, 16, v25
	v_and_b32_e32 v27, 0xffff0000, v25
	v_lshlrev_b32_e32 v28, 16, v21
	v_and_b32_e32 v29, 0xffff0000, v21
	v_lshlrev_b32_e32 v30, 16, v5
	v_and_b32_e32 v31, 0xffff0000, v5
	v_pk_add_f32 v[28:29], v[28:29], v[26:27] neg_lo:[0,1] neg_hi:[0,1]
	v_pk_add_f32 v[30:31], v[30:31], v[26:27] neg_lo:[0,1] neg_hi:[0,1]
	v_pk_fma_f32 v[26:27], v[28:29], v[38:39], v[26:27]
	v_pk_fma_f32 v[66:67], v[30:31], v[46:47], v[26:27]
	v_cvt_pk_bf16_f32 v80, v60, v61
	v_cvt_pk_bf16_f32 v81, v62, v63
	v_cvt_pk_bf16_f32 v82, v64, v65
	v_cvt_pk_bf16_f32 v83, v66, v67
	global_store_dwordx4 v85, v[80:83], s[14:15] offset:1024
	v_add_u32_e32 v85, 0xc00, v85
	v_pk_mul_f32 v[60:61], v[60:61], v[52:53]
	v_pk_mul_f32 v[62:63], v[62:63], v[54:55]
	v_pk_mul_f32 v[64:65], v[64:65], v[56:57]
	v_pk_mul_f32 v[66:67], v[66:67], v[58:59]
	v_pk_mul_f32 v[26:27], v[60:61], v[60:61]
	v_pk_fma_f32 v[26:27], v[62:63], v[62:63], v[26:27]
	v_pk_fma_f32 v[26:27], v[64:65], v[64:65], v[26:27]
	v_pk_fma_f32 v[26:27], v[66:67], v[66:67], v[26:27]
	v_add_f32_e32 v28, v26, v27
	s_nop 1
	v_add_f32_dpp v28, v28, v28 quad_perm:[1,0,3,2] row_mask:0xf bank_mask:0xf
	s_nop 1
	v_add_f32_dpp v28, v28, v28 quad_perm:[2,3,0,1] row_mask:0xf bank_mask:0xf
	s_nop 1
	v_add_f32_dpp v28, v28, v28 row_half_mirror row_mask:0xf bank_mask:0xf
	s_nop 0
	v_add_f32_e32 v28, 0x2b8cbccc, v28
	v_rsq_f32_e32 v28, v28
	s_nop 0
	v_pk_mul_f32 v[60:61], v[60:61], v[28:29] op_sel_hi:[1,0]
	v_pk_mul_f32 v[62:63], v[62:63], v[28:29] op_sel_hi:[1,0]
	v_pk_mul_f32 v[64:65], v[64:65], v[28:29] op_sel_hi:[1,0]
	v_pk_mul_f32 v[66:67], v[66:67], v[28:29] op_sel_hi:[1,0]
	v_cvt_pk_bf16_f32 v80, v60, v61
	v_cvt_pk_bf16_f32 v81, v62, v63
	v_cvt_pk_bf16_f32 v82, v64, v65
	v_cvt_pk_bf16_f32 v83, v66, v67
	global_store_dwordx4 v68, v[80:83], s[34:35]
	v_add_u32_e32 v68, 0x400, v68
	global_load_dwordx4 v[18:21], v84, s[12:13] offset:1024
	v_add_u32_e32 v84, 0x1800, v84
	s_waitcnt vmcnt(9)
	v_lshlrev_b32_e32 v26, 16, v2
	v_and_b32_e32 v27, 0xffff0000, v2
	v_lshlrev_b32_e32 v28, 16, v22
	v_and_b32_e32 v29, 0xffff0000, v22
	v_lshlrev_b32_e32 v30, 16, v6
	v_and_b32_e32 v31, 0xffff0000, v6
	v_pk_add_f32 v[28:29], v[28:29], v[26:27] neg_lo:[0,1] neg_hi:[0,1]
	v_pk_add_f32 v[30:31], v[30:31], v[26:27] neg_lo:[0,1] neg_hi:[0,1]
	v_pk_fma_f32 v[26:27], v[28:29], v[32:33], v[26:27]
	v_pk_fma_f32 v[60:61], v[30:31], v[40:41], v[26:27]
	v_lshlrev_b32_e32 v26, 16, v3
	v_and_b32_e32 v27, 0xffff0000, v3
	v_lshlrev_b32_e32 v28, 16, v23
	v_and_b32_e32 v29, 0xffff0000, v23
	v_lshlrev_b32_e32 v30, 16, v7
	v_and_b32_e32 v31, 0xffff0000, v7
	v_pk_add_f32 v[28:29], v[28:29], v[26:27] neg_lo:[0,1] neg_hi:[0,1]
	v_pk_add_f32 v[30:31], v[30:31], v[26:27] neg_lo:[0,1] neg_hi:[0,1]
	v_pk_fma_f32 v[26:27], v[28:29], v[34:35], v[26:27]
	v_pk_fma_f32 v[62:63], v[30:31], v[42:43], v[26:27]
	v_lshlrev_b32_e32 v26, 16, v4
	v_and_b32_e32 v27, 0xffff0000, v4
	v_lshlrev_b32_e32 v28, 16, v24
	v_and_b32_e32 v29, 0xffff0000, v24
	v_lshlrev_b32_e32 v30, 16, v8
	v_and_b32_e32 v31, 0xffff0000, v8
	v_pk_add_f32 v[28:29], v[28:29], v[26:27] neg_lo:[0,1] neg_hi:[0,1]
	v_pk_add_f32 v[30:31], v[30:31], v[26:27] neg_lo:[0,1] neg_hi:[0,1]
	v_pk_fma_f32 v[26:27], v[28:29], v[36:37], v[26:27]
	v_pk_fma_f32 v[64:65], v[30:31], v[44:45], v[26:27]
	v_lshlrev_b32_e32 v26, 16, v5
	v_and_b32_e32 v27, 0xffff0000, v5
	v_lshlrev_b32_e32 v28, 16, v25
	v_and_b32_e32 v29, 0xffff0000, v25
	v_lshlrev_b32_e32 v30, 16, v9
	v_and_b32_e32 v31, 0xffff0000, v9
	v_pk_add_f32 v[28:29], v[28:29], v[26:27] neg_lo:[0,1] neg_hi:[0,1]
	v_pk_add_f32 v[30:31], v[30:31], v[26:27] neg_lo:[0,1] neg_hi:[0,1]
	v_pk_fma_f32 v[26:27], v[28:29], v[38:39], v[26:27]
	v_pk_fma_f32 v[66:67], v[30:31], v[46:47], v[26:27]
	v_cvt_pk_bf16_f32 v80, v60, v61
	v_cvt_pk_bf16_f32 v81, v62, v63
	v_cvt_pk_bf16_f32 v82, v64, v65
	v_cvt_pk_bf16_f32 v83, v66, v67
	global_store_dwordx4 v85, v[80:83], s[14:15] offset:1024
	v_add_u32_e32 v85, 0xc00, v85
	v_pk_mul_f32 v[60:61], v[60:61], v[52:53]
	v_pk_mul_f32 v[62:63], v[62:63], v[54:55]
	v_pk_mul_f32 v[64:65], v[64:65], v[56:57]
	v_pk_mul_f32 v[66:67], v[66:67], v[58:59]
	v_pk_mul_f32 v[26:27], v[60:61], v[60:61]
	v_pk_fma_f32 v[26:27], v[62:63], v[62:63], v[26:27]
	v_pk_fma_f32 v[26:27], v[64:65], v[64:65], v[26:27]
	v_pk_fma_f32 v[26:27], v[66:67], v[66:67], v[26:27]
	v_add_f32_e32 v28, v26, v27
	s_nop 1
	v_add_f32_dpp v28, v28, v28 quad_perm:[1,0,3,2] row_mask:0xf bank_mask:0xf
	s_nop 1
	v_add_f32_dpp v28, v28, v28 quad_perm:[2,3,0,1] row_mask:0xf bank_mask:0xf
	s_nop 1
	v_add_f32_dpp v28, v28, v28 row_half_mirror row_mask:0xf bank_mask:0xf
	s_nop 0
	v_add_f32_e32 v28, 0x2b8cbccc, v28
	v_rsq_f32_e32 v28, v28
	s_nop 0
	v_pk_mul_f32 v[60:61], v[60:61], v[28:29] op_sel_hi:[1,0]
	v_pk_mul_f32 v[62:63], v[62:63], v[28:29] op_sel_hi:[1,0]
	v_pk_mul_f32 v[64:65], v[64:65], v[28:29] op_sel_hi:[1,0]
	v_pk_mul_f32 v[66:67], v[66:67], v[28:29] op_sel_hi:[1,0]
	v_cvt_pk_bf16_f32 v80, v60, v61
	v_cvt_pk_bf16_f32 v81, v62, v63
	v_cvt_pk_bf16_f32 v82, v64, v65
	v_cvt_pk_bf16_f32 v83, v66, v67
	global_store_dwordx4 v68, v[80:83], s[34:35]
	v_add_u32_e32 v68, 0x400, v68
	global_load_dwordx4 v[22:25], v84, s[12:13] offset:1024
	v_add_u32_e32 v84, 0x1800, v84
	s_branch .Lpa1_loop

.Lpa1_nolast:
	v_lshlrev_b32_e32 v26, 16, v10
	v_and_b32_e32 v27, 0xffff0000, v10
	v_lshlrev_b32_e32 v28, 16, v6
	v_and_b32_e32 v29, 0xffff0000, v6
	v_lshlrev_b32_e32 v30, 16, v14
	v_and_b32_e32 v31, 0xffff0000, v14
	v_pk_add_f32 v[28:29], v[28:29], v[26:27] neg_lo:[0,1] neg_hi:[0,1]
	v_pk_add_f32 v[30:31], v[30:31], v[26:27] neg_lo:[0,1] neg_hi:[0,1]
	v_pk_fma_f32 v[26:27], v[28:29], v[32:33], v[26:27]
	v_pk_fma_f32 v[60:61], v[30:31], v[40:41], v[26:27]
	v_lshlrev_b32_e32 v26, 16, v11
	v_and_b32_e32 v27, 0xffff0000, v11
	v_lshlrev_b32_e32 v28, 16, v7
	v_and_b32_e32 v29, 0xffff0000, v7
	v_lshlrev_b32_e32 v30, 16, v15
	v_and_b32_e32 v31, 0xffff0000, v15
	v_pk_add_f32 v[28:29], v[28:29], v[26:27] neg_lo:[0,1] neg_hi:[0,1]
	v_pk_add_f32 v[30:31], v[30:31], v[26:27] neg_lo:[0,1] neg_hi:[0,1]
	v_pk_fma_f32 v[26:27], v[28:29], v[34:35], v[26:27]
	v_pk_fma_f32 v[62:63], v[30:31], v[42:43], v[26:27]
	v_lshlrev_b32_e32 v26, 16, v12
	v_and_b32_e32 v27, 0xffff0000, v12
	v_lshlrev_b32_e32 v28, 16, v8
	v_and_b32_e32 v29, 0xffff0000, v8
	v_lshlrev_b32_e32 v30, 16, v16
	v_and_b32_e32 v31, 0xffff0000, v16
	v_pk_add_f32 v[28:29], v[28:29], v[26:27] neg_lo:[0,1] neg_hi:[0,1]
	v_pk_add_f32 v[30:31], v[30:31], v[26:27] neg_lo:[0,1] neg_hi:[0,1]
	v_pk_fma_f32 v[26:27], v[28:29], v[36:37], v[26:27]
	v_pk_fma_f32 v[64:65], v[30:31], v[44:45], v[26:27]
	v_lshlrev_b32_e32 v26, 16, v13
	v_and_b32_e32 v27, 0xffff0000, v13
	v_lshlrev_b32_e32 v28, 16, v9
	v_and_b32_e32 v29, 0xffff0000, v9
	v_lshlrev_b32_e32 v30, 16, v17
	v_and_b32_e32 v31, 0xffff0000, v17
	v_pk_add_f32 v[28:29], v[28:29], v[26:27] neg_lo:[0,1] neg_hi:[0,1]
	v_pk_add_f32 v[30:31], v[30:31], v[26:27] neg_lo:[0,1] neg_hi:[0,1]
	v_pk_fma_f32 v[26:27], v[28:29], v[38:39], v[26:27]
	v_pk_fma_f32 v[66:67], v[30:31], v[46:47], v[26:27]
	v_cvt_pk_bf16_f32 v80, v60, v61
	v_cvt_pk_bf16_f32 v81, v62, v63
	v_cvt_pk_bf16_f32 v82, v64, v65
	v_cvt_pk_bf16_f32 v83, v66, v67
	global_store_dwordx4 v85, v[80:83], s[14:15] offset:1024
	v_add_u32_e32 v85, 0xc00, v85
	v_pk_mul_f32 v[60:61], v[60:61], v[52:53]
	v_pk_mul_f32 v[62:63], v[62:63], v[54:55]
	v_pk_mul_f32 v[64:65], v[64:65], v[56:57]
	v_pk_mul_f32 v[66:67], v[66:67], v[58:59]
	v_pk_mul_f32 v[26:27], v[60:61], v[60:61]
	v_pk_fma_f32 v[26:27], v[62:63], v[62:63], v[26:27]
	v_pk_fma_f32 v[26:27], v[64:65], v[64:65], v[26:27]
	v_pk_fma_f32 v[26:27], v[66:67], v[66:67], v[26:27]
	v_add_f32_e32 v28, v26, v27
	s_nop 1
	v_add_f32_dpp v28, v28, v28 quad_perm:[1,0,3,2] row_mask:0xf bank_mask:0xf
	s_nop 1
	v_add_f32_dpp v28, v28, v28 quad_perm:[2,3,0,1] row_mask:0xf bank_mask:0xf
	s_nop 1
	v_add_f32_dpp v28, v28, v28 row_half_mirror row_mask:0xf bank_mask:0xf
	s_nop 0
	v_add_f32_e32 v28, 0x2b8cbccc, v28
	v_rsq_f32_e32 v28, v28
	s_nop 0
	v_pk_mul_f32 v[60:61], v[60:61], v[28:29] op_sel_hi:[1,0]
	v_pk_mul_f32 v[62:63], v[62:63], v[28:29] op_sel_hi:[1,0]
	v_pk_mul_f32 v[64:65], v[64:65], v[28:29] op_sel_hi:[1,0]
	v_pk_mul_f32 v[66:67], v[66:67], v[28:29] op_sel_hi:[1,0]
	v_cvt_pk_bf16_f32 v80, v60, v61
	v_cvt_pk_bf16_f32 v81, v62, v63
	v_cvt_pk_bf16_f32 v82, v64, v65
	v_cvt_pk_bf16_f32 v83, v66, v67
	global_store_dwordx4 v68, v[80:83], s[34:35]
	v_add_u32_e32 v68, 0x400, v68
	v_mov_b32_e32 v84, v48
	global_load_dwordx4 v[2:5], v84, s[12:13] offset:2048
	v_add_u32_e32 v84, 0x1800, v84
	global_load_dwordx4 v[6:9], v84, s[12:13] offset:2048
	v_add_u32_e32 v84, 0x1800, v84
	global_load_dwordx4 v[10:13], v84, s[12:13] offset:2048
	v_add_u32_e32 v84, 0x1800, v84
	global_load_dwordx4 v[14:17], v84, s[12:13] offset:2048
	v_add_u32_e32 v84, 0x1800, v84
	global_load_dwordx4 v[18:21], v84, s[12:13] offset:2048
	v_add_u32_e32 v84, 0x1800, v84
	global_load_dwordx4 v[22:25], v84, s[12:13] offset:2048
	v_add_u32_e32 v84, 0x1800, v84
	v_add_u32_e32 v26, 0x1000, v49
	global_load_dwordx4 v[32:35], v26, s[4:5]
	global_load_dwordx4 v[36:39], v26, s[4:5] offset:16
	global_load_dwordx4 v[40:43], v26, s[6:7]
	global_load_dwordx4 v[44:47], v26, s[6:7] offset:16
	v_mov_b32_e32 v85, v48
	v_mov_b32_e32 v68, v48
	s_waitcnt vmcnt(0)
	s_cmp_lg_u32 s30, 0
	s_cbranch_scc1 .Lpa2_nofirst
	v_mov_b32_e32 v2, 0
	v_mov_b32_e32 v3, 0
	v_mov_b32_e32 v4, 0
	v_mov_b32_e32 v5, 0

.Lpa2_loop:
	s_waitcnt vmcnt(6)
	v_lshlrev_b32_e32 v26, 16, v6
	v_and_b32_e32 v27, 0xffff0000, v6
	v_lshlrev_b32_e32 v28, 16, v2
	v_and_b32_e32 v29, 0xffff0000, v2
	v_lshlrev_b32_e32 v30, 16, v10
	v_and_b32_e32 v31, 0xffff0000, v10
	v_pk_add_f32 v[28:29], v[28:29], v[26:27] neg_lo:[0,1] neg_hi:[0,1]
	v_pk_add_f32 v[30:31], v[30:31], v[26:27] neg_lo:[0,1] neg_hi:[0,1]
	v_pk_fma_f32 v[26:27], v[28:29], v[32:33], v[26:27]
	v_pk_fma_f32 v[60:61], v[30:31], v[40:41], v[26:27]
	v_lshlrev_b32_e32 v26, 16, v7
	v_and_b32_e32 v27, 0xffff0000, v7
	v_lshlrev_b32_e32 v28, 16, v3
	v_and_b32_e32 v29, 0xffff0000, v3
	v_lshlrev_b32_e32 v30, 16, v11
	v_and_b32_e32 v31, 0xffff0000, v11
	v_pk_add_f32 v[28:29], v[28:29], v[26:27] neg_lo:[0,1] neg_hi:[0,1]
	v_pk_add_f32 v[30:31], v[30:31], v[26:27] neg_lo:[0,1] neg_hi:[0,1]
	v_pk_fma_f32 v[26:27], v[28:29], v[34:35], v[26:27]
	v_pk_fma_f32 v[62:63], v[30:31], v[42:43], v[26:27]
	v_lshlrev_b32_e32 v26, 16, v8
	v_and_b32_e32 v27, 0xffff0000, v8
	v_lshlrev_b32_e32 v28, 16, v4
	v_and_b32_e32 v29, 0xffff0000, v4
	v_lshlrev_b32_e32 v30, 16, v12
	v_and_b32_e32 v31, 0xffff0000, v12
	v_pk_add_f32 v[28:29], v[28:29], v[26:27] neg_lo:[0,1] neg_hi:[0,1]
	v_pk_add_f32 v[30:31], v[30:31], v[26:27] neg_lo:[0,1] neg_hi:[0,1]
	v_pk_fma_f32 v[26:27], v[28:29], v[36:37], v[26:27]
	v_pk_fma_f32 v[64:65], v[30:31], v[44:45], v[26:27]
	v_lshlrev_b32_e32 v26, 16, v9
	v_and_b32_e32 v27, 0xffff0000, v9
	v_lshlrev_b32_e32 v28, 16, v5
	v_and_b32_e32 v29, 0xffff0000, v5
	v_lshlrev_b32_e32 v30, 16, v13
	v_and_b32_e32 v31, 0xffff0000, v13
	v_pk_add_f32 v[28:29], v[28:29], v[26:27] neg_lo:[0,1] neg_hi:[0,1]
	v_pk_add_f32 v[30:31], v[30:31], v[26:27] neg_lo:[0,1] neg_hi:[0,1]
	v_pk_fma_f32 v[26:27], v[28:29], v[38:39], v[26:27]
	v_pk_fma_f32 v[66:67], v[30:31], v[46:47], v[26:27]
	v_cvt_pk_bf16_f32 v80, v60, v61
	v_cvt_pk_bf16_f32 v81, v62, v63
	v_cvt_pk_bf16_f32 v82, v64, v65
	v_cvt_pk_bf16_f32 v83, v66, v67
	global_store_dwordx4 v85, v[80:83], s[14:15] offset:2048
	v_add_u32_e32 v85, 0xc00, v85
	global_load_dwordx4 v[2:5], v84, s[12:13] offset:2048
	v_add_u32_e32 v84, 0x1800, v84
	s_add_u32 s17, s17, 6
	s_cmp_eq_u32 s17, 36
	s_cbranch_scc1 .Lpa2_last
	s_waitcnt vmcnt(6)
	v_lshlrev_b32_e32 v26, 16, v10
	v_and_b32_e32 v27, 0xffff0000, v10
	v_lshlrev_b32_e32 v28, 16, v6
	v_and_b32_e32 v29, 0xffff0000, v6
	v_lshlrev_b32_e32 v30, 16, v14
	v_and_b32_e32 v31, 0xffff0000, v14
	v_pk_add_f32 v[28:29], v[28:29], v[26:27] neg_lo:[0,1] neg_hi:[0,1]
	v_pk_add_f32 v[30:31], v[30:31], v[26:27] neg_lo:[0,1] neg_hi:[0,1]
	v_pk_fma_f32 v[26:27], v[28:29], v[32:33], v[26:27]
	v_pk_fma_f32 v[60:61], v[30:31], v[40:41], v[26:27]
	v_lshlrev_b32_e32 v26, 16, v11
	v_and_b32_e32 v27, 0xffff0000, v11
	v_lshlrev_b32_e32 v28, 16, v7
	v_and_b32_e32 v29, 0xffff0000, v7
	v_lshlrev_b32_e32 v30, 16, v15
	v_and_b32_e32 v31, 0xffff0000, v15
	v_pk_add_f32 v[28:29], v[28:29], v[26:27] neg_lo:[0,1] neg_hi:[0,1]
	v_pk_add_f32 v[30:31], v[30:31], v[26:27] neg_lo:[0,1] neg_hi:[0,1]
	v_pk_fma_f32 v[26:27], v[28:29], v[34:35], v[26:27]
	v_pk_fma_f32 v[62:63], v[30:31], v[42:43], v[26:27]
	v_lshlrev_b32_e32 v26, 16, v12
	v_and_b32_e32 v27, 0xffff0000, v12
	v_lshlrev_b32_e32 v28, 16, v8
	v_and_b32_e32 v29, 0xffff0000, v8
	v_lshlrev_b32_e32 v30, 16, v16
	v_and_b32_e32 v31, 0xffff0000, v16
	v_pk_add_f32 v[28:29], v[28:29], v[26:27] neg_lo:[0,1] neg_hi:[0,1]
	v_pk_add_f32 v[30:31], v[30:31], v[26:27] neg_lo:[0,1] neg_hi:[0,1]
	v_pk_fma_f32 v[26:27], v[28:29], v[36:37], v[26:27]
	v_pk_fma_f32 v[64:65], v[30:31], v[44:45], v[26:27]
	v_lshlrev_b32_e32 v26, 16, v13
	v_and_b32_e32 v27, 0xffff0000, v13
	v_lshlrev_b32_e32 v28, 16, v9
	v_and_b32_e32 v29, 0xffff0000, v9
	v_lshlrev_b32_e32 v30, 16, v17
	v_and_b32_e32 v31, 0xffff0000, v17
	v_pk_add_f32 v[28:29], v[28:29], v[26:27] neg_lo:[0,1] neg_hi:[0,1]
	v_pk_add_f32 v[30:31], v[30:31], v[26:27] neg_lo:[0,1] neg_hi:[0,1]
	v_pk_fma_f32 v[26:27], v[28:29], v[38:39], v[26:27]
	v_pk_fma_f32 v[66:67], v[30:31], v[46:47], v[26:27]
	v_cvt_pk_bf16_f32 v80, v60, v61
	v_cvt_pk_bf16_f32 v81, v62, v63
	v_cvt_pk_bf16_f32 v82, v64, v65
	v_cvt_pk_bf16_f32 v83, v66, v67
	global_store_dwordx4 v85, v[80:83], s[14:15] offset:2048
	v_add_u32_e32 v85, 0xc00, v85
	global_load_dwordx4 v[6:9], v84, s[12:13] offset:2048
	v_add_u32_e32 v84, 0x1800, v84
	s_waitcnt vmcnt(6)
	v_lshlrev_b32_e32 v26, 16, v14
	v_and_b32_e32 v27, 0xffff0000, v14
	v_lshlrev_b32_e32 v28, 16, v10
	v_and_b32_e32 v29, 0xffff0000, v10
	v_lshlrev_b32_e32 v30, 16, v18
	v_and_b32_e32 v31, 0xffff0000, v18
	v_pk_add_f32 v[28:29], v[28:29], v[26:27] neg_lo:[0,1] neg_hi:[0,1]
	v_pk_add_f32 v[30:31], v[30:31], v[26:27] neg_lo:[0,1] neg_hi:[0,1]
	v_pk_fma_f32 v[26:27], v[28:29], v[32:33], v[26:27]
	v_pk_fma_f32 v[60:61], v[30:31], v[40:41], v[26:27]
	v_lshlrev_b32_e32 v26, 16, v15
	v_and_b32_e32 v27, 0xffff0000, v15
	v_lshlrev_b32_e32 v28, 16, v11
	v_and_b32_e32 v29, 0xffff0000, v11
	v_lshlrev_b32_e32 v30, 16, v19
	v_and_b32_e32 v31, 0xffff0000, v19
	v_pk_add_f32 v[28:29], v[28:29], v[26:27] neg_lo:[0,1] neg_hi:[0,1]
	v_pk_add_f32 v[30:31], v[30:31], v[26:27] neg_lo:[0,1] neg_hi:[0,1]
	v_pk_fma_f32 v[26:27], v[28:29], v[34:35], v[26:27]
	v_pk_fma_f32 v[62:63], v[30:31], v[42:43], v[26:27]
	v_lshlrev_b32_e32 v26, 16, v16
	v_and_b32_e32 v27, 0xffff0000, v16
	v_lshlrev_b32_e32 v28, 16, v12
	v_and_b32_e32 v29, 0xffff0000, v12
	v_lshlrev_b32_e32 v30, 16, v20
	v_and_b32_e32 v31, 0xffff0000, v20
	v_pk_add_f32 v[28:29], v[28:29], v[26:27] neg_lo:[0,1] neg_hi:[0,1]
	v_pk_add_f32 v[30:31], v[30:31], v[26:27] neg_lo:[0,1] neg_hi:[0,1]
	v_pk_fma_f32 v[26:27], v[28:29], v[36:37], v[26:27]
	v_pk_fma_f32 v[64:65], v[30:31], v[44:45], v[26:27]
	v_lshlrev_b32_e32 v26, 16, v17
	v_and_b32_e32 v27, 0xffff0000, v17
	v_lshlrev_b32_e32 v28, 16, v13
	v_and_b32_e32 v29, 0xffff0000, v13
	v_lshlrev_b32_e32 v30, 16, v21
	v_and_b32_e32 v31, 0xffff0000, v21
	v_pk_add_f32 v[28:29], v[28:29], v[26:27] neg_lo:[0,1] neg_hi:[0,1]
	v_pk_add_f32 v[30:31], v[30:31], v[26:27] neg_lo:[0,1] neg_hi:[0,1]
	v_pk_fma_f32 v[26:27], v[28:29], v[38:39], v[26:27]
	v_pk_fma_f32 v[66:67], v[30:31], v[46:47], v[26:27]
	v_cvt_pk_bf16_f32 v80, v60, v61
	v_cvt_pk_bf16_f32 v81, v62, v63
	v_cvt_pk_bf16_f32 v82, v64, v65
	v_cvt_pk_bf16_f32 v83, v66, v67
	global_store_dwordx4 v85, v[80:83], s[14:15] offset:2048
	v_add_u32_e32 v85, 0xc00, v85
	global_load_dwordx4 v[10:13], v84, s[12:13] offset:2048
	v_add_u32_e32 v84, 0x1800, v84
	s_waitcnt vmcnt(6)
	v_lshlrev_b32_e32 v26, 16, v18
	v_and_b32_e32 v27, 0xffff0000, v18
	v_lshlrev_b32_e32 v28, 16, v14
	v_and_b32_e32 v29, 0xffff0000, v14
	v_lshlrev_b32_e32 v30, 16, v22
	v_and_b32_e32 v31, 0xffff0000, v22
	v_pk_add_f32 v[28:29], v[28:29], v[26:27] neg_lo:[0,1] neg_hi:[0,1]
	v_pk_add_f32 v[30:31], v[30:31], v[26:27] neg_lo:[0,1] neg_hi:[0,1]
	v_pk_fma_f32 v[26:27], v[28:29], v[32:33], v[26:27]
	v_pk_fma_f32 v[60:61], v[30:31], v[40:41], v[26:27]
	v_lshlrev_b32_e32 v26, 16, v19
	v_and_b32_e32 v27, 0xffff0000, v19
	v_lshlrev_b32_e32 v28, 16, v15
	v_and_b32_e32 v29, 0xffff0000, v15
	v_lshlrev_b32_e32 v30, 16, v23
	v_and_b32_e32 v31, 0xffff0000, v23
	v_pk_add_f32 v[28:29], v[28:29], v[26:27] neg_lo:[0,1] neg_hi:[0,1]
	v_pk_add_f32 v[30:31], v[30:31], v[26:27] neg_lo:[0,1] neg_hi:[0,1]
	v_pk_fma_f32 v[26:27], v[28:29], v[34:35], v[26:27]
	v_pk_fma_f32 v[62:63], v[30:31], v[42:43], v[26:27]
	v_lshlrev_b32_e32 v26, 16, v20
	v_and_b32_e32 v27, 0xffff0000, v20
	v_lshlrev_b32_e32 v28, 16, v16
	v_and_b32_e32 v29, 0xffff0000, v16
	v_lshlrev_b32_e32 v30, 16, v24
	v_and_b32_e32 v31, 0xffff0000, v24
	v_pk_add_f32 v[28:29], v[28:29], v[26:27] neg_lo:[0,1] neg_hi:[0,1]
	v_pk_add_f32 v[30:31], v[30:31], v[26:27] neg_lo:[0,1] neg_hi:[0,1]
	v_pk_fma_f32 v[26:27], v[28:29], v[36:37], v[26:27]
	v_pk_fma_f32 v[64:65], v[30:31], v[44:45], v[26:27]
	v_lshlrev_b32_e32 v26, 16, v21
	v_and_b32_e32 v27, 0xffff0000, v21
	v_lshlrev_b32_e32 v28, 16, v17
	v_and_b32_e32 v29, 0xffff0000, v17
	v_lshlrev_b32_e32 v30, 16, v25
	v_and_b32_e32 v31, 0xffff0000, v25
	v_pk_add_f32 v[28:29], v[28:29], v[26:27] neg_lo:[0,1] neg_hi:[0,1]
	v_pk_add_f32 v[30:31], v[30:31], v[26:27] neg_lo:[0,1] neg_hi:[0,1]
	v_pk_fma_f32 v[26:27], v[28:29], v[38:39], v[26:27]
	v_pk_fma_f32 v[66:67], v[30:31], v[46:47], v[26:27]
	v_cvt_pk_bf16_f32 v80, v60, v61
	v_cvt_pk_bf16_f32 v81, v62, v63
	v_cvt_pk_bf16_f32 v82, v64, v65
	v_cvt_pk_bf16_f32 v83, v66, v67
	global_store_dwordx4 v85, v[80:83], s[14:15] offset:2048
	v_add_u32_e32 v85, 0xc00, v85
	global_load_dwordx4 v[14:17], v84, s[12:13] offset:2048
	v_add_u32_e32 v84, 0x1800, v84
	s_waitcnt vmcnt(6)
	v_lshlrev_b32_e32 v26, 16, v22
	v_and_b32_e32 v27, 0xffff0000, v22
	v_lshlrev_b32_e32 v28, 16, v18
	v_and_b32_e32 v29, 0xffff0000, v18
	v_lshlrev_b32_e32 v30, 16, v2
	v_and_b32_e32 v31, 0xffff0000, v2
	v_pk_add_f32 v[28:29], v[28:29], v[26:27] neg_lo:[0,1] neg_hi:[0,1]
	v_pk_add_f32 v[30:31], v[30:31], v[26:27] neg_lo:[0,1] neg_hi:[0,1]
	v_pk_fma_f32 v[26:27], v[28:29], v[32:33], v[26:27]
	v_pk_fma_f32 v[60:61], v[30:31], v[40:41], v[26:27]
	v_lshlrev_b32_e32 v26, 16, v23
	v_and_b32_e32 v27, 0xffff0000, v23
	v_lshlrev_b32_e32 v28, 16, v19
	v_and_b32_e32 v29, 0xffff0000, v19
	v_lshlrev_b32_e32 v30, 16, v3
	v_and_b32_e32 v31, 0xffff0000, v3
	v_pk_add_f32 v[28:29], v[28:29], v[26:27] neg_lo:[0,1] neg_hi:[0,1]
	v_pk_add_f32 v[30:31], v[30:31], v[26:27] neg_lo:[0,1] neg_hi:[0,1]
	v_pk_fma_f32 v[26:27], v[28:29], v[34:35], v[26:27]
	v_pk_fma_f32 v[62:63], v[30:31], v[42:43], v[26:27]
	v_lshlrev_b32_e32 v26, 16, v24
	v_and_b32_e32 v27, 0xffff0000, v24
	v_lshlrev_b32_e32 v28, 16, v20
	v_and_b32_e32 v29, 0xffff0000, v20
	v_lshlrev_b32_e32 v30, 16, v4
	v_and_b32_e32 v31, 0xffff0000, v4
	v_pk_add_f32 v[28:29], v[28:29], v[26:27] neg_lo:[0,1] neg_hi:[0,1]
	v_pk_add_f32 v[30:31], v[30:31], v[26:27] neg_lo:[0,1] neg_hi:[0,1]
	v_pk_fma_f32 v[26:27], v[28:29], v[36:37], v[26:27]
	v_pk_fma_f32 v[64:65], v[30:31], v[44:45], v[26:27]
	v_lshlrev_b32_e32 v26, 16, v25
	v_and_b32_e32 v27, 0xffff0000, v25
	v_lshlrev_b32_e32 v28, 16, v21
	v_and_b32_e32 v29, 0xffff0000, v21
	v_lshlrev_b32_e32 v30, 16, v5
	v_and_b32_e32 v31, 0xffff0000, v5
	v_pk_add_f32 v[28:29], v[28:29], v[26:27] neg_lo:[0,1] neg_hi:[0,1]
	v_pk_add_f32 v[30:31], v[30:31], v[26:27] neg_lo:[0,1] neg_hi:[0,1]
	v_pk_fma_f32 v[26:27], v[28:29], v[38:39], v[26:27]
	v_pk_fma_f32 v[66:67], v[30:31], v[46:47], v[26:27]
	v_cvt_pk_bf16_f32 v80, v60, v61
	v_cvt_pk_bf16_f32 v81, v62, v63
	v_cvt_pk_bf16_f32 v82, v64, v65
	v_cvt_pk_bf16_f32 v83, v66, v67
	global_store_dwordx4 v85, v[80:83], s[14:15] offset:2048
	v_add_u32_e32 v85, 0xc00, v85
	global_load_dwordx4 v[18:21], v84, s[12:13] offset:2048
	v_add_u32_e32 v84, 0x1800, v84
	s_waitcnt vmcnt(6)
	v_lshlrev_b32_e32 v26, 16, v2
	v_and_b32_e32 v27, 0xffff0000, v2
	v_lshlrev_b32_e32 v28, 16, v22
	v_and_b32_e32 v29, 0xffff0000, v22
	v_lshlrev_b32_e32 v30, 16, v6
	v_and_b32_e32 v31, 0xffff0000, v6
	v_pk_add_f32 v[28:29], v[28:29], v[26:27] neg_lo:[0,1] neg_hi:[0,1]
	v_pk_add_f32 v[30:31], v[30:31], v[26:27] neg_lo:[0,1] neg_hi:[0,1]
	v_pk_fma_f32 v[26:27], v[28:29], v[32:33], v[26:27]
	v_pk_fma_f32 v[60:61], v[30:31], v[40:41], v[26:27]
	v_lshlrev_b32_e32 v26, 16, v3
	v_and_b32_e32 v27, 0xffff0000, v3
	v_lshlrev_b32_e32 v28, 16, v23
	v_and_b32_e32 v29, 0xffff0000, v23
	v_lshlrev_b32_e32 v30, 16, v7
	v_and_b32_e32 v31, 0xffff0000, v7
	v_pk_add_f32 v[28:29], v[28:29], v[26:27] neg_lo:[0,1] neg_hi:[0,1]
	v_pk_add_f32 v[30:31], v[30:31], v[26:27] neg_lo:[0,1] neg_hi:[0,1]
	v_pk_fma_f32 v[26:27], v[28:29], v[34:35], v[26:27]
	v_pk_fma_f32 v[62:63], v[30:31], v[42:43], v[26:27]
	v_lshlrev_b32_e32 v26, 16, v4
	v_and_b32_e32 v27, 0xffff0000, v4
	v_lshlrev_b32_e32 v28, 16, v24
	v_and_b32_e32 v29, 0xffff0000, v24
	v_lshlrev_b32_e32 v30, 16, v8
	v_and_b32_e32 v31, 0xffff0000, v8
	v_pk_add_f32 v[28:29], v[28:29], v[26:27] neg_lo:[0,1] neg_hi:[0,1]
	v_pk_add_f32 v[30:31], v[30:31], v[26:27] neg_lo:[0,1] neg_hi:[0,1]
	v_pk_fma_f32 v[26:27], v[28:29], v[36:37], v[26:27]
	v_pk_fma_f32 v[64:65], v[30:31], v[44:45], v[26:27]
	v_lshlrev_b32_e32 v26, 16, v5
	v_and_b32_e32 v27, 0xffff0000, v5
	v_lshlrev_b32_e32 v28, 16, v25
	v_and_b32_e32 v29, 0xffff0000, v25
	v_lshlrev_b32_e32 v30, 16, v9
	v_and_b32_e32 v31, 0xffff0000, v9
	v_pk_add_f32 v[28:29], v[28:29], v[26:27] neg_lo:[0,1] neg_hi:[0,1]
	v_pk_add_f32 v[30:31], v[30:31], v[26:27] neg_lo:[0,1] neg_hi:[0,1]
	v_pk_fma_f32 v[26:27], v[28:29], v[38:39], v[26:27]
	v_pk_fma_f32 v[66:67], v[30:31], v[46:47], v[26:27]
	v_cvt_pk_bf16_f32 v80, v60, v61
	v_cvt_pk_bf16_f32 v81, v62, v63
	v_cvt_pk_bf16_f32 v82, v64, v65
	v_cvt_pk_bf16_f32 v83, v66, v67
	global_store_dwordx4 v85, v[80:83], s[14:15] offset:2048
	v_add_u32_e32 v85, 0xc00, v85
	global_load_dwordx4 v[22:25], v84, s[12:13] offset:2048
	v_add_u32_e32 v84, 0x1800, v84
	s_branch .Lpa2_loop

.Lpa2_nolast:
	v_lshlrev_b32_e32 v26, 16, v10
	v_and_b32_e32 v27, 0xffff0000, v10
	v_lshlrev_b32_e32 v28, 16, v6
	v_and_b32_e32 v29, 0xffff0000, v6
	v_lshlrev_b32_e32 v30, 16, v14
	v_and_b32_e32 v31, 0xffff0000, v14
	v_pk_add_f32 v[28:29], v[28:29], v[26:27] neg_lo:[0,1] neg_hi:[0,1]
	v_pk_add_f32 v[30:31], v[30:31], v[26:27] neg_lo:[0,1] neg_hi:[0,1]
	v_pk_fma_f32 v[26:27], v[28:29], v[32:33], v[26:27]
	v_pk_fma_f32 v[60:61], v[30:31], v[40:41], v[26:27]
	v_lshlrev_b32_e32 v26, 16, v11
	v_and_b32_e32 v27, 0xffff0000, v11
	v_lshlrev_b32_e32 v28, 16, v7
	v_and_b32_e32 v29, 0xffff0000, v7
	v_lshlrev_b32_e32 v30, 16, v15
	v_and_b32_e32 v31, 0xffff0000, v15
	v_pk_add_f32 v[28:29], v[28:29], v[26:27] neg_lo:[0,1] neg_hi:[0,1]
	v_pk_add_f32 v[30:31], v[30:31], v[26:27] neg_lo:[0,1] neg_hi:[0,1]
	v_pk_fma_f32 v[26:27], v[28:29], v[34:35], v[26:27]
	v_pk_fma_f32 v[62:63], v[30:31], v[42:43], v[26:27]
	v_lshlrev_b32_e32 v26, 16, v12
	v_and_b32_e32 v27, 0xffff0000, v12
	v_lshlrev_b32_e32 v28, 16, v8
	v_and_b32_e32 v29, 0xffff0000, v8
	v_lshlrev_b32_e32 v30, 16, v16
	v_and_b32_e32 v31, 0xffff0000, v16
	v_pk_add_f32 v[28:29], v[28:29], v[26:27] neg_lo:[0,1] neg_hi:[0,1]
	v_pk_add_f32 v[30:31], v[30:31], v[26:27] neg_lo:[0,1] neg_hi:[0,1]
	v_pk_fma_f32 v[26:27], v[28:29], v[36:37], v[26:27]
	v_pk_fma_f32 v[64:65], v[30:31], v[44:45], v[26:27]
	v_lshlrev_b32_e32 v26, 16, v13
	v_and_b32_e32 v27, 0xffff0000, v13
	v_lshlrev_b32_e32 v28, 16, v9
	v_and_b32_e32 v29, 0xffff0000, v9
	v_lshlrev_b32_e32 v30, 16, v17
	v_and_b32_e32 v31, 0xffff0000, v17
	v_pk_add_f32 v[28:29], v[28:29], v[26:27] neg_lo:[0,1] neg_hi:[0,1]
	v_pk_add_f32 v[30:31], v[30:31], v[26:27] neg_lo:[0,1] neg_hi:[0,1]
	v_pk_fma_f32 v[26:27], v[28:29], v[38:39], v[26:27]
	v_pk_fma_f32 v[66:67], v[30:31], v[46:47], v[26:27]
	v_cvt_pk_bf16_f32 v80, v60, v61
	v_cvt_pk_bf16_f32 v81, v62, v63
	v_cvt_pk_bf16_f32 v82, v64, v65
	v_cvt_pk_bf16_f32 v83, v66, v67
	global_store_dwordx4 v85, v[80:83], s[14:15] offset:2048
	v_add_u32_e32 v85, 0xc00, v85
	s_mul_i32 s24, s8, 0x6000
	s_add_u32 s34, s20, s24
	s_addc_u32 s35, s21, 0
	s_add_u32 s34, s34, 0xe000000
	s_addc_u32 s35, s35, 0
	s_mov_b64 s[26:27], exec
	s_mov_b32 exec_lo, -1
	s_mov_b32 exec_hi, 0xffff
	v_mov_b32_e32 v84, v48
	global_load_dwordx4 v[2:5], v84, s[12:13] offset:3072
	v_add_u32_e32 v84, 0x1800, v84
	global_load_dwordx4 v[6:9], v84, s[12:13] offset:3072
	v_add_u32_e32 v84, 0x1800, v84
	global_load_dwordx4 v[10:13], v84, s[12:13] offset:3072
	v_add_u32_e32 v84, 0x1800, v84
	global_load_dwordx4 v[14:17], v84, s[12:13] offset:3072
	v_add_u32_e32 v84, 0x1800, v84
	global_load_dwordx4 v[18:21], v84, s[12:13] offset:3072
	v_add_u32_e32 v84, 0x1800, v84
	global_load_dwordx4 v[22:25], v84, s[12:13] offset:3072
	v_add_u32_e32 v84, 0x1800, v84
	v_add_u32_e32 v26, 0x1800, v49
	global_load_dwordx4 v[32:35], v26, s[4:5]
	global_load_dwordx4 v[36:39], v26, s[4:5] offset:16
	global_load_dwordx4 v[40:43], v26, s[6:7]
	global_load_dwordx4 v[44:47], v26, s[6:7] offset:16
	v_mov_b32_e32 v85, v48
	v_mov_b32_e32 v68, v48
	v_mov_b32_e32 v52, 0xbfb8aa3b
	v_mov_b32_e32 v53, 1.0
	v_mov_b32_e32 v54, 0
	v_cmp_gt_u32_e32 vcc, 0x100, v48
	v_mov_b32_e32 v55, 0xc038aa3b
	s_nop 1
	v_cndmask_b32_e32 v52, v52, v55, vcc
	v_mov_b32_e32 v55, 2.0
	v_cndmask_b32_e32 v53, v53, v55, vcc
	v_mov_b32_e32 v55, -1.0
	v_cndmask_b32_e32 v54, v54, v55, vcc
	s_waitcnt vmcnt(0)
	s_cmp_lg_u32 s30, 0
	s_cbranch_scc1 .Lpa3_nofirst
	v_mov_b32_e32 v2, 0
	v_mov_b32_e32 v3, 0
	v_mov_b32_e32 v4, 0
	v_mov_b32_e32 v5, 0

.Lpa3_loop:
	s_waitcnt vmcnt(6)
	v_lshlrev_b32_e32 v26, 16, v6
	v_and_b32_e32 v27, 0xffff0000, v6
	v_lshlrev_b32_e32 v28, 16, v2
	v_and_b32_e32 v29, 0xffff0000, v2
	v_lshlrev_b32_e32 v30, 16, v10
	v_and_b32_e32 v31, 0xffff0000, v10
	v_pk_add_f32 v[28:29], v[28:29], v[26:27] neg_lo:[0,1] neg_hi:[0,1]
	v_pk_add_f32 v[30:31], v[30:31], v[26:27] neg_lo:[0,1] neg_hi:[0,1]
	v_pk_fma_f32 v[26:27], v[28:29], v[32:33], v[26:27]
	v_pk_fma_f32 v[60:61], v[30:31], v[40:41], v[26:27]
	v_lshlrev_b32_e32 v26, 16, v7
	v_and_b32_e32 v27, 0xffff0000, v7
	v_lshlrev_b32_e32 v28, 16, v3
	v_and_b32_e32 v29, 0xffff0000, v3
	v_lshlrev_b32_e32 v30, 16, v11
	v_and_b32_e32 v31, 0xffff0000, v11
	v_pk_add_f32 v[28:29], v[28:29], v[26:27] neg_lo:[0,1] neg_hi:[0,1]
	v_pk_add_f32 v[30:31], v[30:31], v[26:27] neg_lo:[0,1] neg_hi:[0,1]
	v_pk_fma_f32 v[26:27], v[28:29], v[34:35], v[26:27]
	v_pk_fma_f32 v[62:63], v[30:31], v[42:43], v[26:27]
	v_lshlrev_b32_e32 v26, 16, v8
	v_and_b32_e32 v27, 0xffff0000, v8
	v_lshlrev_b32_e32 v28, 16, v4
	v_and_b32_e32 v29, 0xffff0000, v4
	v_lshlrev_b32_e32 v30, 16, v12
	v_and_b32_e32 v31, 0xffff0000, v12
	v_pk_add_f32 v[28:29], v[28:29], v[26:27] neg_lo:[0,1] neg_hi:[0,1]
	v_pk_add_f32 v[30:31], v[30:31], v[26:27] neg_lo:[0,1] neg_hi:[0,1]
	v_pk_fma_f32 v[26:27], v[28:29], v[36:37], v[26:27]
	v_pk_fma_f32 v[64:65], v[30:31], v[44:45], v[26:27]
	v_lshlrev_b32_e32 v26, 16, v9
	v_and_b32_e32 v27, 0xffff0000, v9
	v_lshlrev_b32_e32 v28, 16, v5
	v_and_b32_e32 v29, 0xffff0000, v5
	v_lshlrev_b32_e32 v30, 16, v13
	v_and_b32_e32 v31, 0xffff0000, v13
	v_pk_add_f32 v[28:29], v[28:29], v[26:27] neg_lo:[0,1] neg_hi:[0,1]
	v_pk_add_f32 v[30:31], v[30:31], v[26:27] neg_lo:[0,1] neg_hi:[0,1]
	v_pk_fma_f32 v[26:27], v[28:29], v[38:39], v[26:27]
	v_pk_fma_f32 v[66:67], v[30:31], v[46:47], v[26:27]
	v_mul_f32_e32 v56, v52, v60
	v_mul_f32_e32 v57, v52, v61
	v_mul_f32_e32 v58, v52, v62
	v_mul_f32_e32 v59, v52, v63
	v_exp_f32_e32 v56, v56
	v_exp_f32_e32 v57, v57
	v_exp_f32_e32 v58, v58
	v_exp_f32_e32 v59, v59
	v_add_f32_e32 v56, 1.0, v56
	v_add_f32_e32 v57, 1.0, v57
	v_add_f32_e32 v58, 1.0, v58
	v_add_f32_e32 v59, 1.0, v59
	v_rcp_f32_e32 v56, v56
	v_rcp_f32_e32 v57, v57
	v_rcp_f32_e32 v58, v58
	v_rcp_f32_e32 v59, v59
	v_fma_f32 v56, v56, v53, v54
	v_fma_f32 v57, v57, v53, v54
	v_fma_f32 v58, v58, v53, v54
	v_fma_f32 v59, v59, v53, v54
	v_cndmask_b32_e64 v60, v56, v60, s[28:29]
	v_cndmask_b32_e64 v61, v57, v61, s[28:29]
	v_cndmask_b32_e64 v62, v58, v62, s[28:29]
	v_cndmask_b32_e64 v63, v59, v63, s[28:29]
	v_mul_f32_e32 v56, v52, v64
	v_mul_f32_e32 v57, v52, v65
	v_mul_f32_e32 v58, v52, v66
	v_mul_f32_e32 v59, v52, v67
	v_exp_f32_e32 v56, v56
	v_exp_f32_e32 v57, v57
	v_exp_f32_e32 v58, v58
	v_exp_f32_e32 v59, v59
	v_add_f32_e32 v56, 1.0, v56
	v_add_f32_e32 v57, 1.0, v57
	v_add_f32_e32 v58, 1.0, v58
	v_add_f32_e32 v59, 1.0, v59
	v_rcp_f32_e32 v56, v56
	v_rcp_f32_e32 v57, v57
	v_rcp_f32_e32 v58, v58
	v_rcp_f32_e32 v59, v59
	v_fma_f32 v56, v56, v53, v54
	v_fma_f32 v57, v57, v53, v54
	v_fma_f32 v58, v58, v53, v54
	v_fma_f32 v59, v59, v53, v54
	v_cndmask_b32_e64 v64, v56, v64, s[28:29]
	v_cndmask_b32_e64 v65, v57, v65, s[28:29]
	v_cndmask_b32_e64 v66, v58, v66, s[28:29]
	v_cndmask_b32_e64 v67, v59, v67, s[28:29]
	v_cvt_pk_bf16_f32 v80, v60, v61
	v_cvt_pk_bf16_f32 v81, v62, v63
	v_cvt_pk_bf16_f32 v82, v64, v65
	v_cvt_pk_bf16_f32 v83, v66, v67
	global_store_dwordx4 v68, v[80:83], s[34:35]
	v_add_u32_e32 v68, 0x300, v68
	global_load_dwordx4 v[2:5], v84, s[12:13] offset:3072
	v_add_u32_e32 v84, 0x1800, v84
	s_add_u32 s17, s17, 6
	s_cmp_eq_u32 s17, 36
	s_cbranch_scc1 .Lpa3_last
	s_waitcnt vmcnt(6)
	v_lshlrev_b32_e32 v26, 16, v10
	v_and_b32_e32 v27, 0xffff0000, v10
	v_lshlrev_b32_e32 v28, 16, v6
	v_and_b32_e32 v29, 0xffff0000, v6
	v_lshlrev_b32_e32 v30, 16, v14
	v_and_b32_e32 v31, 0xffff0000, v14
	v_pk_add_f32 v[28:29], v[28:29], v[26:27] neg_lo:[0,1] neg_hi:[0,1]
	v_pk_add_f32 v[30:31], v[30:31], v[26:27] neg_lo:[0,1] neg_hi:[0,1]
	v_pk_fma_f32 v[26:27], v[28:29], v[32:33], v[26:27]
	v_pk_fma_f32 v[60:61], v[30:31], v[40:41], v[26:27]
	v_lshlrev_b32_e32 v26, 16, v11
	v_and_b32_e32 v27, 0xffff0000, v11
	v_lshlrev_b32_e32 v28, 16, v7
	v_and_b32_e32 v29, 0xffff0000, v7
	v_lshlrev_b32_e32 v30, 16, v15
	v_and_b32_e32 v31, 0xffff0000, v15
	v_pk_add_f32 v[28:29], v[28:29], v[26:27] neg_lo:[0,1] neg_hi:[0,1]
	v_pk_add_f32 v[30:31], v[30:31], v[26:27] neg_lo:[0,1] neg_hi:[0,1]
	v_pk_fma_f32 v[26:27], v[28:29], v[34:35], v[26:27]
	v_pk_fma_f32 v[62:63], v[30:31], v[42:43], v[26:27]
	v_lshlrev_b32_e32 v26, 16, v12
	v_and_b32_e32 v27, 0xffff0000, v12
	v_lshlrev_b32_e32 v28, 16, v8
	v_and_b32_e32 v29, 0xffff0000, v8
	v_lshlrev_b32_e32 v30, 16, v16
	v_and_b32_e32 v31, 0xffff0000, v16
	v_pk_add_f32 v[28:29], v[28:29], v[26:27] neg_lo:[0,1] neg_hi:[0,1]
	v_pk_add_f32 v[30:31], v[30:31], v[26:27] neg_lo:[0,1] neg_hi:[0,1]
	v_pk_fma_f32 v[26:27], v[28:29], v[36:37], v[26:27]
	v_pk_fma_f32 v[64:65], v[30:31], v[44:45], v[26:27]
	v_lshlrev_b32_e32 v26, 16, v13
	v_and_b32_e32 v27, 0xffff0000, v13
	v_lshlrev_b32_e32 v28, 16, v9
	v_and_b32_e32 v29, 0xffff0000, v9
	v_lshlrev_b32_e32 v30, 16, v17
	v_and_b32_e32 v31, 0xffff0000, v17
	v_pk_add_f32 v[28:29], v[28:29], v[26:27] neg_lo:[0,1] neg_hi:[0,1]
	v_pk_add_f32 v[30:31], v[30:31], v[26:27] neg_lo:[0,1] neg_hi:[0,1]
	v_pk_fma_f32 v[26:27], v[28:29], v[38:39], v[26:27]
	v_pk_fma_f32 v[66:67], v[30:31], v[46:47], v[26:27]
	v_mul_f32_e32 v56, v52, v60
	v_mul_f32_e32 v57, v52, v61
	v_mul_f32_e32 v58, v52, v62
	v_mul_f32_e32 v59, v52, v63
	v_exp_f32_e32 v56, v56
	v_exp_f32_e32 v57, v57
	v_exp_f32_e32 v58, v58
	v_exp_f32_e32 v59, v59
	v_add_f32_e32 v56, 1.0, v56
	v_add_f32_e32 v57, 1.0, v57
	v_add_f32_e32 v58, 1.0, v58
	v_add_f32_e32 v59, 1.0, v59
	v_rcp_f32_e32 v56, v56
	v_rcp_f32_e32 v57, v57
	v_rcp_f32_e32 v58, v58
	v_rcp_f32_e32 v59, v59
	v_fma_f32 v56, v56, v53, v54
	v_fma_f32 v57, v57, v53, v54
	v_fma_f32 v58, v58, v53, v54
	v_fma_f32 v59, v59, v53, v54
	v_cndmask_b32_e64 v60, v56, v60, s[28:29]
	v_cndmask_b32_e64 v61, v57, v61, s[28:29]
	v_cndmask_b32_e64 v62, v58, v62, s[28:29]
	v_cndmask_b32_e64 v63, v59, v63, s[28:29]
	v_mul_f32_e32 v56, v52, v64
	v_mul_f32_e32 v57, v52, v65
	v_mul_f32_e32 v58, v52, v66
	v_mul_f32_e32 v59, v52, v67
	v_exp_f32_e32 v56, v56
	v_exp_f32_e32 v57, v57
	v_exp_f32_e32 v58, v58
	v_exp_f32_e32 v59, v59
	v_add_f32_e32 v56, 1.0, v56
	v_add_f32_e32 v57, 1.0, v57
	v_add_f32_e32 v58, 1.0, v58
	v_add_f32_e32 v59, 1.0, v59
	v_rcp_f32_e32 v56, v56
	v_rcp_f32_e32 v57, v57
	v_rcp_f32_e32 v58, v58
	v_rcp_f32_e32 v59, v59
	v_fma_f32 v56, v56, v53, v54
	v_fma_f32 v57, v57, v53, v54
	v_fma_f32 v58, v58, v53, v54
	v_fma_f32 v59, v59, v53, v54
	v_cndmask_b32_e64 v64, v56, v64, s[28:29]
	v_cndmask_b32_e64 v65, v57, v65, s[28:29]
	v_cndmask_b32_e64 v66, v58, v66, s[28:29]
	v_cndmask_b32_e64 v67, v59, v67, s[28:29]
	v_cvt_pk_bf16_f32 v80, v60, v61
	v_cvt_pk_bf16_f32 v81, v62, v63
	v_cvt_pk_bf16_f32 v82, v64, v65
	v_cvt_pk_bf16_f32 v83, v66, v67
	global_store_dwordx4 v68, v[80:83], s[34:35]
	v_add_u32_e32 v68, 0x300, v68
	global_load_dwordx4 v[6:9], v84, s[12:13] offset:3072
	v_add_u32_e32 v84, 0x1800, v84
	s_waitcnt vmcnt(6)
	v_lshlrev_b32_e32 v26, 16, v14
	v_and_b32_e32 v27, 0xffff0000, v14
	v_lshlrev_b32_e32 v28, 16, v10
	v_and_b32_e32 v29, 0xffff0000, v10
	v_lshlrev_b32_e32 v30, 16, v18
	v_and_b32_e32 v31, 0xffff0000, v18
	v_pk_add_f32 v[28:29], v[28:29], v[26:27] neg_lo:[0,1] neg_hi:[0,1]
	v_pk_add_f32 v[30:31], v[30:31], v[26:27] neg_lo:[0,1] neg_hi:[0,1]
	v_pk_fma_f32 v[26:27], v[28:29], v[32:33], v[26:27]
	v_pk_fma_f32 v[60:61], v[30:31], v[40:41], v[26:27]
	v_lshlrev_b32_e32 v26, 16, v15
	v_and_b32_e32 v27, 0xffff0000, v15
	v_lshlrev_b32_e32 v28, 16, v11
	v_and_b32_e32 v29, 0xffff0000, v11
	v_lshlrev_b32_e32 v30, 16, v19
	v_and_b32_e32 v31, 0xffff0000, v19
	v_pk_add_f32 v[28:29], v[28:29], v[26:27] neg_lo:[0,1] neg_hi:[0,1]
	v_pk_add_f32 v[30:31], v[30:31], v[26:27] neg_lo:[0,1] neg_hi:[0,1]
	v_pk_fma_f32 v[26:27], v[28:29], v[34:35], v[26:27]
	v_pk_fma_f32 v[62:63], v[30:31], v[42:43], v[26:27]
	v_lshlrev_b32_e32 v26, 16, v16
	v_and_b32_e32 v27, 0xffff0000, v16
	v_lshlrev_b32_e32 v28, 16, v12
	v_and_b32_e32 v29, 0xffff0000, v12
	v_lshlrev_b32_e32 v30, 16, v20
	v_and_b32_e32 v31, 0xffff0000, v20
	v_pk_add_f32 v[28:29], v[28:29], v[26:27] neg_lo:[0,1] neg_hi:[0,1]
	v_pk_add_f32 v[30:31], v[30:31], v[26:27] neg_lo:[0,1] neg_hi:[0,1]
	v_pk_fma_f32 v[26:27], v[28:29], v[36:37], v[26:27]
	v_pk_fma_f32 v[64:65], v[30:31], v[44:45], v[26:27]
	v_lshlrev_b32_e32 v26, 16, v17
	v_and_b32_e32 v27, 0xffff0000, v17
	v_lshlrev_b32_e32 v28, 16, v13
	v_and_b32_e32 v29, 0xffff0000, v13
	v_lshlrev_b32_e32 v30, 16, v21
	v_and_b32_e32 v31, 0xffff0000, v21
	v_pk_add_f32 v[28:29], v[28:29], v[26:27] neg_lo:[0,1] neg_hi:[0,1]
	v_pk_add_f32 v[30:31], v[30:31], v[26:27] neg_lo:[0,1] neg_hi:[0,1]
	v_pk_fma_f32 v[26:27], v[28:29], v[38:39], v[26:27]
	v_pk_fma_f32 v[66:67], v[30:31], v[46:47], v[26:27]
	v_mul_f32_e32 v56, v52, v60
	v_mul_f32_e32 v57, v52, v61
	v_mul_f32_e32 v58, v52, v62
	v_mul_f32_e32 v59, v52, v63
	v_exp_f32_e32 v56, v56
	v_exp_f32_e32 v57, v57
	v_exp_f32_e32 v58, v58
	v_exp_f32_e32 v59, v59
	v_add_f32_e32 v56, 1.0, v56
	v_add_f32_e32 v57, 1.0, v57
	v_add_f32_e32 v58, 1.0, v58
	v_add_f32_e32 v59, 1.0, v59
	v_rcp_f32_e32 v56, v56
	v_rcp_f32_e32 v57, v57
	v_rcp_f32_e32 v58, v58
	v_rcp_f32_e32 v59, v59
	v_fma_f32 v56, v56, v53, v54
	v_fma_f32 v57, v57, v53, v54
	v_fma_f32 v58, v58, v53, v54
	v_fma_f32 v59, v59, v53, v54
	v_cndmask_b32_e64 v60, v56, v60, s[28:29]
	v_cndmask_b32_e64 v61, v57, v61, s[28:29]
	v_cndmask_b32_e64 v62, v58, v62, s[28:29]
	v_cndmask_b32_e64 v63, v59, v63, s[28:29]
	v_mul_f32_e32 v56, v52, v64
	v_mul_f32_e32 v57, v52, v65
	v_mul_f32_e32 v58, v52, v66
	v_mul_f32_e32 v59, v52, v67
	v_exp_f32_e32 v56, v56
	v_exp_f32_e32 v57, v57
	v_exp_f32_e32 v58, v58
	v_exp_f32_e32 v59, v59
	v_add_f32_e32 v56, 1.0, v56
	v_add_f32_e32 v57, 1.0, v57
	v_add_f32_e32 v58, 1.0, v58
	v_add_f32_e32 v59, 1.0, v59
	v_rcp_f32_e32 v56, v56
	v_rcp_f32_e32 v57, v57
	v_rcp_f32_e32 v58, v58
	v_rcp_f32_e32 v59, v59
	v_fma_f32 v56, v56, v53, v54
	v_fma_f32 v57, v57, v53, v54
	v_fma_f32 v58, v58, v53, v54
	v_fma_f32 v59, v59, v53, v54
	v_cndmask_b32_e64 v64, v56, v64, s[28:29]
	v_cndmask_b32_e64 v65, v57, v65, s[28:29]
	v_cndmask_b32_e64 v66, v58, v66, s[28:29]
	v_cndmask_b32_e64 v67, v59, v67, s[28:29]
	v_cvt_pk_bf16_f32 v80, v60, v61
	v_cvt_pk_bf16_f32 v81, v62, v63
	v_cvt_pk_bf16_f32 v82, v64, v65
	v_cvt_pk_bf16_f32 v83, v66, v67
	global_store_dwordx4 v68, v[80:83], s[34:35]
	v_add_u32_e32 v68, 0x300, v68
	global_load_dwordx4 v[10:13], v84, s[12:13] offset:3072
	v_add_u32_e32 v84, 0x1800, v84
	s_waitcnt vmcnt(6)
	v_lshlrev_b32_e32 v26, 16, v18
	v_and_b32_e32 v27, 0xffff0000, v18
	v_lshlrev_b32_e32 v28, 16, v14
	v_and_b32_e32 v29, 0xffff0000, v14
	v_lshlrev_b32_e32 v30, 16, v22
	v_and_b32_e32 v31, 0xffff0000, v22
	v_pk_add_f32 v[28:29], v[28:29], v[26:27] neg_lo:[0,1] neg_hi:[0,1]
	v_pk_add_f32 v[30:31], v[30:31], v[26:27] neg_lo:[0,1] neg_hi:[0,1]
	v_pk_fma_f32 v[26:27], v[28:29], v[32:33], v[26:27]
	v_pk_fma_f32 v[60:61], v[30:31], v[40:41], v[26:27]
	v_lshlrev_b32_e32 v26, 16, v19
	v_and_b32_e32 v27, 0xffff0000, v19
	v_lshlrev_b32_e32 v28, 16, v15
	v_and_b32_e32 v29, 0xffff0000, v15
	v_lshlrev_b32_e32 v30, 16, v23
	v_and_b32_e32 v31, 0xffff0000, v23
	v_pk_add_f32 v[28:29], v[28:29], v[26:27] neg_lo:[0,1] neg_hi:[0,1]
	v_pk_add_f32 v[30:31], v[30:31], v[26:27] neg_lo:[0,1] neg_hi:[0,1]
	v_pk_fma_f32 v[26:27], v[28:29], v[34:35], v[26:27]
	v_pk_fma_f32 v[62:63], v[30:31], v[42:43], v[26:27]
	v_lshlrev_b32_e32 v26, 16, v20
	v_and_b32_e32 v27, 0xffff0000, v20
	v_lshlrev_b32_e32 v28, 16, v16
	v_and_b32_e32 v29, 0xffff0000, v16
	v_lshlrev_b32_e32 v30, 16, v24
	v_and_b32_e32 v31, 0xffff0000, v24
	v_pk_add_f32 v[28:29], v[28:29], v[26:27] neg_lo:[0,1] neg_hi:[0,1]
	v_pk_add_f32 v[30:31], v[30:31], v[26:27] neg_lo:[0,1] neg_hi:[0,1]
	v_pk_fma_f32 v[26:27], v[28:29], v[36:37], v[26:27]
	v_pk_fma_f32 v[64:65], v[30:31], v[44:45], v[26:27]
	v_lshlrev_b32_e32 v26, 16, v21
	v_and_b32_e32 v27, 0xffff0000, v21
	v_lshlrev_b32_e32 v28, 16, v17
	v_and_b32_e32 v29, 0xffff0000, v17
	v_lshlrev_b32_e32 v30, 16, v25
	v_and_b32_e32 v31, 0xffff0000, v25
	v_pk_add_f32 v[28:29], v[28:29], v[26:27] neg_lo:[0,1] neg_hi:[0,1]
	v_pk_add_f32 v[30:31], v[30:31], v[26:27] neg_lo:[0,1] neg_hi:[0,1]
	v_pk_fma_f32 v[26:27], v[28:29], v[38:39], v[26:27]
	v_pk_fma_f32 v[66:67], v[30:31], v[46:47], v[26:27]
	v_mul_f32_e32 v56, v52, v60
	v_mul_f32_e32 v57, v52, v61
	v_mul_f32_e32 v58, v52, v62
	v_mul_f32_e32 v59, v52, v63
	v_exp_f32_e32 v56, v56
	v_exp_f32_e32 v57, v57
	v_exp_f32_e32 v58, v58
	v_exp_f32_e32 v59, v59
	v_add_f32_e32 v56, 1.0, v56
	v_add_f32_e32 v57, 1.0, v57
	v_add_f32_e32 v58, 1.0, v58
	v_add_f32_e32 v59, 1.0, v59
	v_rcp_f32_e32 v56, v56
	v_rcp_f32_e32 v57, v57
	v_rcp_f32_e32 v58, v58
	v_rcp_f32_e32 v59, v59
	v_fma_f32 v56, v56, v53, v54
	v_fma_f32 v57, v57, v53, v54
	v_fma_f32 v58, v58, v53, v54
	v_fma_f32 v59, v59, v53, v54
	v_cndmask_b32_e64 v60, v56, v60, s[28:29]
	v_cndmask_b32_e64 v61, v57, v61, s[28:29]
	v_cndmask_b32_e64 v62, v58, v62, s[28:29]
	v_cndmask_b32_e64 v63, v59, v63, s[28:29]
	v_mul_f32_e32 v56, v52, v64
	v_mul_f32_e32 v57, v52, v65
	v_mul_f32_e32 v58, v52, v66
	v_mul_f32_e32 v59, v52, v67
	v_exp_f32_e32 v56, v56
	v_exp_f32_e32 v57, v57
	v_exp_f32_e32 v58, v58
	v_exp_f32_e32 v59, v59
	v_add_f32_e32 v56, 1.0, v56
	v_add_f32_e32 v57, 1.0, v57
	v_add_f32_e32 v58, 1.0, v58
	v_add_f32_e32 v59, 1.0, v59
	v_rcp_f32_e32 v56, v56
	v_rcp_f32_e32 v57, v57
	v_rcp_f32_e32 v58, v58
	v_rcp_f32_e32 v59, v59
	v_fma_f32 v56, v56, v53, v54
	v_fma_f32 v57, v57, v53, v54
	v_fma_f32 v58, v58, v53, v54
	v_fma_f32 v59, v59, v53, v54
	v_cndmask_b32_e64 v64, v56, v64, s[28:29]
	v_cndmask_b32_e64 v65, v57, v65, s[28:29]
	v_cndmask_b32_e64 v66, v58, v66, s[28:29]
	v_cndmask_b32_e64 v67, v59, v67, s[28:29]
	v_cvt_pk_bf16_f32 v80, v60, v61
	v_cvt_pk_bf16_f32 v81, v62, v63
	v_cvt_pk_bf16_f32 v82, v64, v65
	v_cvt_pk_bf16_f32 v83, v66, v67
	global_store_dwordx4 v68, v[80:83], s[34:35]
	v_add_u32_e32 v68, 0x300, v68
	global_load_dwordx4 v[14:17], v84, s[12:13] offset:3072
	v_add_u32_e32 v84, 0x1800, v84
	s_waitcnt vmcnt(6)
	v_lshlrev_b32_e32 v26, 16, v22
	v_and_b32_e32 v27, 0xffff0000, v22
	v_lshlrev_b32_e32 v28, 16, v18
	v_and_b32_e32 v29, 0xffff0000, v18
	v_lshlrev_b32_e32 v30, 16, v2
	v_and_b32_e32 v31, 0xffff0000, v2
	v_pk_add_f32 v[28:29], v[28:29], v[26:27] neg_lo:[0,1] neg_hi:[0,1]
	v_pk_add_f32 v[30:31], v[30:31], v[26:27] neg_lo:[0,1] neg_hi:[0,1]
	v_pk_fma_f32 v[26:27], v[28:29], v[32:33], v[26:27]
	v_pk_fma_f32 v[60:61], v[30:31], v[40:41], v[26:27]
	v_lshlrev_b32_e32 v26, 16, v23
	v_and_b32_e32 v27, 0xffff0000, v23
	v_lshlrev_b32_e32 v28, 16, v19
	v_and_b32_e32 v29, 0xffff0000, v19
	v_lshlrev_b32_e32 v30, 16, v3
	v_and_b32_e32 v31, 0xffff0000, v3
	v_pk_add_f32 v[28:29], v[28:29], v[26:27] neg_lo:[0,1] neg_hi:[0,1]
	v_pk_add_f32 v[30:31], v[30:31], v[26:27] neg_lo:[0,1] neg_hi:[0,1]
	v_pk_fma_f32 v[26:27], v[28:29], v[34:35], v[26:27]
	v_pk_fma_f32 v[62:63], v[30:31], v[42:43], v[26:27]
	v_lshlrev_b32_e32 v26, 16, v24
	v_and_b32_e32 v27, 0xffff0000, v24
	v_lshlrev_b32_e32 v28, 16, v20
	v_and_b32_e32 v29, 0xffff0000, v20
	v_lshlrev_b32_e32 v30, 16, v4
	v_and_b32_e32 v31, 0xffff0000, v4
	v_pk_add_f32 v[28:29], v[28:29], v[26:27] neg_lo:[0,1] neg_hi:[0,1]
	v_pk_add_f32 v[30:31], v[30:31], v[26:27] neg_lo:[0,1] neg_hi:[0,1]
	v_pk_fma_f32 v[26:27], v[28:29], v[36:37], v[26:27]
	v_pk_fma_f32 v[64:65], v[30:31], v[44:45], v[26:27]
	v_lshlrev_b32_e32 v26, 16, v25
	v_and_b32_e32 v27, 0xffff0000, v25
	v_lshlrev_b32_e32 v28, 16, v21
	v_and_b32_e32 v29, 0xffff0000, v21
	v_lshlrev_b32_e32 v30, 16, v5
	v_and_b32_e32 v31, 0xffff0000, v5
	v_pk_add_f32 v[28:29], v[28:29], v[26:27] neg_lo:[0,1] neg_hi:[0,1]
	v_pk_add_f32 v[30:31], v[30:31], v[26:27] neg_lo:[0,1] neg_hi:[0,1]
	v_pk_fma_f32 v[26:27], v[28:29], v[38:39], v[26:27]
	v_pk_fma_f32 v[66:67], v[30:31], v[46:47], v[26:27]
	v_mul_f32_e32 v56, v52, v60
	v_mul_f32_e32 v57, v52, v61
	v_mul_f32_e32 v58, v52, v62
	v_mul_f32_e32 v59, v52, v63
	v_exp_f32_e32 v56, v56
	v_exp_f32_e32 v57, v57
	v_exp_f32_e32 v58, v58
	v_exp_f32_e32 v59, v59
	v_add_f32_e32 v56, 1.0, v56
	v_add_f32_e32 v57, 1.0, v57
	v_add_f32_e32 v58, 1.0, v58
	v_add_f32_e32 v59, 1.0, v59
	v_rcp_f32_e32 v56, v56
	v_rcp_f32_e32 v57, v57
	v_rcp_f32_e32 v58, v58
	v_rcp_f32_e32 v59, v59
	v_fma_f32 v56, v56, v53, v54
	v_fma_f32 v57, v57, v53, v54
	v_fma_f32 v58, v58, v53, v54
	v_fma_f32 v59, v59, v53, v54
	v_cndmask_b32_e64 v60, v56, v60, s[28:29]
	v_cndmask_b32_e64 v61, v57, v61, s[28:29]
	v_cndmask_b32_e64 v62, v58, v62, s[28:29]
	v_cndmask_b32_e64 v63, v59, v63, s[28:29]
	v_mul_f32_e32 v56, v52, v64
	v_mul_f32_e32 v57, v52, v65
	v_mul_f32_e32 v58, v52, v66
	v_mul_f32_e32 v59, v52, v67
	v_exp_f32_e32 v56, v56
	v_exp_f32_e32 v57, v57
	v_exp_f32_e32 v58, v58
	v_exp_f32_e32 v59, v59
	v_add_f32_e32 v56, 1.0, v56
	v_add_f32_e32 v57, 1.0, v57
	v_add_f32_e32 v58, 1.0, v58
	v_add_f32_e32 v59, 1.0, v59
	v_rcp_f32_e32 v56, v56
	v_rcp_f32_e32 v57, v57
	v_rcp_f32_e32 v58, v58
	v_rcp_f32_e32 v59, v59
	v_fma_f32 v56, v56, v53, v54
	v_fma_f32 v57, v57, v53, v54
	v_fma_f32 v58, v58, v53, v54
	v_fma_f32 v59, v59, v53, v54
	v_cndmask_b32_e64 v64, v56, v64, s[28:29]
	v_cndmask_b32_e64 v65, v57, v65, s[28:29]
	v_cndmask_b32_e64 v66, v58, v66, s[28:29]
	v_cndmask_b32_e64 v67, v59, v67, s[28:29]
	v_cvt_pk_bf16_f32 v80, v60, v61
	v_cvt_pk_bf16_f32 v81, v62, v63
	v_cvt_pk_bf16_f32 v82, v64, v65
	v_cvt_pk_bf16_f32 v83, v66, v67
	global_store_dwordx4 v68, v[80:83], s[34:35]
	v_add_u32_e32 v68, 0x300, v68
	global_load_dwordx4 v[18:21], v84, s[12:13] offset:3072
	v_add_u32_e32 v84, 0x1800, v84
	s_waitcnt vmcnt(6)
	v_lshlrev_b32_e32 v26, 16, v2
	v_and_b32_e32 v27, 0xffff0000, v2
	v_lshlrev_b32_e32 v28, 16, v22
	v_and_b32_e32 v29, 0xffff0000, v22
	v_lshlrev_b32_e32 v30, 16, v6
	v_and_b32_e32 v31, 0xffff0000, v6
	v_pk_add_f32 v[28:29], v[28:29], v[26:27] neg_lo:[0,1] neg_hi:[0,1]
	v_pk_add_f32 v[30:31], v[30:31], v[26:27] neg_lo:[0,1] neg_hi:[0,1]
	v_pk_fma_f32 v[26:27], v[28:29], v[32:33], v[26:27]
	v_pk_fma_f32 v[60:61], v[30:31], v[40:41], v[26:27]
	v_lshlrev_b32_e32 v26, 16, v3
	v_and_b32_e32 v27, 0xffff0000, v3
	v_lshlrev_b32_e32 v28, 16, v23
	v_and_b32_e32 v29, 0xffff0000, v23
	v_lshlrev_b32_e32 v30, 16, v7
	v_and_b32_e32 v31, 0xffff0000, v7
	v_pk_add_f32 v[28:29], v[28:29], v[26:27] neg_lo:[0,1] neg_hi:[0,1]
	v_pk_add_f32 v[30:31], v[30:31], v[26:27] neg_lo:[0,1] neg_hi:[0,1]
	v_pk_fma_f32 v[26:27], v[28:29], v[34:35], v[26:27]
	v_pk_fma_f32 v[62:63], v[30:31], v[42:43], v[26:27]
	v_lshlrev_b32_e32 v26, 16, v4
	v_and_b32_e32 v27, 0xffff0000, v4
	v_lshlrev_b32_e32 v28, 16, v24
	v_and_b32_e32 v29, 0xffff0000, v24
	v_lshlrev_b32_e32 v30, 16, v8
	v_and_b32_e32 v31, 0xffff0000, v8
	v_pk_add_f32 v[28:29], v[28:29], v[26:27] neg_lo:[0,1] neg_hi:[0,1]
	v_pk_add_f32 v[30:31], v[30:31], v[26:27] neg_lo:[0,1] neg_hi:[0,1]
	v_pk_fma_f32 v[26:27], v[28:29], v[36:37], v[26:27]
	v_pk_fma_f32 v[64:65], v[30:31], v[44:45], v[26:27]
	v_lshlrev_b32_e32 v26, 16, v5
	v_and_b32_e32 v27, 0xffff0000, v5
	v_lshlrev_b32_e32 v28, 16, v25
	v_and_b32_e32 v29, 0xffff0000, v25
	v_lshlrev_b32_e32 v30, 16, v9
	v_and_b32_e32 v31, 0xffff0000, v9
	v_pk_add_f32 v[28:29], v[28:29], v[26:27] neg_lo:[0,1] neg_hi:[0,1]
	v_pk_add_f32 v[30:31], v[30:31], v[26:27] neg_lo:[0,1] neg_hi:[0,1]
	v_pk_fma_f32 v[26:27], v[28:29], v[38:39], v[26:27]
	v_pk_fma_f32 v[66:67], v[30:31], v[46:47], v[26:27]
	v_mul_f32_e32 v56, v52, v60
	v_mul_f32_e32 v57, v52, v61
	v_mul_f32_e32 v58, v52, v62
	v_mul_f32_e32 v59, v52, v63
	v_exp_f32_e32 v56, v56
	v_exp_f32_e32 v57, v57
	v_exp_f32_e32 v58, v58
	v_exp_f32_e32 v59, v59
	v_add_f32_e32 v56, 1.0, v56
	v_add_f32_e32 v57, 1.0, v57
	v_add_f32_e32 v58, 1.0, v58
	v_add_f32_e32 v59, 1.0, v59
	v_rcp_f32_e32 v56, v56
	v_rcp_f32_e32 v57, v57
	v_rcp_f32_e32 v58, v58
	v_rcp_f32_e32 v59, v59
	v_fma_f32 v56, v56, v53, v54
	v_fma_f32 v57, v57, v53, v54
	v_fma_f32 v58, v58, v53, v54
	v_fma_f32 v59, v59, v53, v54
	v_cndmask_b32_e64 v60, v56, v60, s[28:29]
	v_cndmask_b32_e64 v61, v57, v61, s[28:29]
	v_cndmask_b32_e64 v62, v58, v62, s[28:29]
	v_cndmask_b32_e64 v63, v59, v63, s[28:29]
	v_mul_f32_e32 v56, v52, v64
	v_mul_f32_e32 v57, v52, v65
	v_mul_f32_e32 v58, v52, v66
	v_mul_f32_e32 v59, v52, v67
	v_exp_f32_e32 v56, v56
	v_exp_f32_e32 v57, v57
	v_exp_f32_e32 v58, v58
	v_exp_f32_e32 v59, v59
	v_add_f32_e32 v56, 1.0, v56
	v_add_f32_e32 v57, 1.0, v57
	v_add_f32_e32 v58, 1.0, v58
	v_add_f32_e32 v59, 1.0, v59
	v_rcp_f32_e32 v56, v56
	v_rcp_f32_e32 v57, v57
	v_rcp_f32_e32 v58, v58
	v_rcp_f32_e32 v59, v59
	v_fma_f32 v56, v56, v53, v54
	v_fma_f32 v57, v57, v53, v54
	v_fma_f32 v58, v58, v53, v54
	v_fma_f32 v59, v59, v53, v54
	v_cndmask_b32_e64 v64, v56, v64, s[28:29]
	v_cndmask_b32_e64 v65, v57, v65, s[28:29]
	v_cndmask_b32_e64 v66, v58, v66, s[28:29]
	v_cndmask_b32_e64 v67, v59, v67, s[28:29]
	v_cvt_pk_bf16_f32 v80, v60, v61
	v_cvt_pk_bf16_f32 v81, v62, v63
	v_cvt_pk_bf16_f32 v82, v64, v65
	v_cvt_pk_bf16_f32 v83, v66, v67
	global_store_dwordx4 v68, v[80:83], s[34:35]
	v_add_u32_e32 v68, 0x300, v68
	global_load_dwordx4 v[22:25], v84, s[12:13] offset:3072
	v_add_u32_e32 v84, 0x1800, v84
	s_branch .Lpa3_loop

.Lpa3_nolast:
	v_lshlrev_b32_e32 v26, 16, v10
	v_and_b32_e32 v27, 0xffff0000, v10
	v_lshlrev_b32_e32 v28, 16, v6
	v_and_b32_e32 v29, 0xffff0000, v6
	v_lshlrev_b32_e32 v30, 16, v14
	v_and_b32_e32 v31, 0xffff0000, v14
	v_pk_add_f32 v[28:29], v[28:29], v[26:27] neg_lo:[0,1] neg_hi:[0,1]
	v_pk_add_f32 v[30:31], v[30:31], v[26:27] neg_lo:[0,1] neg_hi:[0,1]
	v_pk_fma_f32 v[26:27], v[28:29], v[32:33], v[26:27]
	v_pk_fma_f32 v[60:61], v[30:31], v[40:41], v[26:27]
	v_lshlrev_b32_e32 v26, 16, v11
	v_and_b32_e32 v27, 0xffff0000, v11
	v_lshlrev_b32_e32 v28, 16, v7
	v_and_b32_e32 v29, 0xffff0000, v7
	v_lshlrev_b32_e32 v30, 16, v15
	v_and_b32_e32 v31, 0xffff0000, v15
	v_pk_add_f32 v[28:29], v[28:29], v[26:27] neg_lo:[0,1] neg_hi:[0,1]
	v_pk_add_f32 v[30:31], v[30:31], v[26:27] neg_lo:[0,1] neg_hi:[0,1]
	v_pk_fma_f32 v[26:27], v[28:29], v[34:35], v[26:27]
	v_pk_fma_f32 v[62:63], v[30:31], v[42:43], v[26:27]
	v_lshlrev_b32_e32 v26, 16, v12
	v_and_b32_e32 v27, 0xffff0000, v12
	v_lshlrev_b32_e32 v28, 16, v8
	v_and_b32_e32 v29, 0xffff0000, v8
	v_lshlrev_b32_e32 v30, 16, v16
	v_and_b32_e32 v31, 0xffff0000, v16
	v_pk_add_f32 v[28:29], v[28:29], v[26:27] neg_lo:[0,1] neg_hi:[0,1]
	v_pk_add_f32 v[30:31], v[30:31], v[26:27] neg_lo:[0,1] neg_hi:[0,1]
	v_pk_fma_f32 v[26:27], v[28:29], v[36:37], v[26:27]
	v_pk_fma_f32 v[64:65], v[30:31], v[44:45], v[26:27]
	v_lshlrev_b32_e32 v26, 16, v13
	v_and_b32_e32 v27, 0xffff0000, v13
	v_lshlrev_b32_e32 v28, 16, v9
	v_and_b32_e32 v29, 0xffff0000, v9
	v_lshlrev_b32_e32 v30, 16, v17
	v_and_b32_e32 v31, 0xffff0000, v17
	v_pk_add_f32 v[28:29], v[28:29], v[26:27] neg_lo:[0,1] neg_hi:[0,1]
	v_pk_add_f32 v[30:31], v[30:31], v[26:27] neg_lo:[0,1] neg_hi:[0,1]
	v_pk_fma_f32 v[26:27], v[28:29], v[38:39], v[26:27]
	v_pk_fma_f32 v[66:67], v[30:31], v[46:47], v[26:27]
	v_mul_f32_e32 v56, v52, v60
	v_mul_f32_e32 v57, v52, v61
	v_mul_f32_e32 v58, v52, v62
	v_mul_f32_e32 v59, v52, v63
	v_exp_f32_e32 v56, v56
	v_exp_f32_e32 v57, v57
	v_exp_f32_e32 v58, v58
	v_exp_f32_e32 v59, v59
	v_add_f32_e32 v56, 1.0, v56
	v_add_f32_e32 v57, 1.0, v57
	v_add_f32_e32 v58, 1.0, v58
	v_add_f32_e32 v59, 1.0, v59
	v_rcp_f32_e32 v56, v56
	v_rcp_f32_e32 v57, v57
	v_rcp_f32_e32 v58, v58
	v_rcp_f32_e32 v59, v59
	v_fma_f32 v56, v56, v53, v54
	v_fma_f32 v57, v57, v53, v54
	v_fma_f32 v58, v58, v53, v54
	v_fma_f32 v59, v59, v53, v54
	v_cndmask_b32_e64 v60, v56, v60, s[28:29]
	v_cndmask_b32_e64 v61, v57, v61, s[28:29]
	v_cndmask_b32_e64 v62, v58, v62, s[28:29]
	v_cndmask_b32_e64 v63, v59, v63, s[28:29]
	v_mul_f32_e32 v56, v52, v64
	v_mul_f32_e32 v57, v52, v65
	v_mul_f32_e32 v58, v52, v66
	v_mul_f32_e32 v59, v52, v67
	v_exp_f32_e32 v56, v56
	v_exp_f32_e32 v57, v57
	v_exp_f32_e32 v58, v58
	v_exp_f32_e32 v59, v59
	v_add_f32_e32 v56, 1.0, v56
	v_add_f32_e32 v57, 1.0, v57
	v_add_f32_e32 v58, 1.0, v58
	v_add_f32_e32 v59, 1.0, v59
	v_rcp_f32_e32 v56, v56
	v_rcp_f32_e32 v57, v57
	v_rcp_f32_e32 v58, v58
	v_rcp_f32_e32 v59, v59
	v_fma_f32 v56, v56, v53, v54
	v_fma_f32 v57, v57, v53, v54
	v_fma_f32 v58, v58, v53, v54
	v_fma_f32 v59, v59, v53, v54
	v_cndmask_b32_e64 v64, v56, v64, s[28:29]
	v_cndmask_b32_e64 v65, v57, v65, s[28:29]
	v_cndmask_b32_e64 v66, v58, v66, s[28:29]
	v_cndmask_b32_e64 v67, v59, v67, s[28:29]
	v_cvt_pk_bf16_f32 v80, v60, v61
	v_cvt_pk_bf16_f32 v81, v62, v63
	v_cvt_pk_bf16_f32 v82, v64, v65
	v_cvt_pk_bf16_f32 v83, v66, v67
	global_store_dwordx4 v68, v[80:83], s[34:35]
	v_add_u32_e32 v68, 0x300, v68
	s_mov_b64 exec, s[26:27]
	s_add_u32 s8, s8, s16
	s_branch .Lpa_blk_loop
.Lpa_done:
.LBB0_292:
	s_or_b64 exec, exec, s[22:23]
	s_waitcnt vmcnt(0)
	s_waitcnt lgkmcnt(0)
	s_barrier
	v_mbcnt_lo_u32_b32 v0, -1, 0
	v_mbcnt_hi_u32_b32 v0, -1, v0
	s_nop 0
	v_or_b32_e32 v0, s33, v0
	v_cmp_eq_u32_e32 vcc, 0, v0
	s_and_saveexec_b64 s[4:5], vcc
	s_cbranch_execz .LBB0_307
	s_lshl_b32 s6, s43, 2
	s_mov_b64 s[8:9], exec
	s_add_u32 s6, s20, s6
	s_addc_u32 s7, s21, 0
	v_mbcnt_lo_u32_b32 v0, s8, 0
	s_add_u32 s6, s6, 0x9800000
	v_mbcnt_hi_u32_b32 v0, s9, v0
	s_addc_u32 s7, s7, 0
	v_cmp_eq_u32_e32 vcc, 0, v0
	s_and_saveexec_b64 s[10:11], vcc
	s_cbranch_execz .LBB0_295
	s_bcnt1_i32_b64 s8, s[8:9]
	v_mov_b32_e32 v1, 0
	v_mov_b32_e32 v2, s8
	global_atomic_add v1, v1, v2, s[6:7] sc0

.LBB0_479:
	s_or_b64 exec, exec, s[12:13]
	s_bitcmp1_b32 s31, 0
	v_and_b32_e32 v32, 64, v104
	s_cselect_b32 s12, 0x5180, 0
	v_add_u32_e32 v43, 64, v32
	v_xor_b32_e32 v32, 32, v104
	v_add_u32_e32 v37, s12, v72
	v_cmp_lt_i32_e64 s[12:13], v32, v43
	s_waitcnt vmcnt(47)
	v_lshlrev_b32_e32 v33, 16, v106
	s_waitcnt vmcnt(43)
	v_lshlrev_b32_e32 v34, 16, v112
	v_cndmask_b32_e64 v32, v104, v32, s[12:13]
	v_lshlrev_b32_e32 v38, 2, v32
	s_waitcnt vmcnt(40)
	v_lshlrev_b32_e32 v32, 16, v113
	v_sub_f32_e32 v32, 1.0, v32
	v_mul_f32_e32 v45, v32, v44
	v_rcp_f32_e32 v32, v45
	v_mul_f32_e32 v50, v45, v33
	v_add_f32_e32 v33, -1.0, v34
	v_lshlrev_b32_e32 v46, 16, v111
	v_lshlrev_b32_e32 v35, 16, v108
	s_waitcnt vmcnt(0)
	v_fma_f32 v47, v105, v33, 1.0
	v_pk_mul_f32 v[34:35], v[46:47], v[34:35]
	v_xor_b32_e32 v39, 16, v104
	v_pk_mul_f32 v[158:159], v[34:35], v[32:33] op_sel_hi:[1,0]
	v_cmp_lt_i32_e64 s[12:13], v39, v43
	v_pk_mul_f32 v[32:33], v[50:51], v[158:159] op_sel_hi:[0,1]
	ds_bpermute_b32 v32, v38, v32
	ds_bpermute_b32 v33, v38, v33
	v_cndmask_b32_e64 v34, v104, v39, s[12:13]
	v_lshlrev_b32_e32 v39, 2, v34
	v_xor_b32_e32 v40, 8, v104
	v_cmp_lt_i32_e64 s[12:13], v40, v43
	s_waitcnt lgkmcnt(0)
	v_pk_fma_f32 v[32:33], v[50:51], v[158:159], v[32:33] op_sel_hi:[0,1,1]
	ds_bpermute_b32 v34, v39, v32
	ds_bpermute_b32 v35, v39, v33
	v_cndmask_b32_e64 v40, v104, v40, s[12:13]
	v_lshlrev_b32_e32 v40, 2, v40
	v_xor_b32_e32 v41, 4, v104
	v_cmp_lt_i32_e64 s[12:13], v41, v43
	s_waitcnt lgkmcnt(0)
	v_pk_add_f32 v[32:33], v[32:33], v[34:35]
	s_nop 1
	v_mov_b32_dpp v34, v32 row_ror:8 row_mask:0xf bank_mask:0xf
	v_mov_b32_dpp v35, v33 row_ror:8 row_mask:0xf bank_mask:0xf
	v_cndmask_b32_e64 v41, v104, v41, s[12:13]
	v_lshlrev_b32_e32 v41, 2, v41
	v_xor_b32_e32 v42, 2, v104
	v_cmp_lt_i32_e64 s[12:13], v42, v43
	s_waitcnt lgkmcnt(0)
	v_pk_add_f32 v[32:33], v[32:33], v[34:35]
	s_nop 1
	v_mov_b32_dpp v34, v32 row_ror:4 row_mask:0xf bank_mask:0xf
	v_mov_b32_dpp v35, v33 row_ror:4 row_mask:0xf bank_mask:0xf
	v_cndmask_b32_e64 v42, v104, v42, s[12:13]
	v_lshlrev_b32_e32 v42, 2, v42
	v_xor_b32_e32 v47, 1, v104
	v_cmp_lt_i32_e64 s[12:13], v47, v43
	s_waitcnt lgkmcnt(0)
	v_pk_add_f32 v[32:33], v[32:33], v[34:35]
	s_nop 1
	v_mov_b32_dpp v34, v32 quad_perm:[2,3,0,1] row_mask:0xf bank_mask:0xf
	v_mov_b32_dpp v35, v33 quad_perm:[2,3,0,1] row_mask:0xf bank_mask:0xf
	v_cndmask_b32_e64 v43, v104, v47, s[12:13]
	v_lshlrev_b32_e32 v43, 2, v43
	v_lshl_add_u32 v36, v48, 2, v37
	v_lshlrev_b32_e32 v47, 16, v110
	s_waitcnt lgkmcnt(0)
	v_pk_add_f32 v[32:33], v[32:33], v[34:35]
	s_nop 1
	v_mov_b32_dpp v34, v32 quad_perm:[1,0,3,2] row_mask:0xf bank_mask:0xf
	v_mov_b32_dpp v35, v33 quad_perm:[1,0,3,2] row_mask:0xf bank_mask:0xf
	v_add_u32_e32 v59, v36, v92
	v_mul_f32_e64 v44, v44, -v46
	ds_write_b32 v59, v47 offset:1024
	ds_write2st64_b32 v59, v44, v158 offset1:1
	ds_write2st64_b32 v59, v159, v50 offset0:2 offset1:3
	s_and_saveexec_b64 s[12:13], s[4:5]
	s_cbranch_execz .LBB0_481
	s_waitcnt lgkmcnt(3)
	v_pk_add_f32 v[32:33], v[32:33], v[34:35]
	v_add_u32_e32 v34, v37, v93
	ds_write_b64 v34, v[32:33] offset:20736
.LBB0_481:
	s_or_b64 exec, exec, s[12:13]
	v_lshlrev_b32_e32 v32, 16, v121
	v_sub_f32_e32 v32, 1.0, v32
	v_mul_f32_e32 v46, v32, v45
	v_lshlrev_b32_e32 v33, 16, v107
	v_rcp_f32_e32 v32, v46
	s_waitcnt lgkmcnt(4)
	v_lshlrev_b32_e32 v34, 16, v120
	v_mul_f32_e32 v50, v46, v33
	v_add_f32_e32 v33, -1.0, v34
	v_lshlrev_b32_e32 v158, 16, v118
	s_waitcnt lgkmcnt(3)
	v_lshlrev_b32_e32 v35, 16, v109
	v_fma_f32 v159, v105, v33, 1.0
	v_pk_mul_f32 v[34:35], v[158:159], v[34:35]
	v_lshlrev_b32_e32 v47, 16, v116
	v_pk_mul_f32 v[162:163], v[34:35], v[32:33] op_sel_hi:[1,0]
	v_add_u32_e32 v44, v36, v94
	v_pk_mul_f32 v[32:33], v[50:51], v[162:163] op_sel_hi:[0,1]
	ds_bpermute_b32 v32, v38, v32
	ds_bpermute_b32 v33, v38, v33
	v_mul_f32_e64 v45, v45, -v158
	ds_write_b32 v44, v47 offset:1024
	ds_write2st64_b32 v44, v45, v162 offset1:1
	ds_write2st64_b32 v44, v163, v50 offset0:2 offset1:3
	s_waitcnt lgkmcnt(3)
	v_pk_fma_f32 v[32:33], v[50:51], v[162:163], v[32:33] op_sel_hi:[0,1,1]
	ds_bpermute_b32 v34, v39, v32
	ds_bpermute_b32 v35, v39, v33
	s_waitcnt lgkmcnt(0)
	v_pk_add_f32 v[32:33], v[32:33], v[34:35]
	s_nop 1
	v_mov_b32_dpp v34, v32 row_ror:8 row_mask:0xf bank_mask:0xf
	v_mov_b32_dpp v35, v33 row_ror:8 row_mask:0xf bank_mask:0xf
	s_waitcnt lgkmcnt(0)
	v_pk_add_f32 v[32:33], v[32:33], v[34:35]
	s_nop 1
	v_mov_b32_dpp v34, v32 row_ror:4 row_mask:0xf bank_mask:0xf
	v_mov_b32_dpp v35, v33 row_ror:4 row_mask:0xf bank_mask:0xf
	s_waitcnt lgkmcnt(0)
	v_pk_add_f32 v[32:33], v[32:33], v[34:35]
	s_nop 1
	v_mov_b32_dpp v34, v32 quad_perm:[2,3,0,1] row_mask:0xf bank_mask:0xf
	v_mov_b32_dpp v35, v33 quad_perm:[2,3,0,1] row_mask:0xf bank_mask:0xf
	s_waitcnt lgkmcnt(0)
	v_pk_add_f32 v[32:33], v[32:33], v[34:35]
	s_nop 1
	v_mov_b32_dpp v34, v32 quad_perm:[1,0,3,2] row_mask:0xf bank_mask:0xf
	v_mov_b32_dpp v35, v33 quad_perm:[1,0,3,2] row_mask:0xf bank_mask:0xf
	s_and_saveexec_b64 s[12:13], s[4:5]
	s_cbranch_execz .LBB0_483
	s_waitcnt lgkmcnt(0)
	v_pk_add_f32 v[32:33], v[32:33], v[34:35]
	v_add_u32_e32 v34, v37, v95
	ds_write_b64 v34, v[32:33] offset:20736
.LBB0_483:
	s_or_b64 exec, exec, s[12:13]
	v_lshlrev_b32_e32 v32, 16, v129
	v_sub_f32_e32 v32, 1.0, v32
	v_mul_f32_e32 v45, v32, v46
	v_lshlrev_b32_e32 v33, 16, v114
	v_rcp_f32_e32 v32, v45
	s_waitcnt lgkmcnt(1)
	v_lshlrev_b32_e32 v34, 16, v126
	v_mul_f32_e32 v50, v45, v33
	v_add_f32_e32 v33, -1.0, v34
	v_lshlrev_b32_e32 v158, 16, v119
	s_waitcnt lgkmcnt(0)
	v_lshlrev_b32_e32 v35, 16, v115
	v_fma_f32 v159, v105, v33, 1.0
	v_pk_mul_f32 v[34:35], v[158:159], v[34:35]
	v_lshlrev_b32_e32 v47, 16, v117
	v_pk_mul_f32 v[162:163], v[34:35], v[32:33] op_sel_hi:[1,0]
	v_mul_f32_e64 v46, v46, -v158
	v_pk_mul_f32 v[32:33], v[50:51], v[162:163] op_sel_hi:[0,1]
	ds_bpermute_b32 v32, v38, v32
	ds_bpermute_b32 v33, v38, v33
	ds_write_b32 v44, v47 offset:2304
	ds_write2st64_b32 v44, v46, v162 offset0:5 offset1:6
	ds_write2st64_b32 v44, v163, v50 offset0:7 offset1:8
	s_waitcnt lgkmcnt(3)
	v_pk_fma_f32 v[32:33], v[50:51], v[162:163], v[32:33] op_sel_hi:[0,1,1]
	ds_bpermute_b32 v34, v39, v32
	ds_bpermute_b32 v35, v39, v33
	s_waitcnt lgkmcnt(0)
	v_pk_add_f32 v[32:33], v[32:33], v[34:35]
	s_nop 1
	v_mov_b32_dpp v34, v32 row_ror:8 row_mask:0xf bank_mask:0xf
	v_mov_b32_dpp v35, v33 row_ror:8 row_mask:0xf bank_mask:0xf
	s_waitcnt lgkmcnt(0)
	v_pk_add_f32 v[32:33], v[32:33], v[34:35]
	s_nop 1
	v_mov_b32_dpp v34, v32 row_ror:4 row_mask:0xf bank_mask:0xf
	v_mov_b32_dpp v35, v33 row_ror:4 row_mask:0xf bank_mask:0xf
	s_waitcnt lgkmcnt(0)
	v_pk_add_f32 v[32:33], v[32:33], v[34:35]
	s_nop 1
	v_mov_b32_dpp v34, v32 quad_perm:[2,3,0,1] row_mask:0xf bank_mask:0xf
	v_mov_b32_dpp v35, v33 quad_perm:[2,3,0,1] row_mask:0xf bank_mask:0xf
	s_waitcnt lgkmcnt(0)
	v_pk_add_f32 v[32:33], v[32:33], v[34:35]
	s_nop 1
	v_mov_b32_dpp v34, v32 quad_perm:[1,0,3,2] row_mask:0xf bank_mask:0xf
	v_mov_b32_dpp v35, v33 quad_perm:[1,0,3,2] row_mask:0xf bank_mask:0xf
	s_and_saveexec_b64 s[12:13], s[4:5]
	s_cbranch_execz .LBB0_485
	s_waitcnt lgkmcnt(0)
	v_pk_add_f32 v[32:33], v[32:33], v[34:35]
	v_add_u32_e32 v34, v37, v96
	ds_write_b64 v34, v[32:33] offset:20736
.LBB0_485:
	s_or_b64 exec, exec, s[12:13]
	v_lshlrev_b32_e32 v32, 16, v128
	v_sub_f32_e32 v32, 1.0, v32
	v_mul_f32_e32 v46, v32, v45
	v_lshlrev_b32_e32 v33, 16, v122
	v_rcp_f32_e32 v32, v46
	s_waitcnt lgkmcnt(1)
	v_lshlrev_b32_e32 v34, 16, v127
	v_mul_f32_e32 v50, v46, v33
	v_add_f32_e32 v33, -1.0, v34
	v_lshlrev_b32_e32 v158, 16, v125
	s_waitcnt lgkmcnt(0)
	v_lshlrev_b32_e32 v35, 16, v123
	v_fma_f32 v159, v105, v33, 1.0
	v_pk_mul_f32 v[34:35], v[158:159], v[34:35]
	v_lshlrev_b32_e32 v47, 16, v124
	v_pk_mul_f32 v[162:163], v[34:35], v[32:33] op_sel_hi:[1,0]
	v_mul_f32_e64 v45, v45, -v158
	v_pk_mul_f32 v[32:33], v[50:51], v[162:163] op_sel_hi:[0,1]
	ds_bpermute_b32 v32, v38, v32
	ds_bpermute_b32 v33, v38, v33
	ds_write_b32 v44, v47 offset:3584
	ds_write2st64_b32 v44, v45, v162 offset0:10 offset1:11
	ds_write2st64_b32 v44, v163, v50 offset0:12 offset1:13
	s_waitcnt lgkmcnt(3)
	v_pk_fma_f32 v[32:33], v[50:51], v[162:163], v[32:33] op_sel_hi:[0,1,1]
	ds_bpermute_b32 v34, v39, v32
	ds_bpermute_b32 v35, v39, v33
	s_waitcnt lgkmcnt(0)
	v_pk_add_f32 v[32:33], v[32:33], v[34:35]
	s_nop 1
	v_mov_b32_dpp v34, v32 row_ror:8 row_mask:0xf bank_mask:0xf
	v_mov_b32_dpp v35, v33 row_ror:8 row_mask:0xf bank_mask:0xf
	s_waitcnt lgkmcnt(0)
	v_pk_add_f32 v[32:33], v[32:33], v[34:35]
	s_nop 1
	v_mov_b32_dpp v34, v32 row_ror:4 row_mask:0xf bank_mask:0xf
	v_mov_b32_dpp v35, v33 row_ror:4 row_mask:0xf bank_mask:0xf
	s_waitcnt lgkmcnt(0)
	v_pk_add_f32 v[32:33], v[32:33], v[34:35]
	s_nop 1
	v_mov_b32_dpp v34, v32 quad_perm:[2,3,0,1] row_mask:0xf bank_mask:0xf
	v_mov_b32_dpp v35, v33 quad_perm:[2,3,0,1] row_mask:0xf bank_mask:0xf
	s_waitcnt lgkmcnt(0)
	v_pk_add_f32 v[32:33], v[32:33], v[34:35]
	s_nop 1
	v_mov_b32_dpp v34, v32 quad_perm:[1,0,3,2] row_mask:0xf bank_mask:0xf
	v_mov_b32_dpp v35, v33 quad_perm:[1,0,3,2] row_mask:0xf bank_mask:0xf
	s_and_saveexec_b64 s[12:13], s[4:5]
	s_cbranch_execz .LBB0_487
	s_waitcnt lgkmcnt(0)
	v_pk_add_f32 v[32:33], v[32:33], v[34:35]
	v_add_u32_e32 v34, v37, v97
	ds_write_b64 v34, v[32:33] offset:20736
.LBB0_487:
	s_or_b64 exec, exec, s[12:13]
	v_lshlrev_b32_e32 v32, 16, v137
	v_sub_f32_e32 v32, 1.0, v32
	v_mul_f32_e32 v45, v32, v46
	v_lshlrev_b32_e32 v33, 16, v130
	v_rcp_f32_e32 v32, v45
	s_waitcnt lgkmcnt(1)
	v_lshlrev_b32_e32 v34, 16, v136
	v_mul_f32_e32 v50, v45, v33
	v_add_f32_e32 v33, -1.0, v34
	v_lshlrev_b32_e32 v158, 16, v135
	s_waitcnt lgkmcnt(0)
	v_lshlrev_b32_e32 v35, 16, v132
	v_fma_f32 v159, v105, v33, 1.0
	v_pk_mul_f32 v[34:35], v[158:159], v[34:35]
	v_lshlrev_b32_e32 v47, 16, v134
	v_pk_mul_f32 v[162:163], v[34:35], v[32:33] op_sel_hi:[1,0]
	v_mul_f32_e64 v46, v46, -v158
	v_pk_mul_f32 v[32:33], v[50:51], v[162:163] op_sel_hi:[0,1]
	ds_bpermute_b32 v32, v38, v32
	ds_bpermute_b32 v33, v38, v33
	ds_write_b32 v44, v47 offset:4864
	ds_write2st64_b32 v44, v46, v162 offset0:15 offset1:16
	ds_write2st64_b32 v44, v163, v50 offset0:17 offset1:18
	s_waitcnt lgkmcnt(3)
	v_pk_fma_f32 v[32:33], v[50:51], v[162:163], v[32:33] op_sel_hi:[0,1,1]
	ds_bpermute_b32 v34, v39, v32
	ds_bpermute_b32 v35, v39, v33
	s_waitcnt lgkmcnt(0)
	v_pk_add_f32 v[32:33], v[32:33], v[34:35]
	s_nop 1
	v_mov_b32_dpp v34, v32 row_ror:8 row_mask:0xf bank_mask:0xf
	v_mov_b32_dpp v35, v33 row_ror:8 row_mask:0xf bank_mask:0xf
	s_waitcnt lgkmcnt(0)
	v_pk_add_f32 v[32:33], v[32:33], v[34:35]
	s_nop 1
	v_mov_b32_dpp v34, v32 row_ror:4 row_mask:0xf bank_mask:0xf
	v_mov_b32_dpp v35, v33 row_ror:4 row_mask:0xf bank_mask:0xf
	s_waitcnt lgkmcnt(0)
	v_pk_add_f32 v[32:33], v[32:33], v[34:35]
	s_nop 1
	v_mov_b32_dpp v34, v32 quad_perm:[2,3,0,1] row_mask:0xf bank_mask:0xf
	v_mov_b32_dpp v35, v33 quad_perm:[2,3,0,1] row_mask:0xf bank_mask:0xf
	s_waitcnt lgkmcnt(0)
	v_pk_add_f32 v[32:33], v[32:33], v[34:35]
	s_nop 1
	v_mov_b32_dpp v34, v32 quad_perm:[1,0,3,2] row_mask:0xf bank_mask:0xf
	v_mov_b32_dpp v35, v33 quad_perm:[1,0,3,2] row_mask:0xf bank_mask:0xf
	s_and_saveexec_b64 s[12:13], s[4:5]
	s_cbranch_execz .LBB0_489
	s_waitcnt lgkmcnt(0)
	v_pk_add_f32 v[32:33], v[32:33], v[34:35]
	v_add_u32_e32 v34, v37, v98
	ds_write_b64 v34, v[32:33] offset:20736
.LBB0_489:
	s_or_b64 exec, exec, s[12:13]
	v_lshlrev_b32_e32 v32, 16, v145
	v_sub_f32_e32 v32, 1.0, v32
	v_mul_f32_e32 v46, v32, v45
	v_lshlrev_b32_e32 v33, 16, v131
	v_rcp_f32_e32 v32, v46
	s_waitcnt lgkmcnt(1)
	v_lshlrev_b32_e32 v34, 16, v144
	v_mul_f32_e32 v50, v46, v33
	v_add_f32_e32 v33, -1.0, v34
	v_lshlrev_b32_e32 v158, 16, v142
	s_waitcnt lgkmcnt(0)
	v_lshlrev_b32_e32 v35, 16, v133
	v_fma_f32 v159, v105, v33, 1.0
	v_pk_mul_f32 v[34:35], v[158:159], v[34:35]
	v_lshlrev_b32_e32 v47, 16, v140
	v_pk_mul_f32 v[162:163], v[34:35], v[32:33] op_sel_hi:[1,0]
	v_mul_f32_e64 v45, v45, -v158
	v_pk_mul_f32 v[32:33], v[50:51], v[162:163] op_sel_hi:[0,1]
	ds_bpermute_b32 v32, v38, v32
	ds_bpermute_b32 v33, v38, v33
	ds_write_b32 v44, v47 offset:6144
	ds_write2st64_b32 v44, v45, v162 offset0:20 offset1:21
	ds_write2st64_b32 v44, v163, v50 offset0:22 offset1:23
	s_waitcnt lgkmcnt(3)
	v_pk_fma_f32 v[32:33], v[50:51], v[162:163], v[32:33] op_sel_hi:[0,1,1]
	ds_bpermute_b32 v34, v39, v32
	ds_bpermute_b32 v35, v39, v33
	s_waitcnt lgkmcnt(0)
	v_pk_add_f32 v[32:33], v[32:33], v[34:35]
	s_nop 1
	v_mov_b32_dpp v34, v32 row_ror:8 row_mask:0xf bank_mask:0xf
	v_mov_b32_dpp v35, v33 row_ror:8 row_mask:0xf bank_mask:0xf
	s_waitcnt lgkmcnt(0)
	v_pk_add_f32 v[32:33], v[32:33], v[34:35]
	s_nop 1
	v_mov_b32_dpp v34, v32 row_ror:4 row_mask:0xf bank_mask:0xf
	v_mov_b32_dpp v35, v33 row_ror:4 row_mask:0xf bank_mask:0xf
	s_waitcnt lgkmcnt(0)
	v_pk_add_f32 v[32:33], v[32:33], v[34:35]
	s_nop 1
	v_mov_b32_dpp v34, v32 quad_perm:[2,3,0,1] row_mask:0xf bank_mask:0xf
	v_mov_b32_dpp v35, v33 quad_perm:[2,3,0,1] row_mask:0xf bank_mask:0xf
	s_waitcnt lgkmcnt(0)
	v_pk_add_f32 v[32:33], v[32:33], v[34:35]
	s_nop 1
	v_mov_b32_dpp v34, v32 quad_perm:[1,0,3,2] row_mask:0xf bank_mask:0xf
	v_mov_b32_dpp v35, v33 quad_perm:[1,0,3,2] row_mask:0xf bank_mask:0xf
	s_and_saveexec_b64 s[12:13], s[4:5]
	s_cbranch_execz .LBB0_491
	s_waitcnt lgkmcnt(0)
	v_pk_add_f32 v[32:33], v[32:33], v[34:35]
	v_add_u32_e32 v34, v37, v99
	ds_write_b64 v34, v[32:33] offset:20736
.LBB0_491:
	s_or_b64 exec, exec, s[12:13]
	v_lshlrev_b32_e32 v32, 16, v153
	v_sub_f32_e32 v32, 1.0, v32
	v_mul_f32_e32 v45, v32, v46
	v_lshlrev_b32_e32 v33, 16, v138
	v_rcp_f32_e32 v32, v45
	s_waitcnt lgkmcnt(1)
	v_lshlrev_b32_e32 v34, 16, v150
	v_mul_f32_e32 v50, v45, v33
	v_add_f32_e32 v33, -1.0, v34
	v_lshlrev_b32_e32 v158, 16, v143
	s_waitcnt lgkmcnt(0)
	v_lshlrev_b32_e32 v35, 16, v139
	v_fma_f32 v159, v105, v33, 1.0
	v_pk_mul_f32 v[34:35], v[158:159], v[34:35]
	v_lshlrev_b32_e32 v47, 16, v141
	v_pk_mul_f32 v[162:163], v[34:35], v[32:33] op_sel_hi:[1,0]
	v_mul_f32_e64 v46, v46, -v158
	v_pk_mul_f32 v[32:33], v[50:51], v[162:163] op_sel_hi:[0,1]
	ds_bpermute_b32 v32, v38, v32
	ds_bpermute_b32 v33, v38, v33
	ds_write_b32 v44, v47 offset:7424
	ds_write2st64_b32 v44, v46, v162 offset0:25 offset1:26
	ds_write2st64_b32 v44, v163, v50 offset0:27 offset1:28
	s_waitcnt lgkmcnt(3)
	v_pk_fma_f32 v[32:33], v[50:51], v[162:163], v[32:33] op_sel_hi:[0,1,1]
	ds_bpermute_b32 v34, v39, v32
	ds_bpermute_b32 v35, v39, v33
	s_waitcnt lgkmcnt(0)
	v_pk_add_f32 v[32:33], v[32:33], v[34:35]
	s_nop 1
	v_mov_b32_dpp v34, v32 row_ror:8 row_mask:0xf bank_mask:0xf
	v_mov_b32_dpp v35, v33 row_ror:8 row_mask:0xf bank_mask:0xf
	s_waitcnt lgkmcnt(0)
	v_pk_add_f32 v[32:33], v[32:33], v[34:35]
	s_nop 1
	v_mov_b32_dpp v34, v32 row_ror:4 row_mask:0xf bank_mask:0xf
	v_mov_b32_dpp v35, v33 row_ror:4 row_mask:0xf bank_mask:0xf
	s_waitcnt lgkmcnt(0)
	v_pk_add_f32 v[32:33], v[32:33], v[34:35]
	s_nop 1
	v_mov_b32_dpp v34, v32 quad_perm:[2,3,0,1] row_mask:0xf bank_mask:0xf
	v_mov_b32_dpp v35, v33 quad_perm:[2,3,0,1] row_mask:0xf bank_mask:0xf
	s_waitcnt lgkmcnt(0)
	v_pk_add_f32 v[32:33], v[32:33], v[34:35]
	s_nop 1
	v_mov_b32_dpp v34, v32 quad_perm:[1,0,3,2] row_mask:0xf bank_mask:0xf
	v_mov_b32_dpp v35, v33 quad_perm:[1,0,3,2] row_mask:0xf bank_mask:0xf
	s_and_saveexec_b64 s[12:13], s[4:5]
	s_cbranch_execz .LBB0_493
	s_waitcnt lgkmcnt(0)
	v_pk_add_f32 v[32:33], v[32:33], v[34:35]
	v_add_u32_e32 v34, v37, v100
	ds_write_b64 v34, v[32:33] offset:20736
.LBB0_493:
	s_or_b64 exec, exec, s[12:13]
	v_lshlrev_b32_e32 v32, 16, v152
	v_sub_f32_e32 v32, 1.0, v32
	v_mul_f32_e32 v46, v32, v45
	v_lshlrev_b32_e32 v33, 16, v146
	v_rcp_f32_e32 v32, v46
	s_waitcnt lgkmcnt(1)
	v_lshlrev_b32_e32 v34, 16, v151
	v_mul_f32_e32 v50, v46, v33
	v_add_f32_e32 v33, -1.0, v34
	v_lshlrev_b32_e32 v158, 16, v149
	s_waitcnt lgkmcnt(0)
	v_lshlrev_b32_e32 v35, 16, v147
	v_fma_f32 v159, v105, v33, 1.0
	v_pk_mul_f32 v[34:35], v[158:159], v[34:35]
	s_nop 0
	v_pk_mul_f32 v[162:163], v[34:35], v[32:33] op_sel_hi:[1,0]
	s_nop 0
	v_pk_mul_f32 v[32:33], v[50:51], v[162:163] op_sel_hi:[0,1]
	ds_bpermute_b32 v32, v38, v32
	ds_bpermute_b32 v33, v38, v33
	v_lshlrev_b32_e32 v38, 16, v148
	s_waitcnt lgkmcnt(0)
	v_pk_fma_f32 v[32:33], v[50:51], v[162:163], v[32:33] op_sel_hi:[0,1,1]
	ds_bpermute_b32 v34, v39, v32
	ds_bpermute_b32 v35, v39, v33
	v_mul_f32_e64 v39, v45, -v158
	ds_write_b32 v44, v38 offset:8704
	ds_write2st64_b32 v44, v39, v162 offset0:30 offset1:31
	ds_write2st64_b32 v44, v163, v50 offset0:32 offset1:33
	s_waitcnt lgkmcnt(3)
	v_pk_add_f32 v[32:33], v[32:33], v[34:35]
	s_nop 1
	v_mov_b32_dpp v34, v32 row_ror:8 row_mask:0xf bank_mask:0xf
	v_mov_b32_dpp v35, v33 row_ror:8 row_mask:0xf bank_mask:0xf
	s_waitcnt lgkmcnt(0)
	v_pk_add_f32 v[32:33], v[32:33], v[34:35]
	s_nop 1
	v_mov_b32_dpp v34, v32 row_ror:4 row_mask:0xf bank_mask:0xf
	v_mov_b32_dpp v35, v33 row_ror:4 row_mask:0xf bank_mask:0xf
	s_waitcnt lgkmcnt(0)
	v_pk_add_f32 v[32:33], v[32:33], v[34:35]
	s_nop 1
	v_mov_b32_dpp v34, v32 quad_perm:[2,3,0,1] row_mask:0xf bank_mask:0xf
	v_mov_b32_dpp v35, v33 quad_perm:[2,3,0,1] row_mask:0xf bank_mask:0xf
	s_waitcnt lgkmcnt(0)
	v_pk_add_f32 v[32:33], v[32:33], v[34:35]
	s_nop 1
	v_mov_b32_dpp v34, v32 quad_perm:[1,0,3,2] row_mask:0xf bank_mask:0xf
	v_mov_b32_dpp v35, v33 quad_perm:[1,0,3,2] row_mask:0xf bank_mask:0xf
	s_and_saveexec_b64 s[12:13], s[4:5]
	s_cbranch_execz .LBB0_496
	s_waitcnt lgkmcnt(0)
	v_pk_add_f32 v[32:33], v[32:33], v[34:35]
	v_add_u32_e32 v34, v37, v101
	ds_write_b64 v34, v[32:33] offset:20736
	s_or_b64 exec, exec, s[12:13]
	s_and_saveexec_b64 s[12:13], s[10:11]
	s_cbranch_execnz .LBB0_497

.LBB0_583:
	ds_read_b128 v[128:131], v164
	ds_read_b128 v[132:135], v164 offset:1024
	ds_read_b128 v[152:155], v164 offset:2048
	ds_read_b128 v[156:159], v164 offset:3072
	s_add_u32 s38, s36, 0xfffc0080
	s_addc_u32 s39, s37, -1
	s_cmp_eq_u32 s63, 12
	s_cselect_b32 s41, s9, s39
	s_cselect_b32 s40, s29, s38
	s_cselect_b32 s39, s27, s62
	s_cselect_b32 s38, s60, s61
	v_lshl_add_u64 v[200:201], s[36:37], 0, v[144:145]
	s_add_i32 m0, s50, 0xc000
	ds_read_b128 v[168:171], v165
	ds_read_b128 v[172:175], v165 offset:1024
	ds_read_b128 v[176:179], v165 offset:2048
	ds_read_b128 v[180:183], v165 offset:3072
	ds_read_b128 v[184:187], v165 offset:4096
	ds_read_b128 v[188:191], v165 offset:5120
	ds_read_b128 v[192:195], v165 offset:6144
	ds_read_b128 v[196:199], v165 offset:7168
	global_load_lds_dwordx4 v[200:201], off
	v_lshl_add_u64 v[200:201], s[36:37], 0, v[146:147]
	s_add_i32 m0, s50, 0xe000
	s_nop 0
	global_load_lds_dwordx4 v[200:201], off
	s_waitcnt lgkmcnt(8)
	s_barrier
	s_waitcnt lgkmcnt(0)
	s_setprio 1
	s_waitcnt lgkmcnt(0)
	v_mfma_f32_16x16x32_bf16 v[120:123], v[128:131], v[168:171], v[120:123]
	v_mfma_f32_16x16x32_bf16 v[124:127], v[152:155], v[168:171], v[124:127]
	v_mfma_f32_16x16x32_bf16 v[104:107], v[128:131], v[176:179], v[104:107]
	v_mfma_f32_16x16x32_bf16 v[108:111], v[152:155], v[176:179], v[108:111]
	v_mfma_f32_16x16x32_bf16 v[88:91], v[128:131], v[184:187], v[88:91]
	v_mfma_f32_16x16x32_bf16 v[92:95], v[152:155], v[184:187], v[92:95]
	v_mfma_f32_16x16x32_bf16 v[72:75], v[128:131], v[192:195], v[72:75]
	v_mfma_f32_16x16x32_bf16 v[76:79], v[152:155], v[192:195], v[76:79]
	v_mfma_f32_16x16x32_bf16 v[120:123], v[132:135], v[172:175], v[120:123]
	v_mfma_f32_16x16x32_bf16 v[124:127], v[156:159], v[172:175], v[124:127]
	v_mfma_f32_16x16x32_bf16 v[104:107], v[132:135], v[180:183], v[104:107]
	v_mfma_f32_16x16x32_bf16 v[108:111], v[156:159], v[180:183], v[108:111]
	v_mfma_f32_16x16x32_bf16 v[88:91], v[132:135], v[188:191], v[88:91]
	v_mfma_f32_16x16x32_bf16 v[92:95], v[156:159], v[188:191], v[92:95]
	v_mfma_f32_16x16x32_bf16 v[72:75], v[132:135], v[196:199], v[72:75]
	v_mfma_f32_16x16x32_bf16 v[76:79], v[156:159], v[196:199], v[76:79]
	s_setprio 0
	s_barrier
	s_add_i32 s64, s57, s49
	v_lshl_add_u64 v[216:217], s[38:39], 0, v[138:139]
	s_mov_b32 m0, s64
	ds_read_b128 v[200:203], v166
	ds_read_b128 v[204:207], v166 offset:1024
	ds_read_b128 v[208:211], v166 offset:2048
	ds_read_b128 v[212:215], v166 offset:3072
	global_load_lds_dwordx4 v[216:217], off
	v_lshl_add_u64 v[218:219], s[38:39], 0, v[142:143]
	s_add_i32 m0, s64, 0x2000
	s_nop 0
	global_load_lds_dwordx4 v[218:219], off
	s_barrier
	s_waitcnt lgkmcnt(0)
	s_setprio 1
	s_waitcnt lgkmcnt(0)
	v_mfma_f32_16x16x32_bf16 v[112:115], v[200:203], v[168:171], v[112:115]
	v_mfma_f32_16x16x32_bf16 v[116:119], v[208:211], v[168:171], v[116:119]
	v_mfma_f32_16x16x32_bf16 v[96:99], v[200:203], v[176:179], v[96:99]
	v_mfma_f32_16x16x32_bf16 v[100:103], v[208:211], v[176:179], v[100:103]
	v_mfma_f32_16x16x32_bf16 v[80:83], v[200:203], v[184:187], v[80:83]
	v_mfma_f32_16x16x32_bf16 v[84:87], v[208:211], v[184:187], v[84:87]
	v_mfma_f32_16x16x32_bf16 v[64:67], v[200:203], v[192:195], v[64:67]
	v_mfma_f32_16x16x32_bf16 v[68:71], v[208:211], v[192:195], v[68:71]
	v_mfma_f32_16x16x32_bf16 v[112:115], v[204:207], v[172:175], v[112:115]
	v_mfma_f32_16x16x32_bf16 v[116:119], v[212:215], v[172:175], v[116:119]
	v_mfma_f32_16x16x32_bf16 v[96:99], v[204:207], v[180:183], v[96:99]
	v_mfma_f32_16x16x32_bf16 v[100:103], v[212:215], v[180:183], v[100:103]
	v_mfma_f32_16x16x32_bf16 v[80:83], v[204:207], v[188:191], v[80:83]
	v_mfma_f32_16x16x32_bf16 v[84:87], v[212:215], v[188:191], v[84:87]
	v_mfma_f32_16x16x32_bf16 v[64:67], v[204:207], v[196:199], v[64:67]
	v_mfma_f32_16x16x32_bf16 v[68:71], v[212:215], v[196:199], v[68:71]
	s_setprio 0
	s_mov_b32 m0, s50
	v_lshl_add_u64 v[220:221], s[40:41], 0, v[136:137]
	s_barrier
	ds_read_b128 v[168:171], v165 offset:16384
	ds_read_b128 v[172:175], v165 offset:17408
	ds_read_b128 v[176:179], v165 offset:18432
	ds_read_b128 v[180:183], v165 offset:19456
	ds_read_b128 v[184:187], v165 offset:20480
	ds_read_b128 v[188:191], v165 offset:21504
	ds_read_b128 v[192:195], v165 offset:22528
	ds_read_b128 v[196:199], v165 offset:23552
	global_load_lds_dwordx4 v[220:221], off
	v_lshl_add_u64 v[222:223], s[40:41], 0, v[140:141]
	s_mov_b32 m0, s51
	s_nop 0
	global_load_lds_dwordx4 v[222:223], off
	s_barrier
	s_waitcnt lgkmcnt(0)
	s_setprio 1
	s_waitcnt lgkmcnt(0)
	v_mfma_f32_16x16x32_bf16 v[56:59], v[128:131], v[168:171], v[56:59]
	v_mfma_f32_16x16x32_bf16 v[60:63], v[152:155], v[168:171], v[60:63]
	v_mfma_f32_16x16x32_bf16 v[40:43], v[128:131], v[176:179], v[40:43]
	v_mfma_f32_16x16x32_bf16 v[44:47], v[152:155], v[176:179], v[44:47]
	v_mfma_f32_16x16x32_bf16 v[24:27], v[128:131], v[184:187], v[24:27]
	v_mfma_f32_16x16x32_bf16 v[28:31], v[152:155], v[184:187], v[28:31]
	v_mfma_f32_16x16x32_bf16 v[8:11], v[128:131], v[192:195], v[8:11]
	v_mfma_f32_16x16x32_bf16 v[12:15], v[152:155], v[192:195], v[12:15]
	v_mfma_f32_16x16x32_bf16 v[56:59], v[132:135], v[172:175], v[56:59]
	v_mfma_f32_16x16x32_bf16 v[60:63], v[156:159], v[172:175], v[60:63]
	v_mfma_f32_16x16x32_bf16 v[40:43], v[132:135], v[180:183], v[40:43]
	v_mfma_f32_16x16x32_bf16 v[44:47], v[156:159], v[180:183], v[44:47]
	v_mfma_f32_16x16x32_bf16 v[24:27], v[132:135], v[188:191], v[24:27]
	v_mfma_f32_16x16x32_bf16 v[28:31], v[156:159], v[188:191], v[28:31]
	v_mfma_f32_16x16x32_bf16 v[8:11], v[132:135], v[196:199], v[8:11]
	v_mfma_f32_16x16x32_bf16 v[12:15], v[156:159], v[196:199], v[12:15]
	s_setprio 0
	s_barrier
	s_add_u32 s64, s38, 0x40000
	s_addc_u32 s65, s39, 0
	s_add_i32 s66, s58, s49
	v_lshl_add_u64 v[128:129], s[64:65], 0, v[138:139]
	s_mov_b32 m0, s66
	s_nop 0
	global_load_lds_dwordx4 v[128:129], off
	v_lshl_add_u64 v[128:129], s[64:65], 0, v[142:143]
	s_add_i32 m0, s66, 0x2000
	s_nop 0
	global_load_lds_dwordx4 v[128:129], off
	s_waitcnt vmcnt(6)
	s_barrier
	s_setprio 1
	v_mfma_f32_16x16x32_bf16 v[48:51], v[200:203], v[168:171], v[48:51]
	v_mfma_f32_16x16x32_bf16 v[52:55], v[208:211], v[168:171], v[52:55]
	v_mfma_f32_16x16x32_bf16 v[32:35], v[200:203], v[176:179], v[32:35]
	v_mfma_f32_16x16x32_bf16 v[36:39], v[208:211], v[176:179], v[36:39]
	v_mfma_f32_16x16x32_bf16 v[16:19], v[200:203], v[184:187], v[16:19]
	v_mfma_f32_16x16x32_bf16 v[20:23], v[208:211], v[184:187], v[20:23]
	v_mfma_f32_16x16x32_bf16 v[4:7], v[200:203], v[192:195], v[4:7]
	v_mfma_f32_16x16x32_bf16 v[0:3], v[208:211], v[192:195], v[0:3]
	v_mfma_f32_16x16x32_bf16 v[48:51], v[204:207], v[172:175], v[48:51]
	v_mfma_f32_16x16x32_bf16 v[52:55], v[212:215], v[172:175], v[52:55]
	v_mfma_f32_16x16x32_bf16 v[32:35], v[204:207], v[180:183], v[32:35]
	v_mfma_f32_16x16x32_bf16 v[36:39], v[212:215], v[180:183], v[36:39]
	v_mfma_f32_16x16x32_bf16 v[16:19], v[204:207], v[188:191], v[16:19]
	v_mfma_f32_16x16x32_bf16 v[20:23], v[212:215], v[188:191], v[20:23]
	v_mfma_f32_16x16x32_bf16 v[4:7], v[204:207], v[196:199], v[4:7]
	v_mfma_f32_16x16x32_bf16 v[0:3], v[212:215], v[196:199], v[0:3]
	s_setprio 0
	s_add_i32 s64, 0, 0x18000
	v_add_u32_e32 v156, s64, v162
	s_barrier
	ds_read_b128 v[128:131], v156
	ds_read_b128 v[132:135], v156 offset:1024
	ds_read_b128 v[152:155], v156 offset:2048
	ds_read_b128 v[156:159], v156 offset:3072
	s_add_u32 s40, s40, 0x40000
	s_addc_u32 s41, s41, 0
	s_mov_b32 m0, s52
	v_lshl_add_u64 v[200:201], s[40:41], 0, v[136:137]
	ds_read_b128 v[168:171], v165 offset:32768
	ds_read_b128 v[172:175], v165 offset:33792
	ds_read_b128 v[176:179], v165 offset:34816
	ds_read_b128 v[180:183], v165 offset:35840
	ds_read_b128 v[184:187], v165 offset:36864
	ds_read_b128 v[188:191], v165 offset:37888
	ds_read_b128 v[192:195], v165 offset:38912
	ds_read_b128 v[196:199], v165 offset:39936
	global_load_lds_dwordx4 v[200:201], off
	v_lshl_add_u64 v[200:201], s[40:41], 0, v[140:141]
	s_mov_b32 m0, s53
	s_nop 0
	global_load_lds_dwordx4 v[200:201], off
	s_waitcnt lgkmcnt(8)
	s_barrier
	s_waitcnt lgkmcnt(0)
	s_setprio 1
	s_waitcnt lgkmcnt(0)
	v_mfma_f32_16x16x32_bf16 v[120:123], v[128:131], v[168:171], v[120:123]
	v_mfma_f32_16x16x32_bf16 v[124:127], v[152:155], v[168:171], v[124:127]
	v_mfma_f32_16x16x32_bf16 v[104:107], v[128:131], v[176:179], v[104:107]
	v_mfma_f32_16x16x32_bf16 v[108:111], v[152:155], v[176:179], v[108:111]
	v_mfma_f32_16x16x32_bf16 v[88:91], v[128:131], v[184:187], v[88:91]
	v_mfma_f32_16x16x32_bf16 v[92:95], v[152:155], v[184:187], v[92:95]
	v_mfma_f32_16x16x32_bf16 v[72:75], v[128:131], v[192:195], v[72:75]
	v_mfma_f32_16x16x32_bf16 v[76:79], v[152:155], v[192:195], v[76:79]
	v_mfma_f32_16x16x32_bf16 v[120:123], v[132:135], v[172:175], v[120:123]
	v_mfma_f32_16x16x32_bf16 v[124:127], v[156:159], v[172:175], v[124:127]
	v_mfma_f32_16x16x32_bf16 v[104:107], v[132:135], v[180:183], v[104:107]
	v_mfma_f32_16x16x32_bf16 v[108:111], v[156:159], v[180:183], v[108:111]
	v_mfma_f32_16x16x32_bf16 v[88:91], v[132:135], v[188:191], v[88:91]
	v_mfma_f32_16x16x32_bf16 v[92:95], v[156:159], v[188:191], v[92:95]
	v_mfma_f32_16x16x32_bf16 v[72:75], v[132:135], v[196:199], v[72:75]
	v_mfma_f32_16x16x32_bf16 v[76:79], v[156:159], v[196:199], v[76:79]
	s_setprio 0
	s_barrier
	s_add_i32 s40, 0, 0x1c000
	s_add_i32 s41, s64, s49
	v_add_u32_e32 v212, s40, v162
	v_lshl_add_u64 v[216:217], v[216:217], 0, s[22:23]
	s_mov_b32 m0, s41
	ds_read_b128 v[200:203], v212
	ds_read_b128 v[204:207], v212 offset:1024
	ds_read_b128 v[208:211], v212 offset:2048
	ds_read_b128 v[212:215], v212 offset:3072
	global_load_lds_dwordx4 v[216:217], off
	v_lshl_add_u64 v[216:217], v[218:219], 0, s[22:23]
	s_add_i32 m0, s41, 0x2000
	s_nop 0
	global_load_lds_dwordx4 v[216:217], off
	s_barrier
	s_waitcnt lgkmcnt(0)
	s_setprio 1
	s_waitcnt lgkmcnt(0)
	v_mfma_f32_16x16x32_bf16 v[112:115], v[200:203], v[168:171], v[112:115]
	v_mfma_f32_16x16x32_bf16 v[116:119], v[208:211], v[168:171], v[116:119]
	v_mfma_f32_16x16x32_bf16 v[96:99], v[200:203], v[176:179], v[96:99]
	v_mfma_f32_16x16x32_bf16 v[100:103], v[208:211], v[176:179], v[100:103]
	v_mfma_f32_16x16x32_bf16 v[80:83], v[200:203], v[184:187], v[80:83]
	v_mfma_f32_16x16x32_bf16 v[84:87], v[208:211], v[184:187], v[84:87]
	v_mfma_f32_16x16x32_bf16 v[64:67], v[200:203], v[192:195], v[64:67]
	v_mfma_f32_16x16x32_bf16 v[68:71], v[208:211], v[192:195], v[68:71]
	v_mfma_f32_16x16x32_bf16 v[112:115], v[204:207], v[172:175], v[112:115]
	v_mfma_f32_16x16x32_bf16 v[116:119], v[212:215], v[172:175], v[116:119]
	v_mfma_f32_16x16x32_bf16 v[96:99], v[204:207], v[180:183], v[96:99]
	v_mfma_f32_16x16x32_bf16 v[100:103], v[212:215], v[180:183], v[100:103]
	v_mfma_f32_16x16x32_bf16 v[80:83], v[204:207], v[188:191], v[80:83]
	v_mfma_f32_16x16x32_bf16 v[84:87], v[212:215], v[188:191], v[84:87]
	v_mfma_f32_16x16x32_bf16 v[64:67], v[204:207], v[196:199], v[64:67]
	v_mfma_f32_16x16x32_bf16 v[68:71], v[212:215], v[196:199], v[68:71]
	s_setprio 0
	s_mov_b32 m0, s55
	v_lshl_add_u64 v[216:217], v[220:221], 0, s[22:23]
	s_barrier
	ds_read_b128 v[168:171], v165 offset:49152
	ds_read_b128 v[172:175], v165 offset:50176
	ds_read_b128 v[176:179], v165 offset:51200
	ds_read_b128 v[180:183], v165 offset:52224
	ds_read_b128 v[184:187], v165 offset:53248
	ds_read_b128 v[188:191], v165 offset:54272
	ds_read_b128 v[192:195], v165 offset:55296
	ds_read_b128 v[196:199], v165 offset:56320
	global_load_lds_dwordx4 v[216:217], off
	v_lshl_add_u64 v[216:217], v[222:223], 0, s[22:23]
	s_mov_b32 m0, s56
	s_nop 0
	global_load_lds_dwordx4 v[216:217], off
	s_barrier
	s_waitcnt lgkmcnt(0)
	s_setprio 1
	s_waitcnt lgkmcnt(0)
	v_mfma_f32_16x16x32_bf16 v[56:59], v[128:131], v[168:171], v[56:59]
	v_mfma_f32_16x16x32_bf16 v[60:63], v[152:155], v[168:171], v[60:63]
	v_mfma_f32_16x16x32_bf16 v[40:43], v[128:131], v[176:179], v[40:43]
	v_mfma_f32_16x16x32_bf16 v[44:47], v[152:155], v[176:179], v[44:47]
	v_mfma_f32_16x16x32_bf16 v[24:27], v[128:131], v[184:187], v[24:27]
	v_mfma_f32_16x16x32_bf16 v[28:31], v[152:155], v[184:187], v[28:31]
	v_mfma_f32_16x16x32_bf16 v[8:11], v[128:131], v[192:195], v[8:11]
	v_mfma_f32_16x16x32_bf16 v[12:15], v[152:155], v[192:195], v[12:15]
	v_mfma_f32_16x16x32_bf16 v[56:59], v[132:135], v[172:175], v[56:59]
	v_mfma_f32_16x16x32_bf16 v[60:63], v[156:159], v[172:175], v[60:63]
	v_mfma_f32_16x16x32_bf16 v[40:43], v[132:135], v[180:183], v[40:43]
	v_mfma_f32_16x16x32_bf16 v[44:47], v[156:159], v[180:183], v[44:47]
	v_mfma_f32_16x16x32_bf16 v[24:27], v[132:135], v[188:191], v[24:27]
	v_mfma_f32_16x16x32_bf16 v[28:31], v[156:159], v[188:191], v[28:31]
	v_mfma_f32_16x16x32_bf16 v[8:11], v[132:135], v[196:199], v[8:11]
	v_mfma_f32_16x16x32_bf16 v[12:15], v[156:159], v[196:199], v[12:15]
	s_setprio 0
	s_barrier
	s_add_u32 s38, s38, 0x40080
	s_addc_u32 s39, s39, 0
	s_add_i32 s40, s40, s49
	v_lshl_add_u64 v[128:129], s[38:39], 0, v[138:139]
	s_mov_b32 m0, s40
	s_nop 0
	global_load_lds_dwordx4 v[128:129], off
	v_lshl_add_u64 v[128:129], s[38:39], 0, v[142:143]
	s_add_i32 m0, s40, 0x2000
	s_nop 0
	global_load_lds_dwordx4 v[128:129], off
	s_waitcnt vmcnt(6)
	s_barrier
	s_setprio 1
	v_mfma_f32_16x16x32_bf16 v[48:51], v[200:203], v[168:171], v[48:51]
	v_mfma_f32_16x16x32_bf16 v[52:55], v[208:211], v[168:171], v[52:55]
	v_mfma_f32_16x16x32_bf16 v[32:35], v[200:203], v[176:179], v[32:35]
	v_mfma_f32_16x16x32_bf16 v[36:39], v[208:211], v[176:179], v[36:39]
	v_mfma_f32_16x16x32_bf16 v[16:19], v[200:203], v[184:187], v[16:19]
	v_mfma_f32_16x16x32_bf16 v[20:23], v[208:211], v[184:187], v[20:23]
	v_mfma_f32_16x16x32_bf16 v[4:7], v[200:203], v[192:195], v[4:7]
	v_mfma_f32_16x16x32_bf16 v[0:3], v[208:211], v[192:195], v[0:3]
	v_mfma_f32_16x16x32_bf16 v[48:51], v[204:207], v[172:175], v[48:51]
	v_mfma_f32_16x16x32_bf16 v[52:55], v[212:215], v[172:175], v[52:55]
	v_mfma_f32_16x16x32_bf16 v[32:35], v[204:207], v[180:183], v[32:35]
	v_mfma_f32_16x16x32_bf16 v[36:39], v[212:215], v[180:183], v[36:39]
	v_mfma_f32_16x16x32_bf16 v[16:19], v[204:207], v[188:191], v[16:19]
	v_mfma_f32_16x16x32_bf16 v[20:23], v[212:215], v[188:191], v[20:23]
	v_mfma_f32_16x16x32_bf16 v[4:7], v[204:207], v[196:199], v[4:7]
	v_mfma_f32_16x16x32_bf16 v[0:3], v[212:215], v[196:199], v[0:3]
	s_setprio 0
	s_add_i32 s63, s63, 2
	s_add_u32 s36, s36, 0x100
	s_addc_u32 s37, s37, 0
	s_add_u32 s61, s61, 0x100
	s_addc_u32 s62, s62, 0
	s_cmp_gt_u32 s63, 13
	s_barrier
	s_cbranch_scc0 .LBB0_583
	v_lshl_add_u32 v152, s8, 8, v161
	v_lshl_or_b32 v153, s16, 8, v163
	s_lshl_b32 s36, s16, 2
	s_ashr_i32 s37, s36, 31
	s_lshl_b32 s16, s54, 2
	v_lshl_add_u32 v154, v152, 10, v153
	v_lshl_add_u32 v156, v152, 6, s16
	v_lshl_add_u32 v156, s36, 2, v156
	v_lshlrev_b32_e32 v155, 1, v154
	v_lshlrev_b32_e32 v154, 2, v154
	global_load_dwordx4 v[168:171], v154, s[14:15]
	global_load_dwordx4 v[172:175], v154, s[14:15] offset:16
	global_load_dwordx4 v[176:179], v154, s[14:15] offset:512
	global_load_dwordx4 v[180:183], v154, s[14:15] offset:528
	v_add_u32_e32 v154, 0x10000, v154
	global_load_dwordx4 v[184:187], v154, s[14:15]
	global_load_dwordx4 v[188:191], v154, s[14:15] offset:16
	global_load_dwordx4 v[192:195], v154, s[14:15] offset:512
	global_load_dwordx4 v[196:199], v154, s[14:15] offset:528
	v_add_u32_e32 v154, 0x10000, v154
	global_load_dwordx4 v[200:203], v154, s[14:15]
	global_load_dwordx4 v[204:207], v154, s[14:15] offset:16
	global_load_dwordx4 v[208:211], v154, s[14:15] offset:512
	global_load_dwordx4 v[212:215], v154, s[14:15] offset:528
	v_add_u32_e32 v154, 0x10000, v154
	global_load_dwordx4 v[216:219], v154, s[14:15]
	global_load_dwordx4 v[220:223], v154, s[14:15] offset:16
	global_load_dwordx4 v[128:131], v154, s[14:15] offset:512
	global_load_dwordx4 v[132:135], v154, s[14:15] offset:528
	v_add_u32_e32 v154, 0x50000, v154
	s_waitcnt vmcnt(12)
	v_pk_add_f32 v[120:121], v[120:121], v[168:169]
	v_pk_add_f32 v[122:123], v[122:123], v[170:171]
	v_pk_add_f32 v[124:125], v[124:125], v[172:173]
	v_pk_add_f32 v[126:127], v[126:127], v[174:175]
	v_cvt_pk_bf16_f32 v168, v120, v121
	v_cvt_pk_bf16_f32 v169, v122, v123
	v_cvt_pk_bf16_f32 v170, v124, v125
	v_cvt_pk_bf16_f32 v171, v126, v127
	v_pk_mul_f32 v[172:173], v[120:121], v[120:121]
	global_store_dwordx4 v155, v[168:171], s[18:19]
	v_pk_fma_f32 v[172:173], v[122:123], v[122:123], v[172:173]
	v_pk_fma_f32 v[172:173], v[124:125], v[124:125], v[172:173]
	v_pk_fma_f32 v[172:173], v[126:127], v[126:127], v[172:173]
	v_pk_add_f32 v[112:113], v[112:113], v[176:177]
	v_pk_add_f32 v[114:115], v[114:115], v[178:179]
	v_pk_add_f32 v[116:117], v[116:117], v[180:181]
	v_pk_add_f32 v[118:119], v[118:119], v[182:183]
	v_cvt_pk_bf16_f32 v176, v112, v113
	v_cvt_pk_bf16_f32 v177, v114, v115
	v_cvt_pk_bf16_f32 v178, v116, v117
	v_cvt_pk_bf16_f32 v179, v118, v119
	v_pk_fma_f32 v[172:173], v[112:113], v[112:113], v[172:173]
	global_store_dwordx4 v155, v[176:179], s[18:19] offset:256
	v_pk_fma_f32 v[172:173], v[114:115], v[114:115], v[172:173]
	v_pk_fma_f32 v[172:173], v[116:117], v[116:117], v[172:173]
	v_pk_fma_f32 v[172:173], v[118:119], v[118:119], v[172:173]
	v_add_f32_e32 v157, v172, v173
	v_add_u32_e32 v155, 0x8000, v155
	v_mov_b32_e32 v158, v157
	s_nop 1
	v_permlane16_swap_b32_e32 v157, v158
	s_nop 0
	v_add_f32_e32 v157, v157, v158
	v_mov_b32_e32 v158, v157
	s_nop 1
	v_permlane32_swap_b32_e32 v157, v158
	s_nop 0
	v_add_f32_e32 v157, v157, v158
	s_and_saveexec_b64 s[38:39], s[4:5]
	global_store_dword v156, v157, s[20:21]
	s_mov_b64 exec, s[38:39]
	global_load_dwordx4 v[168:171], v154, s[14:15]
	global_load_dwordx4 v[172:175], v154, s[14:15] offset:16
	global_load_dwordx4 v[176:179], v154, s[14:15] offset:512
	global_load_dwordx4 v[180:183], v154, s[14:15] offset:528
	v_add_u32_e32 v154, 0x10000, v154
	s_waitcnt vmcnt(15)
	v_pk_add_f32 v[104:105], v[104:105], v[184:185]
	v_pk_add_f32 v[106:107], v[106:107], v[186:187]
	v_pk_add_f32 v[108:109], v[108:109], v[188:189]
	v_pk_add_f32 v[110:111], v[110:111], v[190:191]
	v_cvt_pk_bf16_f32 v184, v104, v105
	v_cvt_pk_bf16_f32 v185, v106, v107
	v_cvt_pk_bf16_f32 v186, v108, v109
	v_cvt_pk_bf16_f32 v187, v110, v111
	v_pk_mul_f32 v[188:189], v[104:105], v[104:105]
	global_store_dwordx4 v155, v[184:187], s[18:19]
	v_pk_fma_f32 v[188:189], v[106:107], v[106:107], v[188:189]
	v_pk_fma_f32 v[188:189], v[108:109], v[108:109], v[188:189]
	v_pk_fma_f32 v[188:189], v[110:111], v[110:111], v[188:189]
	v_pk_add_f32 v[96:97], v[96:97], v[192:193]
	v_pk_add_f32 v[98:99], v[98:99], v[194:195]
	v_pk_add_f32 v[100:101], v[100:101], v[196:197]
	v_pk_add_f32 v[102:103], v[102:103], v[198:199]
	v_cvt_pk_bf16_f32 v192, v96, v97
	v_cvt_pk_bf16_f32 v193, v98, v99
	v_cvt_pk_bf16_f32 v194, v100, v101
	v_cvt_pk_bf16_f32 v195, v102, v103
	v_pk_fma_f32 v[188:189], v[96:97], v[96:97], v[188:189]
	global_store_dwordx4 v155, v[192:195], s[18:19] offset:256
	v_pk_fma_f32 v[188:189], v[98:99], v[98:99], v[188:189]
	v_pk_fma_f32 v[188:189], v[100:101], v[100:101], v[188:189]
	v_pk_fma_f32 v[188:189], v[102:103], v[102:103], v[188:189]
	v_add_f32_e32 v157, v188, v189
	v_add_u32_e32 v155, 0x8000, v155
	v_mov_b32_e32 v158, v157
	s_nop 1
	v_permlane16_swap_b32_e32 v157, v158
	s_nop 0
	v_add_f32_e32 v157, v157, v158
	v_mov_b32_e32 v158, v157
	s_nop 1
	v_permlane32_swap_b32_e32 v157, v158
	s_nop 0
	v_add_f32_e32 v157, v157, v158
	s_and_saveexec_b64 s[38:39], s[4:5]
	global_store_dword v156, v157, s[20:21] offset:1024
	s_mov_b64 exec, s[38:39]
	global_load_dwordx4 v[184:187], v154, s[14:15]
	global_load_dwordx4 v[188:191], v154, s[14:15] offset:16
	global_load_dwordx4 v[192:195], v154, s[14:15] offset:512
	global_load_dwordx4 v[196:199], v154, s[14:15] offset:528
	v_add_u32_e32 v154, 0x10000, v154
	s_waitcnt vmcnt(18)
	v_pk_add_f32 v[88:89], v[88:89], v[200:201]
	v_pk_add_f32 v[90:91], v[90:91], v[202:203]
	v_pk_add_f32 v[92:93], v[92:93], v[204:205]
	v_pk_add_f32 v[94:95], v[94:95], v[206:207]
	v_cvt_pk_bf16_f32 v200, v88, v89
	v_cvt_pk_bf16_f32 v201, v90, v91
	v_cvt_pk_bf16_f32 v202, v92, v93
	v_cvt_pk_bf16_f32 v203, v94, v95
	v_pk_mul_f32 v[204:205], v[88:89], v[88:89]
	global_store_dwordx4 v155, v[200:203], s[18:19]
	v_pk_fma_f32 v[204:205], v[90:91], v[90:91], v[204:205]
	v_pk_fma_f32 v[204:205], v[92:93], v[92:93], v[204:205]
	v_pk_fma_f32 v[204:205], v[94:95], v[94:95], v[204:205]
	v_pk_add_f32 v[80:81], v[80:81], v[208:209]
	v_pk_add_f32 v[82:83], v[82:83], v[210:211]
	v_pk_add_f32 v[84:85], v[84:85], v[212:213]
	v_pk_add_f32 v[86:87], v[86:87], v[214:215]
	v_cvt_pk_bf16_f32 v208, v80, v81
	v_cvt_pk_bf16_f32 v209, v82, v83
	v_cvt_pk_bf16_f32 v210, v84, v85
	v_cvt_pk_bf16_f32 v211, v86, v87
	v_pk_fma_f32 v[204:205], v[80:81], v[80:81], v[204:205]
	global_store_dwordx4 v155, v[208:211], s[18:19] offset:256
	v_pk_fma_f32 v[204:205], v[82:83], v[82:83], v[204:205]
	v_pk_fma_f32 v[204:205], v[84:85], v[84:85], v[204:205]
	v_pk_fma_f32 v[204:205], v[86:87], v[86:87], v[204:205]
	v_add_f32_e32 v157, v204, v205
	v_add_u32_e32 v155, 0x8000, v155
	v_mov_b32_e32 v158, v157
	s_nop 1
	v_permlane16_swap_b32_e32 v157, v158
	s_nop 0
	v_add_f32_e32 v157, v157, v158
	v_mov_b32_e32 v158, v157
	s_nop 1
	v_permlane32_swap_b32_e32 v157, v158
	s_nop 0
	v_add_f32_e32 v157, v157, v158
	s_and_saveexec_b64 s[38:39], s[4:5]
	global_store_dword v156, v157, s[20:21] offset:2048
	s_mov_b64 exec, s[38:39]
	global_load_dwordx4 v[200:203], v154, s[14:15]
	global_load_dwordx4 v[204:207], v154, s[14:15] offset:16
	global_load_dwordx4 v[208:211], v154, s[14:15] offset:512
	global_load_dwordx4 v[212:215], v154, s[14:15] offset:528
	v_add_u32_e32 v154, 0x10000, v154
	s_waitcnt vmcnt(21)
	v_pk_add_f32 v[72:73], v[72:73], v[216:217]
	v_pk_add_f32 v[74:75], v[74:75], v[218:219]
	v_pk_add_f32 v[76:77], v[76:77], v[220:221]
	v_pk_add_f32 v[78:79], v[78:79], v[222:223]
	v_cvt_pk_bf16_f32 v216, v72, v73
	v_cvt_pk_bf16_f32 v217, v74, v75
	v_cvt_pk_bf16_f32 v218, v76, v77
	v_cvt_pk_bf16_f32 v219, v78, v79
	v_pk_mul_f32 v[220:221], v[72:73], v[72:73]
	global_store_dwordx4 v155, v[216:219], s[18:19]
	v_pk_fma_f32 v[220:221], v[74:75], v[74:75], v[220:221]
	v_pk_fma_f32 v[220:221], v[76:77], v[76:77], v[220:221]
	v_pk_fma_f32 v[220:221], v[78:79], v[78:79], v[220:221]
	v_pk_add_f32 v[64:65], v[64:65], v[128:129]
	v_pk_add_f32 v[66:67], v[66:67], v[130:131]
	v_pk_add_f32 v[68:69], v[68:69], v[132:133]
	v_pk_add_f32 v[70:71], v[70:71], v[134:135]
	v_cvt_pk_bf16_f32 v128, v64, v65
	v_cvt_pk_bf16_f32 v129, v66, v67
	v_cvt_pk_bf16_f32 v130, v68, v69
	v_cvt_pk_bf16_f32 v131, v70, v71
	v_pk_fma_f32 v[220:221], v[64:65], v[64:65], v[220:221]
	global_store_dwordx4 v155, v[128:131], s[18:19] offset:256
	v_pk_fma_f32 v[220:221], v[66:67], v[66:67], v[220:221]
	v_pk_fma_f32 v[220:221], v[68:69], v[68:69], v[220:221]
	v_pk_fma_f32 v[220:221], v[70:71], v[70:71], v[220:221]
	v_add_f32_e32 v157, v220, v221
	v_add_u32_e32 v155, 0x28000, v155
	v_mov_b32_e32 v158, v157
	s_nop 1
	v_permlane16_swap_b32_e32 v157, v158
	s_nop 0
	v_add_f32_e32 v157, v157, v158
	v_mov_b32_e32 v158, v157
	s_nop 1
	v_permlane32_swap_b32_e32 v157, v158
	s_nop 0
	v_add_f32_e32 v157, v157, v158
	s_and_saveexec_b64 s[38:39], s[4:5]
	global_store_dword v156, v157, s[20:21] offset:3072
	s_mov_b64 exec, s[38:39]
	v_add_u32_e32 v156, 0x2000, v156
	global_load_dwordx4 v[216:219], v154, s[14:15]
	global_load_dwordx4 v[220:223], v154, s[14:15] offset:16
	global_load_dwordx4 v[128:131], v154, s[14:15] offset:512
	global_load_dwordx4 v[132:135], v154, s[14:15] offset:528
	s_waitcnt vmcnt(21)
	v_pk_add_f32 v[56:57], v[56:57], v[168:169]
	v_pk_add_f32 v[58:59], v[58:59], v[170:171]
	v_pk_add_f32 v[60:61], v[60:61], v[172:173]
	v_pk_add_f32 v[62:63], v[62:63], v[174:175]
	v_cvt_pk_bf16_f32 v168, v56, v57
	v_cvt_pk_bf16_f32 v169, v58, v59
	v_cvt_pk_bf16_f32 v170, v60, v61
	v_cvt_pk_bf16_f32 v171, v62, v63
	v_pk_mul_f32 v[172:173], v[56:57], v[56:57]
	global_store_dwordx4 v155, v[168:171], s[18:19]
	v_pk_fma_f32 v[172:173], v[58:59], v[58:59], v[172:173]
	v_pk_fma_f32 v[172:173], v[60:61], v[60:61], v[172:173]
	v_pk_fma_f32 v[172:173], v[62:63], v[62:63], v[172:173]
	v_pk_add_f32 v[48:49], v[48:49], v[176:177]
	v_pk_add_f32 v[50:51], v[50:51], v[178:179]
	v_pk_add_f32 v[52:53], v[52:53], v[180:181]
	v_pk_add_f32 v[54:55], v[54:55], v[182:183]
	v_cvt_pk_bf16_f32 v176, v48, v49
	v_cvt_pk_bf16_f32 v177, v50, v51
	v_cvt_pk_bf16_f32 v178, v52, v53
	v_cvt_pk_bf16_f32 v179, v54, v55
	v_pk_fma_f32 v[172:173], v[48:49], v[48:49], v[172:173]
	global_store_dwordx4 v155, v[176:179], s[18:19] offset:256
	v_pk_fma_f32 v[172:173], v[50:51], v[50:51], v[172:173]
	v_pk_fma_f32 v[172:173], v[52:53], v[52:53], v[172:173]
	v_pk_fma_f32 v[172:173], v[54:55], v[54:55], v[172:173]
	v_add_f32_e32 v157, v172, v173
	v_add_u32_e32 v155, 0x8000, v155
	v_mov_b32_e32 v158, v157
	s_nop 1
	v_permlane16_swap_b32_e32 v157, v158
	s_nop 0
	v_add_f32_e32 v157, v157, v158
	v_mov_b32_e32 v158, v157
	s_nop 1
	v_permlane32_swap_b32_e32 v157, v158
	s_nop 0
	v_add_f32_e32 v157, v157, v158
	s_and_saveexec_b64 s[38:39], s[4:5]
	global_store_dword v156, v157, s[20:21]
	s_mov_b64 exec, s[38:39]
	s_waitcnt vmcnt(17)
	v_pk_add_f32 v[40:41], v[40:41], v[184:185]
	v_pk_add_f32 v[42:43], v[42:43], v[186:187]
	v_pk_add_f32 v[44:45], v[44:45], v[188:189]
	v_pk_add_f32 v[46:47], v[46:47], v[190:191]
	v_cvt_pk_bf16_f32 v184, v40, v41
	v_cvt_pk_bf16_f32 v185, v42, v43
	v_cvt_pk_bf16_f32 v186, v44, v45
	v_cvt_pk_bf16_f32 v187, v46, v47
	v_pk_mul_f32 v[188:189], v[40:41], v[40:41]
	global_store_dwordx4 v155, v[184:187], s[18:19]
	v_pk_fma_f32 v[188:189], v[42:43], v[42:43], v[188:189]
	v_pk_fma_f32 v[188:189], v[44:45], v[44:45], v[188:189]
	v_pk_fma_f32 v[188:189], v[46:47], v[46:47], v[188:189]
	v_pk_add_f32 v[32:33], v[32:33], v[192:193]
	v_pk_add_f32 v[34:35], v[34:35], v[194:195]
	v_pk_add_f32 v[36:37], v[36:37], v[196:197]
	v_pk_add_f32 v[38:39], v[38:39], v[198:199]
	v_cvt_pk_bf16_f32 v192, v32, v33
	v_cvt_pk_bf16_f32 v193, v34, v35
	v_cvt_pk_bf16_f32 v194, v36, v37
	v_cvt_pk_bf16_f32 v195, v38, v39
	v_pk_fma_f32 v[188:189], v[32:33], v[32:33], v[188:189]
	global_store_dwordx4 v155, v[192:195], s[18:19] offset:256
	v_pk_fma_f32 v[188:189], v[34:35], v[34:35], v[188:189]
	v_pk_fma_f32 v[188:189], v[36:37], v[36:37], v[188:189]
	v_pk_fma_f32 v[188:189], v[38:39], v[38:39], v[188:189]
	v_add_f32_e32 v157, v188, v189
	v_add_u32_e32 v155, 0x8000, v155
	v_mov_b32_e32 v158, v157
	s_nop 1
	v_permlane16_swap_b32_e32 v157, v158
	s_nop 0
	v_add_f32_e32 v157, v157, v158
	v_mov_b32_e32 v158, v157
	s_nop 1
	v_permlane32_swap_b32_e32 v157, v158
	s_nop 0
	v_add_f32_e32 v157, v157, v158
	s_and_saveexec_b64 s[38:39], s[4:5]
	global_store_dword v156, v157, s[20:21] offset:1024
	s_mov_b64 exec, s[38:39]
	s_waitcnt vmcnt(13)
	v_pk_add_f32 v[24:25], v[24:25], v[200:201]
	v_pk_add_f32 v[26:27], v[26:27], v[202:203]
	v_pk_add_f32 v[28:29], v[28:29], v[204:205]
	v_pk_add_f32 v[30:31], v[30:31], v[206:207]
	v_cvt_pk_bf16_f32 v200, v24, v25
	v_cvt_pk_bf16_f32 v201, v26, v27
	v_cvt_pk_bf16_f32 v202, v28, v29
	v_cvt_pk_bf16_f32 v203, v30, v31
	v_pk_mul_f32 v[204:205], v[24:25], v[24:25]
	global_store_dwordx4 v155, v[200:203], s[18:19]
	v_pk_fma_f32 v[204:205], v[26:27], v[26:27], v[204:205]
	v_pk_fma_f32 v[204:205], v[28:29], v[28:29], v[204:205]
	v_pk_fma_f32 v[204:205], v[30:31], v[30:31], v[204:205]
	v_pk_add_f32 v[16:17], v[16:17], v[208:209]
	v_pk_add_f32 v[18:19], v[18:19], v[210:211]
	v_pk_add_f32 v[20:21], v[20:21], v[212:213]
	v_pk_add_f32 v[22:23], v[22:23], v[214:215]
	v_cvt_pk_bf16_f32 v208, v16, v17
	v_cvt_pk_bf16_f32 v209, v18, v19
	v_cvt_pk_bf16_f32 v210, v20, v21
	v_cvt_pk_bf16_f32 v211, v22, v23
	v_pk_fma_f32 v[204:205], v[16:17], v[16:17], v[204:205]
	global_store_dwordx4 v155, v[208:211], s[18:19] offset:256
	v_pk_fma_f32 v[204:205], v[18:19], v[18:19], v[204:205]
	v_pk_fma_f32 v[204:205], v[20:21], v[20:21], v[204:205]
	v_pk_fma_f32 v[204:205], v[22:23], v[22:23], v[204:205]
	v_add_f32_e32 v157, v204, v205
	v_add_u32_e32 v155, 0x8000, v155
	v_mov_b32_e32 v158, v157
	s_nop 1
	v_permlane16_swap_b32_e32 v157, v158
	s_nop 0
	v_add_f32_e32 v157, v157, v158
	v_mov_b32_e32 v158, v157
	s_nop 1
	v_permlane32_swap_b32_e32 v157, v158
	s_nop 0
	v_add_f32_e32 v157, v157, v158
	s_and_saveexec_b64 s[38:39], s[4:5]
	global_store_dword v156, v157, s[20:21] offset:2048
	s_mov_b64 exec, s[38:39]
	s_waitcnt vmcnt(9)
	v_pk_add_f32 v[8:9], v[8:9], v[216:217]
	v_pk_add_f32 v[10:11], v[10:11], v[218:219]
	v_pk_add_f32 v[12:13], v[12:13], v[220:221]
	v_pk_add_f32 v[14:15], v[14:15], v[222:223]
	v_cvt_pk_bf16_f32 v216, v8, v9
	v_cvt_pk_bf16_f32 v217, v10, v11
	v_cvt_pk_bf16_f32 v218, v12, v13
	v_cvt_pk_bf16_f32 v219, v14, v15
	v_pk_mul_f32 v[220:221], v[8:9], v[8:9]
	global_store_dwordx4 v155, v[216:219], s[18:19]
	v_pk_fma_f32 v[220:221], v[10:11], v[10:11], v[220:221]
	v_pk_fma_f32 v[220:221], v[12:13], v[12:13], v[220:221]
	v_pk_fma_f32 v[220:221], v[14:15], v[14:15], v[220:221]
	v_pk_add_f32 v[4:5], v[4:5], v[128:129]
	v_pk_add_f32 v[6:7], v[6:7], v[130:131]
	v_pk_add_f32 v[0:1], v[0:1], v[132:133]
	v_pk_add_f32 v[2:3], v[2:3], v[134:135]
	v_cvt_pk_bf16_f32 v128, v4, v5
	v_cvt_pk_bf16_f32 v129, v6, v7
	v_cvt_pk_bf16_f32 v130, v0, v1
	v_cvt_pk_bf16_f32 v131, v2, v3
	v_pk_fma_f32 v[220:221], v[4:5], v[4:5], v[220:221]
	global_store_dwordx4 v155, v[128:131], s[18:19] offset:256
	v_pk_fma_f32 v[220:221], v[6:7], v[6:7], v[220:221]
	v_pk_fma_f32 v[220:221], v[0:1], v[0:1], v[220:221]
	v_pk_fma_f32 v[220:221], v[2:3], v[2:3], v[220:221]
	v_add_f32_e32 v157, v220, v221
	v_add_u32_e32 v155, 0x8000, v155
	v_mov_b32_e32 v158, v157
	s_nop 1
	v_permlane16_swap_b32_e32 v157, v158
	s_nop 0
	v_add_f32_e32 v157, v157, v158
	v_mov_b32_e32 v158, v157
	s_nop 1
	v_permlane32_swap_b32_e32 v157, v158
	s_nop 0
	v_add_f32_e32 v157, v157, v158
	s_and_saveexec_b64 s[38:39], s[4:5]
	global_store_dword v156, v157, s[20:21] offset:3072
	s_mov_b64 exec, s[38:39]
	s_branch .LBB0_575
